# gather tail: last 512 tokens one per block, 2 PEER heads per wave, LDS sum, one finishing wave
# speedup vs baseline: 1.0102x; 1.0021x over previous
.LBB0_324:
	s_nop 0
	v_readlane_b32 s0, v249, 46
	v_readlane_b32 s1, v249, 47
	s_and_b64 vcc, exec, s[0:1]
	s_cbranch_vccz .LBB0_345
	v_mov_b32_e32 v1, v220
	v_readlane_b32 s0, v249, 0
	s_nop 0
	v_ashrrev_i32_e32 v0, 6, v1
	v_lshl_add_u32 v116, s0, 2, v0
	v_readfirstlane_b32 s60, v0
	v_readlane_b32 s55, v249, 9
	s_mov_b32 s54, 0
	s_movk_i32 s56, 0x4200
	s_mov_b32 s58, 0
	s_mov_b32 s59, 0
	s_movk_i32 s61, 0xe00
	s_cmp_eq_u32 s55, 0x800
	s_cselect_b32 s55, 1, 0
	s_cselect_b32 s56, 0x4000, s56
	s_sub_u32 s57, s56, 1
	s_lshl_b32 s62, s60, 13
	s_or_b32 s62, s62, 0x8000
	v_cmp_gt_i32_e32 vcc, s56, v116
	s_and_saveexec_b64 s[0:1], vcc
	s_cbranch_execz .LBB0_344
	v_readlane_b32 s2, v249, 37
	v_readlane_b32 s26, v249, 30
	v_readlane_b32 s3, v249, 38
	v_readlane_b32 s27, v249, 31
	s_mul_hi_i32 s4, s2, 0x1400000
	s_mul_i32 s5, s2, 0x1400000
	s_load_dwordx2 s[2:3], s[26:27], 0x160
	v_and_b32_e32 v6, 31, v1
	v_mul_u32_u24_e32 v2, 24, v6
	v_mov_b32_e32 v3, v80
	v_and_b32_e32 v81, 63, v1
	v_and_b32_e32 v255, 32, v81
	v_lshlrev_b32_e32 v255, 2, v255
	s_waitcnt lgkmcnt(0)
	s_add_u32 s2, s2, s5
	s_addc_u32 s3, s3, s4
	v_lshl_add_u64 v[118:119], s[2:3], 0, v[2:3]
	v_lshlrev_b32_e32 v2, 4, v6
	s_getpc_b64 s[4:5]
	s_add_u32 s4, s4, c_cand@rel32@lo+4
	s_addc_u32 s5, s5, c_cand@rel32@hi+12
	v_lshl_add_u64 v[120:121], s[2:3], 0, v[2:3]
	s_load_dwordx4 s[12:15], s[26:27], 0x90
	s_load_dwordx2 s[2:3], s[26:27], 0xc8
	global_load_ubyte v2, v81, s[4:5]
	v_readlane_b32 s16, v249, 13
	s_sub_i32 s10, s16, 19
	s_cmp_lt_u32 s10, 6
	s_cselect_b64 s[4:5], -1, 0
	s_cmp_gt_u32 s10, 5
	v_readlane_b32 s10, v249, 39
	v_readlane_b32 s11, v249, 40
	s_cselect_b64 s[20:21], -1, 0
	s_lshl_b64 s[10:11], s[10:11], 2
	s_waitcnt lgkmcnt(0)
	s_add_u32 s22, s14, s10
	s_addc_u32 s23, s15, s11
	s_add_u32 s24, s12, s10
	s_addc_u32 s25, s13, s11
	s_load_dwordx2 s[10:11], s[26:27], 0x140
	v_lshlrev_b32_e32 v3, 3, v81
	v_lshlrev_b32_e32 v4, 6, v6
	v_mov_b32_e32 v5, v80
	v_lshl_or_b32 v239, v0, 12, v3
	s_waitcnt lgkmcnt(0)
	v_lshl_add_u64 v[122:123], s[10:11], 0, v[4:5]
	v_and_b32_e32 v3, 3, v1
	v_and_b32_e32 v4, 64, v229
	v_cmp_eq_u32_e64 s[12:13], 0, v3
	v_xor_b32_e32 v3, 4, v229
	v_add_u32_e32 v4, 64, v4
	v_cmp_lt_i32_e32 vcc, v3, v4
	v_readlane_b32 s18, v249, 15
	v_readlane_b32 s19, v249, 16
	v_cndmask_b32_e32 v3, v229, v3, vcc
	v_lshlrev_b32_e32 v240, 2, v3
	v_xor_b32_e32 v3, 8, v229
	v_cmp_lt_i32_e32 vcc, v3, v4
	v_readlane_b32 s17, v249, 14
	v_cmp_lt_u32_e64 s[6:7], 31, v81
	v_cndmask_b32_e32 v3, v229, v3, vcc
	v_lshlrev_b32_e32 v241, 2, v3
	v_xor_b32_e32 v3, 16, v229
	v_cmp_lt_i32_e32 vcc, v3, v4
	v_cmp_gt_u32_e64 s[8:9], 32, v81
	v_cmp_gt_u32_e64 s[10:11], 50, v81
	v_cndmask_b32_e32 v3, v229, v3, vcc
	v_lshlrev_b32_e32 v242, 2, v3
	v_xor_b32_e32 v3, 32, v229
	v_cmp_lt_i32_e32 vcc, v3, v4
	s_waitcnt vmcnt(0)
	v_and_b32_e32 v0, 15, v2
	v_cndmask_b32_e32 v3, v229, v3, vcc
	v_lshlrev_b32_e32 v243, 2, v3
	v_and_b32_e32 v3, 16, v1
	v_cmp_eq_u32_e64 s[14:15], 0, v3
	v_and_b32_e32 v3, 8, v1
	v_and_b32_e32 v1, 4, v1
	v_cmp_eq_u32_e64 s[18:19], 0, v1
	v_xor_b32_e32 v1, 2, v229
	v_cmp_lt_i32_e32 vcc, v1, v4
	v_lshrrev_b32_e32 v2, 4, v2
	v_cmp_eq_u32_e64 s[16:17], 0, v3
	v_cndmask_b32_e32 v1, v229, v1, vcc
	v_lshlrev_b32_e32 v244, 2, v1
	v_xor_b32_e32 v1, 1, v229
	v_cmp_lt_i32_e32 vcc, v1, v4
	v_lshlrev_b32_e32 v4, 7, v6
	v_lshl_add_u64 v[124:125], s[24:25], 0, v[4:5]
	v_cndmask_b32_e32 v1, v229, v1, vcc
	v_lshlrev_b32_e32 v245, 2, v1
	v_lshl_add_u64 v[126:127], s[22:23], 0, v[4:5]
	v_lshl_add_u64 v[128:129], s[2:3], 0, v[4:5]
	s_mov_b64 s[22:23], 0
	v_lshlrev_b32_e32 v130, 2, v2
	v_lshlrev_b32_e32 v132, 2, v0
	s_branch .LBB0_328
.LBB0_327:
	s_or_b64 exec, exec, s[2:3]
	v_readlane_b32 s2, v249, 9
	s_nop 1
	v_add_u32_e32 v116, s2, v116
	v_cmp_lt_i32_e32 vcc, s57, v116
	s_or_b64 s[22:23], vcc, s[22:23]
	s_andn2_b64 exec, exec, s[22:23]
	s_cbranch_execz .Lg_tail_check
.LBB0_328:
	v_ashrrev_i32_e32 v117, 31, v116
	v_lshlrev_b64 v[0:1], 11, v[116:117]
	v_lshl_add_u64 v[134:135], v[122:123], 0, v[0:1]
	global_load_dwordx4 v[12:15], v[134:135], off
	global_load_dwordx4 v[0:3], v[134:135], off offset:16
	v_readlane_b32 s2, v249, 30
	v_readlane_b32 s3, v249, 31
	s_load_dwordx2 s[2:3], s[2:3], 0x180
	v_lshlrev_b64 v[136:137], 10, v[116:117]
	v_mov_b32_e32 v131, v80
	v_mov_b32_e32 v133, v80
	s_movk_i32 s43, 0x80
	s_waitcnt lgkmcnt(0)
	v_lshl_add_u64 v[4:5], s[2:3], 0, v[136:137]
	v_lshl_add_u64 v[4:5], s[58:59], 0, v[4:5]
	v_lshl_add_u64 v[18:19], v[4:5], 0, v[130:131]
	v_lshl_add_u64 v[16:17], v[4:5], 0, v[132:133]
	global_load_dword v26, v[16:17], off offset:64
	global_load_dword v28, v[18:19], off
	global_load_dword v25, v[16:17], off offset:192
	global_load_dword v27, v[18:19], off offset:128
	global_load_dwordx4 v[4:7], v[134:135], off offset:48
	global_load_dwordx4 v[8:11], v[134:135], off offset:32
	global_load_dword v21, v[18:19], off offset:256
	global_load_dword v23, v[18:19], off offset:384
	global_load_dword v22, v[18:19], off offset:512
	global_load_dword v24, v[18:19], off offset:640
	global_load_dword v20, v[18:19], off offset:768
	s_nop 0
	global_load_dword v18, v[18:19], off offset:896
	s_nop 0
	global_load_dword v117, v[16:17], off offset:320
	global_load_dword v31, v[16:17], off offset:448
	global_load_dword v30, v[16:17], off offset:576
	global_load_dword v29, v[16:17], off offset:704
	global_load_dword v19, v[16:17], off offset:832
	s_nop 0
	global_load_dword v16, v[16:17], off offset:960
	s_movk_i32 s44, 0x3f80
	v_mov_b32_e32 v176, 0
	v_mov_b32_e32 v177, v176
	v_mov_b32_e32 v216, v176
	v_mov_b32_e32 v217, v176
	v_mov_b32_e32 v214, v176
	v_mov_b32_e32 v215, v176
	v_mov_b32_e32 v212, v176
	v_mov_b32_e32 v213, v176
	v_mov_b32_e32 v210, v176
	v_mov_b32_e32 v211, v176
	v_mov_b32_e32 v208, v176
	v_mov_b32_e32 v209, v176
	v_mov_b32_e32 v206, v176
	v_mov_b32_e32 v207, v176
	v_mov_b32_e32 v204, v176
	v_mov_b32_e32 v205, v176
	v_mov_b32_e32 v202, v176
	v_mov_b32_e32 v203, v176
	v_mov_b32_e32 v200, v176
	v_mov_b32_e32 v201, v176
	v_mov_b32_e32 v198, v176
	v_mov_b32_e32 v199, v176
	v_mov_b32_e32 v196, v176
	v_mov_b32_e32 v197, v176
	v_mov_b32_e32 v194, v176
	v_mov_b32_e32 v195, v176
	v_mov_b32_e32 v192, v176
	v_mov_b32_e32 v193, v176
	v_mov_b32_e32 v190, v176
	v_mov_b32_e32 v191, v176
	v_mov_b32_e32 v188, v176
	v_mov_b32_e32 v189, v176
	s_waitcnt vmcnt(17)
	v_cmp_lt_i32_e32 vcc, -1, v26
	s_waitcnt vmcnt(13)
	v_lshlrev_b32_e32 v160, 16, v4
	v_lshlrev_b32_e32 v152, 16, v12
	v_lshlrev_b32_e32 v174, 16, v1
	v_and_b32_e32 v143, 0xffff0000, v1
	v_cndmask_b32_e64 v1, v232, -1, vcc
	v_cmp_lt_i32_e32 vcc, -1, v28
	v_and_b32_e32 v150, 0xffff0000, v12
	v_lshlrev_b32_e32 v148, 16, v14
	v_cndmask_b32_e64 v12, v232, -1, vcc
	v_cmp_lt_i32_e32 vcc, -1, v25
	v_and_b32_e32 v146, 0xffff0000, v14
	v_lshlrev_b32_e32 v172, 16, v15
	v_cndmask_b32_e64 v17, v232, -1, vcc
	v_cmp_lt_i32_e32 vcc, -1, v27
	v_and_b32_e32 v147, 0xffff0000, v15
	v_lshlrev_b32_e32 v144, 16, v0
	v_and_b32_e32 v142, 0xffff0000, v0
	v_lshlrev_b32_e32 v140, 16, v2
	v_and_b32_e32 v138, 0xffff0000, v2
	v_and_b32_e32 v0, 0xffffff80, v26
	v_and_b32_e32 v2, 0xffffff80, v28
	v_and_b32_e32 v14, 0xffffff80, v25
	v_and_b32_e32 v15, 0xffffff80, v27
	v_cndmask_b32_e64 v32, v232, -1, vcc
	v_lshlrev_b32_e32 v170, 16, v13
	v_and_b32_e32 v151, 0xffff0000, v13
	v_xor_b32_e32 v1, v1, v0
	v_xor_b32_e32 v13, v12, v2
	v_xor_b32_e32 v0, v17, v14
	v_xor_b32_e32 v12, v32, v15
	v_pk_add_f32 v[0:1], v[12:13], v[0:1]
	v_lshlrev_b32_e32 v178, 16, v3
	v_or_b32_e32 v2, 0x80000000, v1
	v_not_b32_e32 v12, v1
	v_cmp_gt_i32_e32 vcc, 0, v1
	v_and_b32_e32 v139, 0xffff0000, v3
	s_waitcnt vmcnt(12)
	v_lshlrev_b32_e32 v168, 16, v8
	v_cndmask_b32_e32 v2, v2, v12, vcc
	v_and_b32_e32 v2, 0xffffffc0, v2
	v_bitop3_b32 v2, v2, 63, v81 bitop3:0x36
	v_cndmask_b32_e64 v2, 0, v2, s[10:11]
	v_and_b32_e32 v166, 0xffff0000, v8
	v_readlane_b32 s3, v2, 1
	v_readlane_b32 s24, v2, 2
	v_readlane_b32 s26, v2, 4
	v_cmp_gt_u32_e32 vcc, s3, v2
	v_readlane_b32 s30, v2, 6
	v_readlane_b32 s34, v2, 8
	v_cndmask_b32_e64 v12, 0, 1, vcc
	v_cmp_gt_u32_e32 vcc, s24, v2
	v_readlane_b32 s2, v2, 0
	v_readlane_b32 s25, v2, 3
	v_cndmask_b32_e64 v13, 0, 1, vcc
	v_cmp_gt_u32_e32 vcc, s26, v2
	v_readlane_b32 s27, v2, 5
	v_readlane_b32 s31, v2, 7
	v_cndmask_b32_e64 v14, 0, 1, vcc
	v_cmp_gt_u32_e32 vcc, s30, v2
	v_and_b32_e32 v158, 0xffff0000, v4
	v_lshlrev_b32_e32 v184, 16, v5
	v_cndmask_b32_e64 v15, 0, 1, vcc
	v_cmp_gt_u32_e32 vcc, s34, v2
	v_and_b32_e32 v159, 0xffff0000, v5
	v_lshlrev_b32_e32 v156, 16, v6
	v_cndmask_b32_e64 v17, 0, 1, vcc
	v_cmp_gt_u32_e32 vcc, s2, v2
	v_readlane_b32 s2, v2, 9
	v_and_b32_e32 v154, 0xffff0000, v6
	v_addc_co_u32_e32 v12, vcc, 0, v12, vcc
	v_cmp_gt_u32_e32 vcc, s25, v2
	v_lshlrev_b32_e32 v5, 7, v28
	v_and_b32_e32 v6, 0x7f, v26
	v_addc_co_u32_e32 v12, vcc, v12, v13, vcc
	v_cmp_gt_u32_e32 vcc, s27, v2
	v_and_or_b32 v5, v5, s44, v6
	v_lshlrev_b32_e32 v186, 16, v7
	v_addc_co_u32_e32 v12, vcc, v12, v14, vcc
	v_cmp_gt_u32_e32 vcc, s31, v2
	v_and_b32_e32 v155, 0xffff0000, v7
	v_lshlrev_b32_e32 v164, 16, v10
	v_addc_co_u32_e32 v12, vcc, v12, v15, vcc
	v_cmp_gt_u32_e32 vcc, s2, v2
	v_readlane_b32 s2, v2, 10
	v_and_b32_e32 v162, 0xffff0000, v10
	v_addc_co_u32_e32 v12, vcc, v12, v17, vcc
	v_cmp_gt_u32_e32 vcc, s2, v2
	v_readlane_b32 s2, v2, 11
	v_lshlrev_b32_e32 v182, 16, v11
	v_cndmask_b32_e64 v13, 0, 1, vcc
	v_cmp_gt_u32_e32 vcc, s2, v2
	v_readlane_b32 s2, v2, 12
	v_and_b32_e32 v163, 0xffff0000, v11
	v_addc_co_u32_e32 v12, vcc, v12, v13, vcc
	v_cmp_gt_u32_e32 vcc, s2, v2
	v_readlane_b32 s2, v2, 13
	v_not_b32_e32 v17, v0
	v_cndmask_b32_e64 v13, 0, 1, vcc
	v_cmp_gt_u32_e32 vcc, s2, v2
	v_readlane_b32 s2, v2, 14
	v_lshlrev_b32_e32 v180, 16, v9
	v_addc_co_u32_e32 v12, vcc, v12, v13, vcc
	v_cmp_gt_u32_e32 vcc, s2, v2
	v_readlane_b32 s2, v2, 15
	v_and_b32_e32 v167, 0xffff0000, v9
	v_cndmask_b32_e64 v13, 0, 1, vcc
	v_cmp_gt_u32_e32 vcc, s2, v2
	v_readlane_b32 s2, v2, 16
	v_and_b32_e32 v9, 0x7f, v25
	v_addc_co_u32_e32 v12, vcc, v12, v13, vcc
	v_cmp_gt_u32_e32 vcc, s2, v2
	v_readlane_b32 s2, v2, 17
	s_mov_b32 s24, 0
	v_cndmask_b32_e64 v13, 0, 1, vcc
	v_cmp_gt_u32_e32 vcc, s2, v2
	v_readlane_b32 s2, v2, 18
	v_mov_b32_e32 v153, v150
	v_addc_co_u32_e32 v12, vcc, v12, v13, vcc
	v_cmp_gt_u32_e32 vcc, s2, v2
	v_readlane_b32 s2, v2, 19
	v_mov_b32_e32 v171, v151
	v_cndmask_b32_e64 v13, 0, 1, vcc
	v_cmp_gt_u32_e32 vcc, s2, v2
	v_readlane_b32 s2, v2, 20
	v_mov_b32_e32 v149, v146
	v_addc_co_u32_e32 v12, vcc, v12, v13, vcc
	v_cmp_gt_u32_e32 vcc, s2, v2
	v_readlane_b32 s2, v2, 21
	v_mov_b32_e32 v173, v147
	v_cndmask_b32_e64 v13, 0, 1, vcc
	v_cmp_gt_u32_e32 vcc, s2, v2
	v_readlane_b32 s2, v2, 22
	v_mov_b32_e32 v145, v142
	v_addc_co_u32_e32 v12, vcc, v12, v13, vcc
	v_cmp_gt_u32_e32 vcc, s2, v2
	v_readlane_b32 s2, v2, 23
	v_mov_b32_e32 v175, v143
	v_cndmask_b32_e64 v13, 0, 1, vcc
	v_cmp_gt_u32_e32 vcc, s2, v2
	v_readlane_b32 s2, v2, 24
	v_mov_b32_e32 v141, v138
	v_addc_co_u32_e32 v12, vcc, v12, v13, vcc
	v_cmp_gt_u32_e32 vcc, s2, v2
	v_readlane_b32 s2, v2, 25
	v_mov_b32_e32 v179, v139
	v_cndmask_b32_e64 v13, 0, 1, vcc
	v_cmp_gt_u32_e32 vcc, s2, v2
	v_readlane_b32 s2, v2, 26
	v_mov_b32_e32 v169, v166
	v_addc_co_u32_e32 v12, vcc, v12, v13, vcc
	v_cmp_gt_u32_e32 vcc, s2, v2
	v_readlane_b32 s2, v2, 27
	v_mov_b32_e32 v181, v167
	v_cndmask_b32_e64 v13, 0, 1, vcc
	v_cmp_gt_u32_e32 vcc, s2, v2
	v_readlane_b32 s2, v2, 28
	v_mov_b32_e32 v165, v162
	v_addc_co_u32_e32 v12, vcc, v12, v13, vcc
	v_cmp_gt_u32_e32 vcc, s2, v2
	v_readlane_b32 s2, v2, 29
	v_mov_b32_e32 v183, v163
	v_cndmask_b32_e64 v13, 0, 1, vcc
	v_cmp_gt_u32_e32 vcc, s2, v2
	v_readlane_b32 s2, v2, 30
	v_mov_b32_e32 v161, v158
	v_addc_co_u32_e32 v12, vcc, v12, v13, vcc
	v_cmp_gt_u32_e32 vcc, s2, v2
	v_readlane_b32 s2, v2, 31
	v_mov_b32_e32 v185, v159
	v_cndmask_b32_e64 v13, 0, 1, vcc
	v_cmp_gt_u32_e32 vcc, s2, v2
	v_readlane_b32 s2, v2, 32
	v_mov_b32_e32 v157, v154
	v_addc_co_u32_e32 v12, vcc, v12, v13, vcc
	v_cmp_gt_u32_e32 vcc, s2, v2
	v_readlane_b32 s2, v2, 33
	v_mov_b32_e32 v187, v155
	v_cndmask_b32_e64 v13, 0, 1, vcc
	v_cmp_gt_u32_e32 vcc, s2, v2
	v_readlane_b32 s2, v2, 34
	s_nop 0
	v_addc_co_u32_e32 v12, vcc, v12, v13, vcc
	v_cmp_gt_u32_e32 vcc, s2, v2
	v_readlane_b32 s2, v2, 35
	s_nop 0
	v_cndmask_b32_e64 v13, 0, 1, vcc
	v_cmp_gt_u32_e32 vcc, s2, v2
	v_readlane_b32 s2, v2, 36
	s_nop 0
	v_addc_co_u32_e32 v12, vcc, v12, v13, vcc
	v_cmp_gt_u32_e32 vcc, s2, v2
	v_readlane_b32 s2, v2, 37
	s_nop 0
	v_cndmask_b32_e64 v13, 0, 1, vcc
	v_cmp_gt_u32_e32 vcc, s2, v2
	v_readlane_b32 s2, v2, 38
	s_nop 0
	v_addc_co_u32_e32 v12, vcc, v12, v13, vcc
	v_cmp_gt_u32_e32 vcc, s2, v2
	v_readlane_b32 s2, v2, 39
	s_nop 0
	v_cndmask_b32_e64 v13, 0, 1, vcc
	v_cmp_gt_u32_e32 vcc, s2, v2
	v_readlane_b32 s2, v2, 40
	s_nop 0
	v_addc_co_u32_e32 v12, vcc, v12, v13, vcc
	v_cmp_gt_u32_e32 vcc, s2, v2
	v_readlane_b32 s2, v2, 41
	s_nop 0
	v_cndmask_b32_e64 v13, 0, 1, vcc
	v_cmp_gt_u32_e32 vcc, s2, v2
	v_readlane_b32 s2, v2, 42
	s_nop 0
	v_addc_co_u32_e32 v12, vcc, v12, v13, vcc
	v_cmp_gt_u32_e32 vcc, s2, v2
	v_readlane_b32 s2, v2, 43
	s_nop 0
	v_cndmask_b32_e64 v13, 0, 1, vcc
	v_cmp_gt_u32_e32 vcc, s2, v2
	v_readlane_b32 s2, v2, 44
	s_nop 0
	v_addc_co_u32_e32 v12, vcc, v12, v13, vcc
	v_cmp_gt_u32_e32 vcc, s2, v2
	v_readlane_b32 s2, v2, 45
	s_nop 0
	v_cndmask_b32_e64 v13, 0, 1, vcc
	v_cmp_gt_u32_e32 vcc, s2, v2
	v_readlane_b32 s2, v2, 46
	s_nop 0
	v_addc_co_u32_e32 v12, vcc, v12, v13, vcc
	v_cmp_gt_u32_e32 vcc, s2, v2
	v_readlane_b32 s2, v2, 47
	s_nop 0
	v_cndmask_b32_e64 v13, 0, 1, vcc
	v_cmp_gt_u32_e32 vcc, s2, v2
	v_readlane_b32 s2, v2, 48
	s_nop 0
	v_addc_co_u32_e32 v12, vcc, v12, v13, vcc
	v_cmp_gt_u32_e32 vcc, s2, v2
	v_readlane_b32 s2, v2, 49
	s_nop 0
	v_cndmask_b32_e64 v13, 0, 1, vcc
	v_cmp_gt_u32_e32 vcc, s2, v2
	s_nop 1
	v_addc_co_u32_e32 v2, vcc, v12, v13, vcc
	v_lshlrev_b32_e32 v13, 3, v2
	v_lshlrev_b32_e32 v12, 7, v2
	v_and_b32_e32 v13, 0x70, v13
	v_and_or_b32 v12, v12, s43, v13
	v_cmp_gt_u32_e32 vcc, 16, v2
	s_nop 1
	v_cndmask_b32_e32 v2, 4, v12, vcc
	ds_permute_b32 v1, v2, v1
	ds_permute_b32 v2, v2, v5
	s_waitcnt lgkmcnt(1)
	v_readlane_b32 s2, v1, 0
	s_nop 1
	v_subrev_f32_e32 v1, s2, v1
	v_mul_f32_e32 v1, 0x3fb8aa3b, v1
	v_exp_f32_e32 v1, v1
	s_waitcnt lgkmcnt(0)
	v_readlane_b32 s25, v2, 4
	v_readlane_b32 s26, v2, 36
	v_readlane_b32 s27, v2, 8
	v_cndmask_b32_e64 v1, 0, v1, s[12:13]
	ds_bpermute_b32 v3, v240, v1
	v_readlane_b32 s30, v2, 40
	v_readlane_b32 s31, v2, 12
	v_readlane_b32 s34, v2, 44
	v_readlane_b32 s35, v2, 16
	s_waitcnt lgkmcnt(0)
	v_add_f32_e32 v3, v1, v3
	ds_bpermute_b32 v8, v241, v3
	v_readlane_b32 s36, v2, 48
	v_readlane_b32 s37, v2, 20
	v_readlane_b32 s38, v2, 52
	v_readlane_b32 s39, v2, 24
	s_waitcnt lgkmcnt(0)
	v_add_f32_e32 v3, v3, v8
	ds_bpermute_b32 v4, v242, v3
	v_readlane_b32 s40, v2, 56
	v_readlane_b32 s41, v2, 28
	v_readlane_b32 s42, v2, 60
	v_lshlrev_b32_e32 v8, 7, v27
	s_waitcnt lgkmcnt(0)
	v_add_f32_e32 v3, v3, v4
	ds_bpermute_b32 v4, v243, v3
	v_and_or_b32 v8, v8, s44, v9
	s_waitcnt lgkmcnt(0)
	v_add_f32_e32 v3, v3, v4
	v_div_scale_f32 v4, s[2:3], v3, v3, v1
	v_rcp_f32_e32 v6, v4
	v_readlane_b32 s2, v2, 0
	v_readlane_b32 s3, v2, 32
	v_fma_f32 v5, -v4, v6, 1.0
	v_fmac_f32_e32 v6, v5, v6
	v_div_scale_f32 v5, vcc, v1, v3, v1
	v_mul_f32_e32 v7, v5, v6
	v_fma_f32 v10, -v4, v7, v5
	v_fmac_f32_e32 v7, v10, v6
	v_fma_f32 v4, -v4, v7, v5
	v_div_fmas_f32 v4, v4, v6, v7
	v_div_fixup_f32 v3, v4, v3, v1
	v_mov_b32_e32 v1, s2
	v_mov_b32_e32 v4, s3
	v_cndmask_b32_e64 v1, v1, v4, s[6:7]
	v_mad_i64_i32 v[4:5], s[2:3], v1, s28, v[118:119]
	global_load_dwordx2 v[36:37], v[4:5], off offset:16
	global_load_dwordx4 v[32:35], v[4:5], off
	v_mov_b32_e32 v4, s25
	v_mov_b32_e32 v5, s26
	v_cndmask_b32_e64 v6, v4, v5, s[6:7]
	v_mad_i64_i32 v[4:5], s[2:3], v6, s28, v[118:119]
	global_load_dwordx2 v[42:43], v[4:5], off offset:16
	global_load_dwordx4 v[38:41], v[4:5], off
	v_mov_b32_e32 v4, s27
	v_mov_b32_e32 v5, s30
	v_cndmask_b32_e64 v10, v4, v5, s[6:7]
	v_mad_i64_i32 v[4:5], s[2:3], v10, s28, v[118:119]
	global_load_dwordx2 v[48:49], v[4:5], off offset:16
	global_load_dwordx4 v[44:47], v[4:5], off
	v_mov_b32_e32 v4, s31
	v_mov_b32_e32 v5, s34
	v_cndmask_b32_e64 v11, v4, v5, s[6:7]
	v_mad_i64_i32 v[4:5], s[2:3], v11, s28, v[118:119]
	global_load_dwordx2 v[54:55], v[4:5], off offset:16
	global_load_dwordx4 v[50:53], v[4:5], off
	v_mov_b32_e32 v4, s35
	v_mov_b32_e32 v5, s36
	v_cndmask_b32_e64 v12, v4, v5, s[6:7]
	v_mad_i64_i32 v[4:5], s[2:3], v12, s28, v[118:119]
	global_load_dwordx2 v[60:61], v[4:5], off offset:16
	global_load_dwordx4 v[56:59], v[4:5], off
	v_mov_b32_e32 v4, s37
	v_mov_b32_e32 v5, s38
	v_cndmask_b32_e64 v13, v4, v5, s[6:7]
	v_mad_i64_i32 v[4:5], s[2:3], v13, s28, v[118:119]
	global_load_dwordx2 v[66:67], v[4:5], off offset:16
	global_load_dwordx4 v[62:65], v[4:5], off
	v_mov_b32_e32 v4, s39
	v_mov_b32_e32 v5, s40
	v_cndmask_b32_e64 v14, v4, v5, s[6:7]
	v_mad_i64_i32 v[4:5], s[2:3], v14, s28, v[118:119]
	global_load_dwordx2 v[72:73], v[4:5], off offset:16
	global_load_dwordx4 v[68:71], v[4:5], off
	v_mov_b32_e32 v4, s41
	v_mov_b32_e32 v5, s42
	v_cndmask_b32_e64 v15, v4, v5, s[6:7]
	v_mad_i64_i32 v[4:5], s[2:3], v15, s28, v[118:119]
	global_load_dwordx2 v[78:79], v[4:5], off offset:16
	global_load_dwordx4 v[74:77], v[4:5], off
	v_mad_i64_i32 v[4:5], s[2:3], v1, s28, v[120:121]
	v_or_b32_e32 v1, 0x80000000, v0
	v_cmp_gt_i32_e32 vcc, 0, v0
	v_mad_i64_i32 v[6:7], s[2:3], v6, s28, v[120:121]
	s_nop 0
	v_cndmask_b32_e32 v1, v1, v17, vcc
	v_and_b32_e32 v1, 0xffffffc0, v1
	v_cndmask_b32_e64 v1, 0, v1, s[10:11]
	v_bitop3_b32 v1, v1, 63, v81 bitop3:0x36
	global_load_dwordx4 v[110:113], v[4:5], off offset:768
	global_load_dwordx4 v[106:109], v[6:7], off offset:768
	s_mov_b32 vcc_lo, 0x55555555
	s_mov_b32 vcc_hi, 0x55555555
	s_mov_b32 s48, 0x33333333
	s_mov_b32 s49, 0x33333333
	v_max_u32_dpp v250, v1, v1 quad_perm:[1,0,3,2] row_mask:0xf bank_mask:0xf
	v_min_u32_dpp v251, v1, v1 quad_perm:[1,0,3,2] row_mask:0xf bank_mask:0xf
	v_cndmask_b32_e32 v17, v251, v250, vcc
	s_nop 1
	v_max_u32_dpp v250, v17, v17 quad_perm:[3,2,1,0] row_mask:0xf bank_mask:0xf
	v_min_u32_dpp v251, v17, v17 quad_perm:[3,2,1,0] row_mask:0xf bank_mask:0xf
	v_cndmask_b32_e64 v1, v251, v250, s[48:49]
	s_nop 1
	v_max_u32_dpp v250, v1, v1 quad_perm:[1,0,3,2] row_mask:0xf bank_mask:0xf
	v_min_u32_dpp v251, v1, v1 quad_perm:[1,0,3,2] row_mask:0xf bank_mask:0xf
	v_cndmask_b32_e32 v17, v251, v250, vcc
	s_nop 1
	v_max_u32_dpp v1, v17, v17 row_half_mirror row_mask:0xf bank_mask:0x5
	v_min_u32_dpp v1, v17, v17 row_half_mirror row_mask:0xf bank_mask:0xa
	s_nop 1
	v_max_u32_dpp v250, v1, v1 quad_perm:[2,3,0,1] row_mask:0xf bank_mask:0xf
	v_min_u32_dpp v251, v1, v1 quad_perm:[2,3,0,1] row_mask:0xf bank_mask:0xf
	v_cndmask_b32_e64 v17, v251, v250, s[48:49]
	s_nop 1
	v_max_u32_dpp v250, v17, v17 quad_perm:[1,0,3,2] row_mask:0xf bank_mask:0xf
	v_min_u32_dpp v251, v17, v17 quad_perm:[1,0,3,2] row_mask:0xf bank_mask:0xf
	v_cndmask_b32_e32 v1, v251, v250, vcc
	s_nop 1
	v_max_u32_dpp v17, v1, v1 row_mirror row_mask:0xf bank_mask:0x3
	v_min_u32_dpp v17, v1, v1 row_mirror row_mask:0xf bank_mask:0xc
	s_nop 1
	v_max_u32_dpp v1, v17, v17 row_ror:12 row_mask:0xf bank_mask:0x5
	v_min_u32_dpp v1, v17, v17 row_ror:4 row_mask:0xf bank_mask:0xa
	s_nop 1
	v_max_u32_dpp v250, v1, v1 quad_perm:[2,3,0,1] row_mask:0xf bank_mask:0xf
	v_min_u32_dpp v251, v1, v1 quad_perm:[2,3,0,1] row_mask:0xf bank_mask:0xf
	v_cndmask_b32_e64 v17, v251, v250, s[48:49]
	s_nop 1
	v_max_u32_dpp v250, v17, v17 quad_perm:[1,0,3,2] row_mask:0xf bank_mask:0xf
	v_min_u32_dpp v251, v17, v17 quad_perm:[1,0,3,2] row_mask:0xf bank_mask:0xf
	v_cndmask_b32_e32 v1, v251, v250, vcc
	ds_swizzle_b32 v252, v1 offset:0x7c1f
	s_waitcnt lgkmcnt(0)
	v_max_u32_dpp v17, v252, v1 quad_perm:[0,1,2,3] row_mask:0x5 bank_mask:0xf
	v_min_u32_dpp v17, v252, v1 quad_perm:[0,1,2,3] row_mask:0xa bank_mask:0xf
	s_nop 1
	v_max_u32_dpp v1, v17, v17 row_ror:8 row_mask:0xf bank_mask:0x3
	v_min_u32_dpp v1, v17, v17 row_ror:8 row_mask:0xf bank_mask:0xc
	s_nop 1
	v_max_u32_dpp v17, v1, v1 row_ror:12 row_mask:0xf bank_mask:0x5
	v_min_u32_dpp v17, v1, v1 row_ror:4 row_mask:0xf bank_mask:0xa
	s_nop 1
	v_max_u32_dpp v250, v17, v17 quad_perm:[2,3,0,1] row_mask:0xf bank_mask:0xf
	v_min_u32_dpp v251, v17, v17 quad_perm:[2,3,0,1] row_mask:0xf bank_mask:0xf
	v_cndmask_b32_e64 v1, v251, v250, s[48:49]
	s_nop 1
	v_max_u32_dpp v250, v1, v1 quad_perm:[1,0,3,2] row_mask:0xf bank_mask:0xf
	v_min_u32_dpp v251, v1, v1 quad_perm:[1,0,3,2] row_mask:0xf bank_mask:0xf
	v_cndmask_b32_e32 v17, v251, v250, vcc
	v_xor_b32_e32 v253, 63, v81
	v_lshlrev_b32_e32 v253, 2, v253
	ds_bpermute_b32 v252, v253, v17
	s_waitcnt lgkmcnt(0)
	v_max_u32_dpp v1, v252, v17 quad_perm:[0,1,2,3] row_mask:0x3 bank_mask:0xf
	v_min_u32_dpp v1, v252, v17 quad_perm:[0,1,2,3] row_mask:0xc bank_mask:0xf
	ds_swizzle_b32 v252, v1 offset:0x401f
	s_waitcnt lgkmcnt(0)
	v_max_u32_dpp v17, v252, v1 quad_perm:[0,1,2,3] row_mask:0x5 bank_mask:0xf
	v_min_u32_dpp v17, v252, v1 quad_perm:[0,1,2,3] row_mask:0xa bank_mask:0xf
	s_nop 1
	v_max_u32_dpp v1, v17, v17 row_ror:8 row_mask:0xf bank_mask:0x3
	v_min_u32_dpp v1, v17, v17 row_ror:8 row_mask:0xf bank_mask:0xc
	s_nop 1
	v_max_u32_dpp v17, v1, v1 row_ror:12 row_mask:0xf bank_mask:0x5
	v_min_u32_dpp v17, v1, v1 row_ror:4 row_mask:0xf bank_mask:0xa
	s_nop 1
	v_max_u32_dpp v250, v17, v17 quad_perm:[2,3,0,1] row_mask:0xf bank_mask:0xf
	v_min_u32_dpp v251, v17, v17 quad_perm:[2,3,0,1] row_mask:0xf bank_mask:0xf
	v_cndmask_b32_e64 v1, v251, v250, s[48:49]
	s_nop 1
	v_max_u32_dpp v250, v1, v1 quad_perm:[1,0,3,2] row_mask:0xf bank_mask:0xf
	v_min_u32_dpp v251, v1, v1 quad_perm:[1,0,3,2] row_mask:0xf bank_mask:0xf
	v_cndmask_b32_e32 v17, v251, v250, vcc
	v_not_b32_e32 v253, v17
	v_and_b32_e32 v253, 63, v253
	v_lshlrev_b32_e32 v253, 2, v253
	ds_permute_b32 v1, v253, v81
	s_waitcnt lgkmcnt(0)
	v_lshlrev_b32_e32 v25, 3, v1
	v_lshlrev_b32_e32 v17, 7, v1
	v_and_b32_e32 v25, 0x70, v25
	v_and_or_b32 v17, v17, s43, v25
	v_cmp_gt_u32_e32 vcc, 16, v1
	s_nop 1
	v_cndmask_b32_e32 v17, 4, v17, vcc
	ds_permute_b32 v25, v17, v0
	v_mad_i64_i32 v[0:1], s[2:3], v10, s28, v[120:121]
	s_waitcnt vmcnt(23)
	v_cmp_lt_i32_e32 vcc, -1, v117
	s_waitcnt lgkmcnt(0)
	v_readlane_b32 s2, v25, 0
	s_nop 1
	v_subrev_f32_e32 v4, s2, v25
	v_mul_f32_e32 v4, 0x3fb8aa3b, v4
	v_exp_f32_e32 v6, v4
	v_mad_i64_i32 v[4:5], s[2:3], v11, s28, v[120:121]
	global_load_dwordx4 v[102:105], v[0:1], off offset:768
	global_load_dwordx4 v[98:101], v[4:5], off offset:768
	v_cndmask_b32_e64 v6, 0, v6, s[12:13]
	ds_bpermute_b32 v7, v240, v6
	v_mad_i64_i32 v[0:1], s[2:3], v12, s28, v[120:121]
	v_mad_i64_i32 v[4:5], s[2:3], v13, s28, v[120:121]
	s_waitcnt lgkmcnt(0)
	v_add_f32_e32 v7, v6, v7
	ds_bpermute_b32 v10, v241, v7
	global_load_dwordx4 v[94:97], v[0:1], off offset:768
	global_load_dwordx4 v[90:93], v[4:5], off offset:768
	v_mad_i64_i32 v[0:1], s[2:3], v14, s28, v[120:121]
	v_mad_i64_i32 v[4:5], s[2:3], v15, s28, v[120:121]
	s_waitcnt lgkmcnt(0)
	v_add_f32_e32 v7, v7, v10
	ds_bpermute_b32 v10, v242, v7
	global_load_dwordx4 v[86:89], v[0:1], off offset:768
	global_load_dwordx4 v[82:85], v[4:5], off offset:768
	v_cndmask_b32_e64 v1, v232, -1, vcc
	v_cmp_lt_i32_e32 vcc, -1, v21
	v_and_b32_e32 v0, 0xffffff80, v117
	s_waitcnt lgkmcnt(0)
	v_add_f32_e32 v7, v7, v10
	v_cndmask_b32_e64 v5, v232, -1, vcc
	s_waitcnt vmcnt(28)
	v_cmp_lt_i32_e32 vcc, -1, v31
	v_and_b32_e32 v4, 0xffffff80, v21
	v_xor_b32_e32 v1, v1, v0
	v_cndmask_b32_e64 v10, v232, -1, vcc
	v_cmp_lt_i32_e32 vcc, -1, v23
	v_xor_b32_e32 v5, v5, v4
	v_and_b32_e32 v0, 0xffffff80, v31
	v_and_b32_e32 v4, 0xffffff80, v23
	v_cndmask_b32_e64 v11, v232, -1, vcc
	v_xor_b32_e32 v0, v10, v0
	v_xor_b32_e32 v4, v11, v4
	v_pk_add_f32 v[0:1], v[4:5], v[0:1]
	ds_bpermute_b32 v9, v243, v7
	v_or_b32_e32 v4, 0x80000000, v1
	v_not_b32_e32 v5, v1
	v_cmp_gt_i32_e32 vcc, 0, v1
	s_nop 1
	v_cndmask_b32_e32 v4, v4, v5, vcc
	v_and_b32_e32 v4, 0xffffffc0, v4
	v_cndmask_b32_e64 v4, 0, v4, s[10:11]
	v_bitop3_b32 v4, v4, 63, v81 bitop3:0x36
	s_nop 0
	s_mov_b32 vcc_lo, 0x55555555
	s_mov_b32 vcc_hi, 0x55555555
	s_mov_b32 s48, 0x33333333
	s_mov_b32 s49, 0x33333333
	v_max_u32_dpp v250, v4, v4 quad_perm:[1,0,3,2] row_mask:0xf bank_mask:0xf
	v_min_u32_dpp v251, v4, v4 quad_perm:[1,0,3,2] row_mask:0xf bank_mask:0xf
	v_cndmask_b32_e32 v5, v251, v250, vcc
	s_nop 1
	v_max_u32_dpp v250, v5, v5 quad_perm:[3,2,1,0] row_mask:0xf bank_mask:0xf
	v_min_u32_dpp v251, v5, v5 quad_perm:[3,2,1,0] row_mask:0xf bank_mask:0xf
	v_cndmask_b32_e64 v4, v251, v250, s[48:49]
	s_nop 1
	v_max_u32_dpp v250, v4, v4 quad_perm:[1,0,3,2] row_mask:0xf bank_mask:0xf
	v_min_u32_dpp v251, v4, v4 quad_perm:[1,0,3,2] row_mask:0xf bank_mask:0xf
	v_cndmask_b32_e32 v5, v251, v250, vcc
	s_nop 1
	v_max_u32_dpp v4, v5, v5 row_half_mirror row_mask:0xf bank_mask:0x5
	v_min_u32_dpp v4, v5, v5 row_half_mirror row_mask:0xf bank_mask:0xa
	s_nop 1
	v_max_u32_dpp v250, v4, v4 quad_perm:[2,3,0,1] row_mask:0xf bank_mask:0xf
	v_min_u32_dpp v251, v4, v4 quad_perm:[2,3,0,1] row_mask:0xf bank_mask:0xf
	v_cndmask_b32_e64 v5, v251, v250, s[48:49]
	s_nop 1
	v_max_u32_dpp v250, v5, v5 quad_perm:[1,0,3,2] row_mask:0xf bank_mask:0xf
	v_min_u32_dpp v251, v5, v5 quad_perm:[1,0,3,2] row_mask:0xf bank_mask:0xf
	v_cndmask_b32_e32 v4, v251, v250, vcc
	s_nop 1
	v_max_u32_dpp v5, v4, v4 row_mirror row_mask:0xf bank_mask:0x3
	v_min_u32_dpp v5, v4, v4 row_mirror row_mask:0xf bank_mask:0xc
	s_nop 1
	v_max_u32_dpp v4, v5, v5 row_ror:12 row_mask:0xf bank_mask:0x5
	v_min_u32_dpp v4, v5, v5 row_ror:4 row_mask:0xf bank_mask:0xa
	s_nop 1
	v_max_u32_dpp v250, v4, v4 quad_perm:[2,3,0,1] row_mask:0xf bank_mask:0xf
	v_min_u32_dpp v251, v4, v4 quad_perm:[2,3,0,1] row_mask:0xf bank_mask:0xf
	v_cndmask_b32_e64 v5, v251, v250, s[48:49]
	s_nop 1
	v_max_u32_dpp v250, v5, v5 quad_perm:[1,0,3,2] row_mask:0xf bank_mask:0xf
	v_min_u32_dpp v251, v5, v5 quad_perm:[1,0,3,2] row_mask:0xf bank_mask:0xf
	v_cndmask_b32_e32 v4, v251, v250, vcc
	ds_swizzle_b32 v252, v4 offset:0x7c1f
	s_waitcnt lgkmcnt(0)
	v_max_u32_dpp v5, v252, v4 quad_perm:[0,1,2,3] row_mask:0x5 bank_mask:0xf
	v_min_u32_dpp v5, v252, v4 quad_perm:[0,1,2,3] row_mask:0xa bank_mask:0xf
	s_nop 1
	v_max_u32_dpp v4, v5, v5 row_ror:8 row_mask:0xf bank_mask:0x3
	v_min_u32_dpp v4, v5, v5 row_ror:8 row_mask:0xf bank_mask:0xc
	s_nop 1
	v_max_u32_dpp v5, v4, v4 row_ror:12 row_mask:0xf bank_mask:0x5
	v_min_u32_dpp v5, v4, v4 row_ror:4 row_mask:0xf bank_mask:0xa
	s_nop 1
	v_max_u32_dpp v250, v5, v5 quad_perm:[2,3,0,1] row_mask:0xf bank_mask:0xf
	v_min_u32_dpp v251, v5, v5 quad_perm:[2,3,0,1] row_mask:0xf bank_mask:0xf
	v_cndmask_b32_e64 v4, v251, v250, s[48:49]
	s_nop 1
	v_max_u32_dpp v250, v4, v4 quad_perm:[1,0,3,2] row_mask:0xf bank_mask:0xf
	v_min_u32_dpp v251, v4, v4 quad_perm:[1,0,3,2] row_mask:0xf bank_mask:0xf
	v_cndmask_b32_e32 v5, v251, v250, vcc
	v_xor_b32_e32 v253, 63, v81
	v_lshlrev_b32_e32 v253, 2, v253
	ds_bpermute_b32 v252, v253, v5
	s_waitcnt lgkmcnt(0)
	v_max_u32_dpp v4, v252, v5 quad_perm:[0,1,2,3] row_mask:0x3 bank_mask:0xf
	v_min_u32_dpp v4, v252, v5 quad_perm:[0,1,2,3] row_mask:0xc bank_mask:0xf
	ds_swizzle_b32 v252, v4 offset:0x401f
	s_waitcnt lgkmcnt(0)
	v_max_u32_dpp v5, v252, v4 quad_perm:[0,1,2,3] row_mask:0x5 bank_mask:0xf
	v_min_u32_dpp v5, v252, v4 quad_perm:[0,1,2,3] row_mask:0xa bank_mask:0xf
	s_nop 1
	v_max_u32_dpp v4, v5, v5 row_ror:8 row_mask:0xf bank_mask:0x3
	v_min_u32_dpp v4, v5, v5 row_ror:8 row_mask:0xf bank_mask:0xc
	s_nop 1
	v_max_u32_dpp v5, v4, v4 row_ror:12 row_mask:0xf bank_mask:0x5
	v_min_u32_dpp v5, v4, v4 row_ror:4 row_mask:0xf bank_mask:0xa
	s_nop 1
	v_max_u32_dpp v250, v5, v5 quad_perm:[2,3,0,1] row_mask:0xf bank_mask:0xf
	v_min_u32_dpp v251, v5, v5 quad_perm:[2,3,0,1] row_mask:0xf bank_mask:0xf
	v_cndmask_b32_e64 v4, v251, v250, s[48:49]
	s_nop 1
	v_max_u32_dpp v250, v4, v4 quad_perm:[1,0,3,2] row_mask:0xf bank_mask:0xf
	v_min_u32_dpp v251, v4, v4 quad_perm:[1,0,3,2] row_mask:0xf bank_mask:0xf
	v_cndmask_b32_e32 v5, v251, v250, vcc
	v_not_b32_e32 v253, v5
	v_and_b32_e32 v253, 63, v253
	v_lshlrev_b32_e32 v253, 2, v253
	ds_permute_b32 v4, v253, v81
	s_waitcnt lgkmcnt(0)
	v_lshlrev_b32_e32 v10, 3, v4
	v_lshlrev_b32_e32 v5, 7, v4
	v_and_b32_e32 v10, 0x70, v10
	v_and_or_b32 v5, v5, s43, v10
	v_cmp_gt_u32_e32 vcc, 16, v4
	ds_permute_b32 v4, v17, v8
	s_nop 0
	v_cndmask_b32_e32 v10, 4, v5, vcc
	ds_permute_b32 v1, v10, v1
	s_waitcnt lgkmcnt(2)
	v_add_f32_e32 v5, v7, v9
	v_div_scale_f32 v7, s[2:3], v5, v5, v6
	v_rcp_f32_e32 v9, v7
	s_waitcnt lgkmcnt(0)
	v_readlane_b32 s2, v1, 0
	v_div_scale_f32 v11, vcc, v6, v5, v6
	s_nop 0
	v_subrev_f32_e32 v1, s2, v1
	v_mul_f32_e32 v1, 0x3fb8aa3b, v1
	v_exp_f32_e32 v1, v1
	v_fma_f32 v8, -v7, v9, 1.0
	v_fmac_f32_e32 v9, v8, v9
	v_mul_f32_e32 v12, v11, v9
	v_cndmask_b32_e64 v1, 0, v1, s[12:13]
	ds_bpermute_b32 v8, v240, v1
	v_fma_f32 v13, -v7, v12, v11
	v_fmac_f32_e32 v12, v13, v9
	v_fma_f32 v7, -v7, v12, v11
	v_div_fmas_f32 v7, v7, v9, v12
	s_waitcnt lgkmcnt(0)
	v_add_f32_e32 v8, v1, v8
	ds_bpermute_b32 v14, v241, v8
	v_div_fixup_f32 v5, v7, v5, v6
	v_or_b32_e32 v6, 0x80000000, v0
	v_not_b32_e32 v7, v0
	v_cmp_gt_i32_e32 vcc, 0, v0
	s_waitcnt lgkmcnt(0)
	v_add_f32_e32 v8, v8, v14
	ds_bpermute_b32 v9, v242, v8
	v_cndmask_b32_e32 v6, v6, v7, vcc
	v_and_b32_e32 v6, 0xffffffc0, v6
	v_cndmask_b32_e64 v6, 0, v6, s[10:11]
	v_bitop3_b32 v6, v6, 63, v81 bitop3:0x36
	ds_write2st64_b64 v239, v[2:3], v[4:5] offset1:1
	s_cmp_lg_u32 s54, 0
	s_cbranch_scc1 .Lg_selskip
	s_mov_b32 vcc_lo, 0x55555555
	s_waitcnt lgkmcnt(1)
	v_add_f32_e32 v4, v8, v9
	s_mov_b32 vcc_hi, 0x55555555
	ds_bpermute_b32 v5, v243, v4
	s_mov_b32 s48, 0x33333333
	s_mov_b32 s49, 0x33333333
	v_lshlrev_b32_e32 v2, 7, v21
	v_max_u32_dpp v250, v6, v6 quad_perm:[1,0,3,2] row_mask:0xf bank_mask:0xf
	v_min_u32_dpp v251, v6, v6 quad_perm:[1,0,3,2] row_mask:0xf bank_mask:0xf
	v_cndmask_b32_e32 v7, v251, v250, vcc
	v_and_b32_e32 v3, 0x7f, v117
	s_nop 1
	v_max_u32_dpp v250, v7, v7 quad_perm:[3,2,1,0] row_mask:0xf bank_mask:0xf
	v_min_u32_dpp v251, v7, v7 quad_perm:[3,2,1,0] row_mask:0xf bank_mask:0xf
	v_and_or_b32 v2, v2, s44, v3
	v_cndmask_b32_e64 v6, v251, v250, s[48:49]
	s_nop 1
	v_max_u32_dpp v250, v6, v6 quad_perm:[1,0,3,2] row_mask:0xf bank_mask:0xf
	s_waitcnt lgkmcnt(0)
	v_min_u32_dpp v251, v6, v6 quad_perm:[1,0,3,2] row_mask:0xf bank_mask:0xf
	v_add_f32_e32 v3, v4, v5
	v_cndmask_b32_e32 v7, v251, v250, vcc
	s_nop 1
	v_max_u32_dpp v6, v7, v7 row_half_mirror row_mask:0xf bank_mask:0x5
	ds_permute_b32 v2, v10, v2
	v_min_u32_dpp v6, v7, v7 row_half_mirror row_mask:0xf bank_mask:0xa
	s_nop 1
	v_max_u32_dpp v250, v6, v6 quad_perm:[2,3,0,1] row_mask:0xf bank_mask:0xf
	v_min_u32_dpp v251, v6, v6 quad_perm:[2,3,0,1] row_mask:0xf bank_mask:0xf
	v_cndmask_b32_e64 v7, v251, v250, s[48:49]
	s_nop 1
	v_max_u32_dpp v250, v7, v7 quad_perm:[1,0,3,2] row_mask:0xf bank_mask:0xf
	v_min_u32_dpp v251, v7, v7 quad_perm:[1,0,3,2] row_mask:0xf bank_mask:0xf
	v_cndmask_b32_e32 v6, v251, v250, vcc
	s_nop 1
	v_max_u32_dpp v7, v6, v6 row_mirror row_mask:0xf bank_mask:0x3
	v_min_u32_dpp v7, v6, v6 row_mirror row_mask:0xf bank_mask:0xc
	s_nop 1
	v_max_u32_dpp v6, v7, v7 row_ror:12 row_mask:0xf bank_mask:0x5
	v_min_u32_dpp v6, v7, v7 row_ror:4 row_mask:0xf bank_mask:0xa
	s_nop 1
	v_max_u32_dpp v250, v6, v6 quad_perm:[2,3,0,1] row_mask:0xf bank_mask:0xf
	v_min_u32_dpp v251, v6, v6 quad_perm:[2,3,0,1] row_mask:0xf bank_mask:0xf
	v_cndmask_b32_e64 v7, v251, v250, s[48:49]
	s_nop 1
	v_max_u32_dpp v250, v7, v7 quad_perm:[1,0,3,2] row_mask:0xf bank_mask:0xf
	v_min_u32_dpp v251, v7, v7 quad_perm:[1,0,3,2] row_mask:0xf bank_mask:0xf
	v_cndmask_b32_e32 v6, v251, v250, vcc
	ds_swizzle_b32 v252, v6 offset:0x7c1f
	s_waitcnt lgkmcnt(0)
	v_max_u32_dpp v7, v252, v6 quad_perm:[0,1,2,3] row_mask:0x5 bank_mask:0xf
	v_min_u32_dpp v7, v252, v6 quad_perm:[0,1,2,3] row_mask:0xa bank_mask:0xf
	s_nop 1
	v_max_u32_dpp v6, v7, v7 row_ror:8 row_mask:0xf bank_mask:0x3
	v_min_u32_dpp v6, v7, v7 row_ror:8 row_mask:0xf bank_mask:0xc
	s_nop 1
	v_max_u32_dpp v7, v6, v6 row_ror:12 row_mask:0xf bank_mask:0x5
	v_min_u32_dpp v7, v6, v6 row_ror:4 row_mask:0xf bank_mask:0xa
	s_nop 1
	v_max_u32_dpp v250, v7, v7 quad_perm:[2,3,0,1] row_mask:0xf bank_mask:0xf
	v_min_u32_dpp v251, v7, v7 quad_perm:[2,3,0,1] row_mask:0xf bank_mask:0xf
	v_cndmask_b32_e64 v6, v251, v250, s[48:49]
	s_nop 1
	v_max_u32_dpp v250, v6, v6 quad_perm:[1,0,3,2] row_mask:0xf bank_mask:0xf
	v_min_u32_dpp v251, v6, v6 quad_perm:[1,0,3,2] row_mask:0xf bank_mask:0xf
	v_cndmask_b32_e32 v7, v251, v250, vcc
	v_xor_b32_e32 v253, 63, v81
	v_lshlrev_b32_e32 v253, 2, v253
	ds_bpermute_b32 v252, v253, v7
	s_waitcnt lgkmcnt(0)
	v_max_u32_dpp v6, v252, v7 quad_perm:[0,1,2,3] row_mask:0x3 bank_mask:0xf
	v_min_u32_dpp v6, v252, v7 quad_perm:[0,1,2,3] row_mask:0xc bank_mask:0xf
	ds_swizzle_b32 v252, v6 offset:0x401f
	s_waitcnt lgkmcnt(0)
	v_max_u32_dpp v7, v252, v6 quad_perm:[0,1,2,3] row_mask:0x5 bank_mask:0xf
	v_min_u32_dpp v7, v252, v6 quad_perm:[0,1,2,3] row_mask:0xa bank_mask:0xf
	s_nop 1
	v_max_u32_dpp v6, v7, v7 row_ror:8 row_mask:0xf bank_mask:0x3
	v_min_u32_dpp v6, v7, v7 row_ror:8 row_mask:0xf bank_mask:0xc
	s_nop 1
	v_max_u32_dpp v7, v6, v6 row_ror:12 row_mask:0xf bank_mask:0x5
	v_min_u32_dpp v7, v6, v6 row_ror:4 row_mask:0xf bank_mask:0xa
	s_nop 1
	v_max_u32_dpp v250, v7, v7 quad_perm:[2,3,0,1] row_mask:0xf bank_mask:0xf
	v_min_u32_dpp v251, v7, v7 quad_perm:[2,3,0,1] row_mask:0xf bank_mask:0xf
	v_cndmask_b32_e64 v6, v251, v250, s[48:49]
	s_nop 1
	v_max_u32_dpp v250, v6, v6 quad_perm:[1,0,3,2] row_mask:0xf bank_mask:0xf
	v_min_u32_dpp v251, v6, v6 quad_perm:[1,0,3,2] row_mask:0xf bank_mask:0xf
	v_cndmask_b32_e32 v7, v251, v250, vcc
	v_not_b32_e32 v253, v7
	v_and_b32_e32 v253, 63, v253
	v_lshlrev_b32_e32 v253, 2, v253
	ds_permute_b32 v6, v253, v81
	s_waitcnt lgkmcnt(0)
	v_lshlrev_b32_e32 v8, 3, v6
	v_lshlrev_b32_e32 v7, 7, v6
	v_and_b32_e32 v8, 0x70, v8
	v_and_or_b32 v7, v7, s43, v8
	v_cmp_gt_u32_e32 vcc, 16, v6
	v_and_b32_e32 v8, 0x7f, v31
	s_nop 0
	v_cndmask_b32_e32 v6, 4, v7, vcc
	ds_permute_b32 v0, v6, v0
	v_lshlrev_b32_e32 v7, 7, v23
	v_and_or_b32 v7, v7, s44, v8
	s_waitcnt lgkmcnt(0)
	v_readlane_b32 s2, v0, 0
	s_nop 1
	v_subrev_f32_e32 v0, s2, v0
	v_mul_f32_e32 v0, 0x3fb8aa3b, v0
	v_exp_f32_e32 v0, v0
	v_div_scale_f32 v4, s[2:3], v3, v3, v1
	v_rcp_f32_e32 v5, v4
	v_cndmask_b32_e64 v9, 0, v0, s[12:13]
	ds_bpermute_b32 v0, v240, v9
	v_fma_f32 v10, -v4, v5, 1.0
	v_fmac_f32_e32 v5, v10, v5
	v_div_scale_f32 v10, vcc, v1, v3, v1
	s_waitcnt lgkmcnt(0)
	v_add_f32_e32 v0, v9, v0
	ds_bpermute_b32 v11, v241, v0
	v_mul_f32_e32 v12, v10, v5
	v_fma_f32 v13, -v4, v12, v10
	v_fmac_f32_e32 v12, v13, v5
	v_fma_f32 v4, -v4, v12, v10
	s_waitcnt lgkmcnt(0)
	v_add_f32_e32 v0, v0, v11
	ds_bpermute_b32 v10, v242, v0
	v_div_fmas_f32 v4, v4, v5, v12
	s_waitcnt vmcnt(27)
	v_cmp_lt_i32_e32 vcc, -1, v30
	v_div_fixup_f32 v3, v4, v3, v1
	v_and_b32_e32 v4, 0xffffff80, v22
	v_cndmask_b32_e64 v1, v232, -1, vcc
	v_cmp_lt_i32_e32 vcc, -1, v22
	s_waitcnt lgkmcnt(0)
	v_add_f32_e32 v8, v0, v10
	v_and_b32_e32 v0, 0xffffff80, v30
	v_cndmask_b32_e64 v5, v232, -1, vcc
	s_waitcnt vmcnt(26)
	v_cmp_lt_i32_e32 vcc, -1, v29
	v_xor_b32_e32 v1, v1, v0
	v_xor_b32_e32 v5, v5, v4
	v_cndmask_b32_e64 v11, v232, -1, vcc
	v_cmp_lt_i32_e32 vcc, -1, v24
	v_and_b32_e32 v0, 0xffffff80, v29
	v_and_b32_e32 v4, 0xffffff80, v24
	v_cndmask_b32_e64 v12, v232, -1, vcc
	v_xor_b32_e32 v0, v11, v0
	v_xor_b32_e32 v4, v12, v4
	v_pk_add_f32 v[0:1], v[4:5], v[0:1]
	ds_bpermute_b32 v10, v243, v8
	v_or_b32_e32 v4, 0x80000000, v1
	v_not_b32_e32 v5, v1
	v_cmp_gt_i32_e32 vcc, 0, v1
	s_nop 1
	v_cndmask_b32_e32 v4, v4, v5, vcc
	v_and_b32_e32 v4, 0xffffffc0, v4
	v_cndmask_b32_e64 v4, 0, v4, s[10:11]
	v_bitop3_b32 v4, v4, 63, v81 bitop3:0x36
	s_nop 0
	s_mov_b32 vcc_lo, 0x55555555
	s_mov_b32 vcc_hi, 0x55555555
	s_mov_b32 s48, 0x33333333
	s_mov_b32 s49, 0x33333333
	v_max_u32_dpp v250, v4, v4 quad_perm:[1,0,3,2] row_mask:0xf bank_mask:0xf
	v_min_u32_dpp v251, v4, v4 quad_perm:[1,0,3,2] row_mask:0xf bank_mask:0xf
	v_cndmask_b32_e32 v5, v251, v250, vcc
	s_nop 1
	v_max_u32_dpp v250, v5, v5 quad_perm:[3,2,1,0] row_mask:0xf bank_mask:0xf
	v_min_u32_dpp v251, v5, v5 quad_perm:[3,2,1,0] row_mask:0xf bank_mask:0xf
	v_cndmask_b32_e64 v4, v251, v250, s[48:49]
	s_nop 1
	v_max_u32_dpp v250, v4, v4 quad_perm:[1,0,3,2] row_mask:0xf bank_mask:0xf
	v_min_u32_dpp v251, v4, v4 quad_perm:[1,0,3,2] row_mask:0xf bank_mask:0xf
	v_cndmask_b32_e32 v5, v251, v250, vcc
	s_nop 1
	v_max_u32_dpp v4, v5, v5 row_half_mirror row_mask:0xf bank_mask:0x5
	v_min_u32_dpp v4, v5, v5 row_half_mirror row_mask:0xf bank_mask:0xa
	s_nop 1
	v_max_u32_dpp v250, v4, v4 quad_perm:[2,3,0,1] row_mask:0xf bank_mask:0xf
	v_min_u32_dpp v251, v4, v4 quad_perm:[2,3,0,1] row_mask:0xf bank_mask:0xf
	v_cndmask_b32_e64 v5, v251, v250, s[48:49]
	s_nop 1
	v_max_u32_dpp v250, v5, v5 quad_perm:[1,0,3,2] row_mask:0xf bank_mask:0xf
	v_min_u32_dpp v251, v5, v5 quad_perm:[1,0,3,2] row_mask:0xf bank_mask:0xf
	v_cndmask_b32_e32 v4, v251, v250, vcc
	s_nop 1
	v_max_u32_dpp v5, v4, v4 row_mirror row_mask:0xf bank_mask:0x3
	v_min_u32_dpp v5, v4, v4 row_mirror row_mask:0xf bank_mask:0xc
	s_nop 1
	v_max_u32_dpp v4, v5, v5 row_ror:12 row_mask:0xf bank_mask:0x5
	v_min_u32_dpp v4, v5, v5 row_ror:4 row_mask:0xf bank_mask:0xa
	s_nop 1
	v_max_u32_dpp v250, v4, v4 quad_perm:[2,3,0,1] row_mask:0xf bank_mask:0xf
	v_min_u32_dpp v251, v4, v4 quad_perm:[2,3,0,1] row_mask:0xf bank_mask:0xf
	v_cndmask_b32_e64 v5, v251, v250, s[48:49]
	s_nop 1
	v_max_u32_dpp v250, v5, v5 quad_perm:[1,0,3,2] row_mask:0xf bank_mask:0xf
	v_min_u32_dpp v251, v5, v5 quad_perm:[1,0,3,2] row_mask:0xf bank_mask:0xf
	v_cndmask_b32_e32 v4, v251, v250, vcc
	ds_swizzle_b32 v252, v4 offset:0x7c1f
	s_waitcnt lgkmcnt(0)
	v_max_u32_dpp v5, v252, v4 quad_perm:[0,1,2,3] row_mask:0x5 bank_mask:0xf
	v_min_u32_dpp v5, v252, v4 quad_perm:[0,1,2,3] row_mask:0xa bank_mask:0xf
	s_nop 1
	v_max_u32_dpp v4, v5, v5 row_ror:8 row_mask:0xf bank_mask:0x3
	v_min_u32_dpp v4, v5, v5 row_ror:8 row_mask:0xf bank_mask:0xc
	s_nop 1
	v_max_u32_dpp v5, v4, v4 row_ror:12 row_mask:0xf bank_mask:0x5
	v_min_u32_dpp v5, v4, v4 row_ror:4 row_mask:0xf bank_mask:0xa
	s_nop 1
	v_max_u32_dpp v250, v5, v5 quad_perm:[2,3,0,1] row_mask:0xf bank_mask:0xf
	v_min_u32_dpp v251, v5, v5 quad_perm:[2,3,0,1] row_mask:0xf bank_mask:0xf
	v_cndmask_b32_e64 v4, v251, v250, s[48:49]
	s_nop 1
	v_max_u32_dpp v250, v4, v4 quad_perm:[1,0,3,2] row_mask:0xf bank_mask:0xf
	v_min_u32_dpp v251, v4, v4 quad_perm:[1,0,3,2] row_mask:0xf bank_mask:0xf
	v_cndmask_b32_e32 v5, v251, v250, vcc
	v_xor_b32_e32 v253, 63, v81
	v_lshlrev_b32_e32 v253, 2, v253
	ds_bpermute_b32 v252, v253, v5
	s_waitcnt lgkmcnt(0)
	v_max_u32_dpp v4, v252, v5 quad_perm:[0,1,2,3] row_mask:0x3 bank_mask:0xf
	v_min_u32_dpp v4, v252, v5 quad_perm:[0,1,2,3] row_mask:0xc bank_mask:0xf
	ds_swizzle_b32 v252, v4 offset:0x401f
	s_waitcnt lgkmcnt(0)
	v_max_u32_dpp v5, v252, v4 quad_perm:[0,1,2,3] row_mask:0x5 bank_mask:0xf
	v_min_u32_dpp v5, v252, v4 quad_perm:[0,1,2,3] row_mask:0xa bank_mask:0xf
	s_nop 1
	v_max_u32_dpp v4, v5, v5 row_ror:8 row_mask:0xf bank_mask:0x3
	v_min_u32_dpp v4, v5, v5 row_ror:8 row_mask:0xf bank_mask:0xc
	s_nop 1
	v_max_u32_dpp v5, v4, v4 row_ror:12 row_mask:0xf bank_mask:0x5
	v_min_u32_dpp v5, v4, v4 row_ror:4 row_mask:0xf bank_mask:0xa
	s_nop 1
	v_max_u32_dpp v250, v5, v5 quad_perm:[2,3,0,1] row_mask:0xf bank_mask:0xf
	v_min_u32_dpp v251, v5, v5 quad_perm:[2,3,0,1] row_mask:0xf bank_mask:0xf
	v_cndmask_b32_e64 v4, v251, v250, s[48:49]
	s_nop 1
	v_max_u32_dpp v250, v4, v4 quad_perm:[1,0,3,2] row_mask:0xf bank_mask:0xf
	v_min_u32_dpp v251, v4, v4 quad_perm:[1,0,3,2] row_mask:0xf bank_mask:0xf
	v_cndmask_b32_e32 v5, v251, v250, vcc
	v_not_b32_e32 v253, v5
	v_and_b32_e32 v253, 63, v253
	v_lshlrev_b32_e32 v253, 2, v253
	ds_permute_b32 v4, v253, v81
	s_waitcnt lgkmcnt(0)
	v_lshlrev_b32_e32 v11, 3, v4
	v_lshlrev_b32_e32 v5, 7, v4
	v_and_b32_e32 v11, 0x70, v11
	v_and_or_b32 v5, v5, s43, v11
	v_cmp_gt_u32_e32 vcc, 16, v4
	ds_permute_b32 v4, v6, v7
	s_nop 0
	v_cndmask_b32_e32 v11, 4, v5, vcc
	ds_permute_b32 v1, v11, v1
	s_waitcnt lgkmcnt(2)
	v_add_f32_e32 v5, v8, v10
	v_div_scale_f32 v8, s[2:3], v5, v5, v9
	v_rcp_f32_e32 v10, v8
	s_waitcnt lgkmcnt(0)
	v_readlane_b32 s2, v1, 0
	v_div_scale_f32 v7, vcc, v9, v5, v9
	s_nop 0
	v_subrev_f32_e32 v1, s2, v1
	v_mul_f32_e32 v1, 0x3fb8aa3b, v1
	v_exp_f32_e32 v1, v1
	v_fma_f32 v6, -v8, v10, 1.0
	v_fmac_f32_e32 v10, v6, v10
	v_mul_f32_e32 v12, v7, v10
	v_cndmask_b32_e64 v1, 0, v1, s[12:13]
	ds_bpermute_b32 v6, v240, v1
	v_fma_f32 v13, -v8, v12, v7
	v_fmac_f32_e32 v12, v13, v10
	v_fma_f32 v7, -v8, v12, v7
	v_div_fmas_f32 v7, v7, v10, v12
	s_waitcnt lgkmcnt(0)
	v_add_f32_e32 v6, v1, v6
	ds_bpermute_b32 v14, v241, v6
	v_div_fixup_f32 v5, v7, v5, v9
	ds_write2st64_b64 v239, v[2:3], v[4:5] offset0:2 offset1:3
	v_not_b32_e32 v7, v0
	v_cmp_gt_i32_e32 vcc, 0, v0
	s_waitcnt lgkmcnt(1)
	v_add_f32_e32 v6, v6, v14
	ds_bpermute_b32 v8, v242, v6
	v_lshlrev_b32_e32 v2, 7, v22
	v_and_b32_e32 v3, 0x7f, v30
	v_and_or_b32 v2, v2, s44, v3
	v_lshlrev_b32_e32 v3, 7, v24
	s_waitcnt lgkmcnt(0)
	v_add_f32_e32 v4, v6, v8
	v_or_b32_e32 v6, 0x80000000, v0
	v_cndmask_b32_e32 v6, v6, v7, vcc
	v_and_b32_e32 v6, 0xffffffc0, v6
	v_cndmask_b32_e64 v6, 0, v6, s[10:11]
	v_bitop3_b32 v6, v6, 63, v81 bitop3:0x36
	ds_bpermute_b32 v5, v243, v4
	s_mov_b32 vcc_lo, 0x55555555
	s_waitcnt lgkmcnt(0)
	s_mov_b32 vcc_hi, 0x55555555
	v_add_f32_e32 v4, v4, v5
	s_mov_b32 s48, 0x33333333
	s_mov_b32 s49, 0x33333333
	v_max_u32_dpp v250, v6, v6 quad_perm:[1,0,3,2] row_mask:0xf bank_mask:0xf
	v_min_u32_dpp v251, v6, v6 quad_perm:[1,0,3,2] row_mask:0xf bank_mask:0xf
	v_cndmask_b32_e32 v7, v251, v250, vcc
	s_nop 1
	v_max_u32_dpp v250, v7, v7 quad_perm:[3,2,1,0] row_mask:0xf bank_mask:0xf
	v_min_u32_dpp v251, v7, v7 quad_perm:[3,2,1,0] row_mask:0xf bank_mask:0xf
	v_cndmask_b32_e64 v6, v251, v250, s[48:49]
	s_nop 1
	v_max_u32_dpp v250, v6, v6 quad_perm:[1,0,3,2] row_mask:0xf bank_mask:0xf
	v_min_u32_dpp v251, v6, v6 quad_perm:[1,0,3,2] row_mask:0xf bank_mask:0xf
	v_cndmask_b32_e32 v7, v251, v250, vcc
	s_nop 1
	v_max_u32_dpp v6, v7, v7 row_half_mirror row_mask:0xf bank_mask:0x5
	v_min_u32_dpp v6, v7, v7 row_half_mirror row_mask:0xf bank_mask:0xa
	s_nop 1
	v_max_u32_dpp v250, v6, v6 quad_perm:[2,3,0,1] row_mask:0xf bank_mask:0xf
	v_min_u32_dpp v251, v6, v6 quad_perm:[2,3,0,1] row_mask:0xf bank_mask:0xf
	v_cndmask_b32_e64 v7, v251, v250, s[48:49]
	s_nop 1
	v_max_u32_dpp v250, v7, v7 quad_perm:[1,0,3,2] row_mask:0xf bank_mask:0xf
	v_min_u32_dpp v251, v7, v7 quad_perm:[1,0,3,2] row_mask:0xf bank_mask:0xf
	v_cndmask_b32_e32 v6, v251, v250, vcc
	s_nop 1
	v_max_u32_dpp v7, v6, v6 row_mirror row_mask:0xf bank_mask:0x3
	v_min_u32_dpp v7, v6, v6 row_mirror row_mask:0xf bank_mask:0xc
	s_nop 1
	v_max_u32_dpp v6, v7, v7 row_ror:12 row_mask:0xf bank_mask:0x5
	v_min_u32_dpp v6, v7, v7 row_ror:4 row_mask:0xf bank_mask:0xa
	s_nop 1
	v_max_u32_dpp v250, v6, v6 quad_perm:[2,3,0,1] row_mask:0xf bank_mask:0xf
	v_min_u32_dpp v251, v6, v6 quad_perm:[2,3,0,1] row_mask:0xf bank_mask:0xf
	v_cndmask_b32_e64 v7, v251, v250, s[48:49]
	s_nop 1
	v_max_u32_dpp v250, v7, v7 quad_perm:[1,0,3,2] row_mask:0xf bank_mask:0xf
	v_min_u32_dpp v251, v7, v7 quad_perm:[1,0,3,2] row_mask:0xf bank_mask:0xf
	v_cndmask_b32_e32 v6, v251, v250, vcc
	ds_swizzle_b32 v252, v6 offset:0x7c1f
	s_waitcnt lgkmcnt(0)
	v_max_u32_dpp v7, v252, v6 quad_perm:[0,1,2,3] row_mask:0x5 bank_mask:0xf
	v_min_u32_dpp v7, v252, v6 quad_perm:[0,1,2,3] row_mask:0xa bank_mask:0xf
	s_nop 1
	v_max_u32_dpp v6, v7, v7 row_ror:8 row_mask:0xf bank_mask:0x3
	v_min_u32_dpp v6, v7, v7 row_ror:8 row_mask:0xf bank_mask:0xc
	s_nop 1
	v_max_u32_dpp v7, v6, v6 row_ror:12 row_mask:0xf bank_mask:0x5
	v_min_u32_dpp v7, v6, v6 row_ror:4 row_mask:0xf bank_mask:0xa
	s_nop 1
	v_max_u32_dpp v250, v7, v7 quad_perm:[2,3,0,1] row_mask:0xf bank_mask:0xf
	v_min_u32_dpp v251, v7, v7 quad_perm:[2,3,0,1] row_mask:0xf bank_mask:0xf
	v_cndmask_b32_e64 v6, v251, v250, s[48:49]
	s_nop 1
	v_max_u32_dpp v250, v6, v6 quad_perm:[1,0,3,2] row_mask:0xf bank_mask:0xf
	v_min_u32_dpp v251, v6, v6 quad_perm:[1,0,3,2] row_mask:0xf bank_mask:0xf
	v_cndmask_b32_e32 v7, v251, v250, vcc
	v_xor_b32_e32 v253, 63, v81
	v_lshlrev_b32_e32 v253, 2, v253
	ds_bpermute_b32 v252, v253, v7
	s_waitcnt lgkmcnt(0)
	v_max_u32_dpp v6, v252, v7 quad_perm:[0,1,2,3] row_mask:0x3 bank_mask:0xf
	v_min_u32_dpp v6, v252, v7 quad_perm:[0,1,2,3] row_mask:0xc bank_mask:0xf
	ds_swizzle_b32 v252, v6 offset:0x401f
	s_waitcnt lgkmcnt(0)
	v_max_u32_dpp v7, v252, v6 quad_perm:[0,1,2,3] row_mask:0x5 bank_mask:0xf
	v_min_u32_dpp v7, v252, v6 quad_perm:[0,1,2,3] row_mask:0xa bank_mask:0xf
	s_nop 1
	v_max_u32_dpp v6, v7, v7 row_ror:8 row_mask:0xf bank_mask:0x3
	v_min_u32_dpp v6, v7, v7 row_ror:8 row_mask:0xf bank_mask:0xc
	s_nop 1
	v_max_u32_dpp v7, v6, v6 row_ror:12 row_mask:0xf bank_mask:0x5
	v_min_u32_dpp v7, v6, v6 row_ror:4 row_mask:0xf bank_mask:0xa
	s_nop 1
	v_max_u32_dpp v250, v7, v7 quad_perm:[2,3,0,1] row_mask:0xf bank_mask:0xf
	v_min_u32_dpp v251, v7, v7 quad_perm:[2,3,0,1] row_mask:0xf bank_mask:0xf
	v_cndmask_b32_e64 v6, v251, v250, s[48:49]
	s_nop 1
	v_max_u32_dpp v250, v6, v6 quad_perm:[1,0,3,2] row_mask:0xf bank_mask:0xf
	v_min_u32_dpp v251, v6, v6 quad_perm:[1,0,3,2] row_mask:0xf bank_mask:0xf
	v_cndmask_b32_e32 v7, v251, v250, vcc
	v_not_b32_e32 v253, v7
	v_and_b32_e32 v253, 63, v253
	v_lshlrev_b32_e32 v253, 2, v253
	ds_permute_b32 v6, v253, v81
	s_waitcnt lgkmcnt(0)
	v_lshlrev_b32_e32 v8, 3, v6
	v_lshlrev_b32_e32 v7, 7, v6
	v_and_b32_e32 v8, 0x70, v8
	v_and_or_b32 v7, v7, s43, v8
	v_cmp_gt_u32_e32 vcc, 16, v6
	s_nop 1
	v_cndmask_b32_e32 v6, 4, v7, vcc
	ds_permute_b32 v0, v6, v0
	v_and_b32_e32 v7, 0x7f, v29
	v_and_or_b32 v7, v3, s44, v7
	s_waitcnt lgkmcnt(0)
	v_readlane_b32 s2, v0, 0
	s_nop 1
	v_subrev_f32_e32 v0, s2, v0
	v_mul_f32_e32 v0, 0x3fb8aa3b, v0
	v_exp_f32_e32 v5, v0
	ds_permute_b32 v0, v11, v2
	v_div_scale_f32 v8, s[2:3], v4, v4, v1
	v_cndmask_b32_e64 v10, 0, v5, s[12:13]
	ds_bpermute_b32 v2, v240, v10
	v_rcp_f32_e32 v9, v8
	s_waitcnt lgkmcnt(0)
	v_add_f32_e32 v2, v10, v2
	ds_bpermute_b32 v11, v241, v2
	v_fma_f32 v5, -v8, v9, 1.0
	v_fmac_f32_e32 v9, v5, v9
	v_div_scale_f32 v5, vcc, v1, v4, v1
	v_mul_f32_e32 v12, v5, v9
	v_fma_f32 v13, -v8, v12, v5
	v_fmac_f32_e32 v12, v13, v9
	s_waitcnt lgkmcnt(0)
	v_add_f32_e32 v2, v2, v11
	v_fma_f32 v5, -v8, v12, v5
	ds_bpermute_b32 v8, v242, v2
	v_div_fmas_f32 v5, v5, v9, v12
	s_waitcnt vmcnt(25)
	v_cmp_lt_i32_e32 vcc, -1, v19
	v_div_fixup_f32 v1, v5, v4, v1
	v_and_b32_e32 v4, 0xffffff80, v20
	v_cndmask_b32_e64 v3, v232, -1, vcc
	v_cmp_lt_i32_e32 vcc, -1, v20
	s_waitcnt lgkmcnt(0)
	v_add_f32_e32 v8, v2, v8
	v_and_b32_e32 v2, 0xffffff80, v19
	v_cndmask_b32_e64 v5, v232, -1, vcc
	s_waitcnt vmcnt(24)
	v_cmp_lt_i32_e32 vcc, -1, v16
	v_xor_b32_e32 v3, v3, v2
	v_xor_b32_e32 v5, v5, v4
	v_cndmask_b32_e64 v11, v232, -1, vcc
	v_cmp_lt_i32_e32 vcc, -1, v18
	v_and_b32_e32 v2, 0xffffff80, v16
	v_and_b32_e32 v4, 0xffffff80, v18
	v_cndmask_b32_e64 v12, v232, -1, vcc
	v_xor_b32_e32 v2, v11, v2
	v_xor_b32_e32 v4, v12, v4
	v_pk_add_f32 v[2:3], v[4:5], v[2:3]
	ds_bpermute_b32 v9, v243, v8
	v_or_b32_e32 v4, 0x80000000, v3
	v_not_b32_e32 v5, v3
	v_cmp_gt_i32_e32 vcc, 0, v3
	s_nop 1
	v_cndmask_b32_e32 v4, v4, v5, vcc
	v_and_b32_e32 v4, 0xffffffc0, v4
	v_cndmask_b32_e64 v4, 0, v4, s[10:11]
	v_bitop3_b32 v4, v4, 63, v81 bitop3:0x36
	s_nop 0
	s_mov_b32 vcc_lo, 0x55555555
	s_mov_b32 vcc_hi, 0x55555555
	s_mov_b32 s48, 0x33333333
	s_mov_b32 s49, 0x33333333
	v_max_u32_dpp v250, v4, v4 quad_perm:[1,0,3,2] row_mask:0xf bank_mask:0xf
	v_min_u32_dpp v251, v4, v4 quad_perm:[1,0,3,2] row_mask:0xf bank_mask:0xf
	v_cndmask_b32_e32 v5, v251, v250, vcc
	s_nop 1
	v_max_u32_dpp v250, v5, v5 quad_perm:[3,2,1,0] row_mask:0xf bank_mask:0xf
	v_min_u32_dpp v251, v5, v5 quad_perm:[3,2,1,0] row_mask:0xf bank_mask:0xf
	v_cndmask_b32_e64 v4, v251, v250, s[48:49]
	s_nop 1
	v_max_u32_dpp v250, v4, v4 quad_perm:[1,0,3,2] row_mask:0xf bank_mask:0xf
	v_min_u32_dpp v251, v4, v4 quad_perm:[1,0,3,2] row_mask:0xf bank_mask:0xf
	v_cndmask_b32_e32 v5, v251, v250, vcc
	s_nop 1
	v_max_u32_dpp v4, v5, v5 row_half_mirror row_mask:0xf bank_mask:0x5
	v_min_u32_dpp v4, v5, v5 row_half_mirror row_mask:0xf bank_mask:0xa
	s_nop 1
	v_max_u32_dpp v250, v4, v4 quad_perm:[2,3,0,1] row_mask:0xf bank_mask:0xf
	v_min_u32_dpp v251, v4, v4 quad_perm:[2,3,0,1] row_mask:0xf bank_mask:0xf
	v_cndmask_b32_e64 v5, v251, v250, s[48:49]
	s_nop 1
	v_max_u32_dpp v250, v5, v5 quad_perm:[1,0,3,2] row_mask:0xf bank_mask:0xf
	v_min_u32_dpp v251, v5, v5 quad_perm:[1,0,3,2] row_mask:0xf bank_mask:0xf
	v_cndmask_b32_e32 v4, v251, v250, vcc
	s_nop 1
	v_max_u32_dpp v5, v4, v4 row_mirror row_mask:0xf bank_mask:0x3
	v_min_u32_dpp v5, v4, v4 row_mirror row_mask:0xf bank_mask:0xc
	s_nop 1
	v_max_u32_dpp v4, v5, v5 row_ror:12 row_mask:0xf bank_mask:0x5
	v_min_u32_dpp v4, v5, v5 row_ror:4 row_mask:0xf bank_mask:0xa
	s_nop 1
	v_max_u32_dpp v250, v4, v4 quad_perm:[2,3,0,1] row_mask:0xf bank_mask:0xf
	v_min_u32_dpp v251, v4, v4 quad_perm:[2,3,0,1] row_mask:0xf bank_mask:0xf
	v_cndmask_b32_e64 v5, v251, v250, s[48:49]
	s_nop 1
	v_max_u32_dpp v250, v5, v5 quad_perm:[1,0,3,2] row_mask:0xf bank_mask:0xf
	v_min_u32_dpp v251, v5, v5 quad_perm:[1,0,3,2] row_mask:0xf bank_mask:0xf
	v_cndmask_b32_e32 v4, v251, v250, vcc
	ds_swizzle_b32 v252, v4 offset:0x7c1f
	s_waitcnt lgkmcnt(0)
	v_max_u32_dpp v5, v252, v4 quad_perm:[0,1,2,3] row_mask:0x5 bank_mask:0xf
	v_min_u32_dpp v5, v252, v4 quad_perm:[0,1,2,3] row_mask:0xa bank_mask:0xf
	s_nop 1
	v_max_u32_dpp v4, v5, v5 row_ror:8 row_mask:0xf bank_mask:0x3
	v_min_u32_dpp v4, v5, v5 row_ror:8 row_mask:0xf bank_mask:0xc
	s_nop 1
	v_max_u32_dpp v5, v4, v4 row_ror:12 row_mask:0xf bank_mask:0x5
	v_min_u32_dpp v5, v4, v4 row_ror:4 row_mask:0xf bank_mask:0xa
	s_nop 1
	v_max_u32_dpp v250, v5, v5 quad_perm:[2,3,0,1] row_mask:0xf bank_mask:0xf
	v_min_u32_dpp v251, v5, v5 quad_perm:[2,3,0,1] row_mask:0xf bank_mask:0xf
	v_cndmask_b32_e64 v4, v251, v250, s[48:49]
	s_nop 1
	v_max_u32_dpp v250, v4, v4 quad_perm:[1,0,3,2] row_mask:0xf bank_mask:0xf
	v_min_u32_dpp v251, v4, v4 quad_perm:[1,0,3,2] row_mask:0xf bank_mask:0xf
	v_cndmask_b32_e32 v5, v251, v250, vcc
	v_xor_b32_e32 v253, 63, v81
	v_lshlrev_b32_e32 v253, 2, v253
	ds_bpermute_b32 v252, v253, v5
	s_waitcnt lgkmcnt(0)
	v_max_u32_dpp v4, v252, v5 quad_perm:[0,1,2,3] row_mask:0x3 bank_mask:0xf
	v_min_u32_dpp v4, v252, v5 quad_perm:[0,1,2,3] row_mask:0xc bank_mask:0xf
	ds_swizzle_b32 v252, v4 offset:0x401f
	s_waitcnt lgkmcnt(0)
	v_max_u32_dpp v5, v252, v4 quad_perm:[0,1,2,3] row_mask:0x5 bank_mask:0xf
	v_min_u32_dpp v5, v252, v4 quad_perm:[0,1,2,3] row_mask:0xa bank_mask:0xf
	s_nop 1
	v_max_u32_dpp v4, v5, v5 row_ror:8 row_mask:0xf bank_mask:0x3
	v_min_u32_dpp v4, v5, v5 row_ror:8 row_mask:0xf bank_mask:0xc
	s_nop 1
	v_max_u32_dpp v5, v4, v4 row_ror:12 row_mask:0xf bank_mask:0x5
	v_min_u32_dpp v5, v4, v4 row_ror:4 row_mask:0xf bank_mask:0xa
	s_nop 1
	v_max_u32_dpp v250, v5, v5 quad_perm:[2,3,0,1] row_mask:0xf bank_mask:0xf
	v_min_u32_dpp v251, v5, v5 quad_perm:[2,3,0,1] row_mask:0xf bank_mask:0xf
	v_cndmask_b32_e64 v4, v251, v250, s[48:49]
	s_nop 1
	v_max_u32_dpp v250, v4, v4 quad_perm:[1,0,3,2] row_mask:0xf bank_mask:0xf
	v_min_u32_dpp v251, v4, v4 quad_perm:[1,0,3,2] row_mask:0xf bank_mask:0xf
	v_cndmask_b32_e32 v5, v251, v250, vcc
	v_not_b32_e32 v253, v5
	v_and_b32_e32 v253, 63, v253
	v_lshlrev_b32_e32 v253, 2, v253
	ds_permute_b32 v4, v253, v81
	s_waitcnt lgkmcnt(0)
	v_lshlrev_b32_e32 v11, 3, v4
	v_lshlrev_b32_e32 v5, 7, v4
	v_and_b32_e32 v11, 0x70, v11
	v_and_or_b32 v5, v5, s43, v11
	v_cmp_gt_u32_e32 vcc, 16, v4
	ds_permute_b32 v4, v6, v7
	s_nop 0
	v_cndmask_b32_e32 v11, 4, v5, vcc
	s_waitcnt lgkmcnt(1)
	v_add_f32_e32 v5, v8, v9
	v_div_scale_f32 v8, s[2:3], v5, v5, v10
	v_rcp_f32_e32 v9, v8
	v_div_scale_f32 v7, vcc, v10, v5, v10
	ds_permute_b32 v3, v11, v3
	v_fma_f32 v6, -v8, v9, 1.0
	v_fmac_f32_e32 v9, v6, v9
	v_mul_f32_e32 v12, v7, v9
	v_fma_f32 v13, -v8, v12, v7
	v_fmac_f32_e32 v12, v13, v9
	v_fma_f32 v7, -v8, v12, v7
	v_div_fmas_f32 v7, v7, v9, v12
	v_or_b32_e32 v8, 0x80000000, v2
	v_not_b32_e32 v9, v2
	v_cmp_gt_i32_e32 vcc, 0, v2
	s_waitcnt lgkmcnt(0)
	v_readlane_b32 s2, v3, 0
	v_div_fixup_f32 v5, v7, v5, v10
	v_cndmask_b32_e32 v8, v8, v9, vcc
	v_and_b32_e32 v8, 0xffffffc0, v8
	v_cndmask_b32_e64 v8, 0, v8, s[10:11]
	v_bitop3_b32 v8, v8, 63, v81 bitop3:0x36
	v_subrev_f32_e32 v3, s2, v3
	s_mov_b32 vcc_lo, 0x55555555
	v_mul_f32_e32 v3, 0x3fb8aa3b, v3
	v_exp_f32_e32 v3, v3
	s_mov_b32 vcc_hi, 0x55555555
	s_mov_b32 s48, 0x33333333
	s_mov_b32 s49, 0x33333333
	ds_write2st64_b64 v239, v[0:1], v[4:5] offset0:4 offset1:5
	v_max_u32_dpp v250, v8, v8 quad_perm:[1,0,3,2] row_mask:0xf bank_mask:0xf
	v_min_u32_dpp v251, v8, v8 quad_perm:[1,0,3,2] row_mask:0xf bank_mask:0xf
	v_cndmask_b32_e32 v9, v251, v250, vcc
	v_cndmask_b32_e64 v3, 0, v3, s[12:13]
	s_nop 1
	v_max_u32_dpp v250, v9, v9 quad_perm:[3,2,1,0] row_mask:0xf bank_mask:0xf
	v_min_u32_dpp v251, v9, v9 quad_perm:[3,2,1,0] row_mask:0xf bank_mask:0xf
	ds_bpermute_b32 v6, v240, v3
	v_cndmask_b32_e64 v8, v251, v250, s[48:49]
	s_nop 1
	v_max_u32_dpp v250, v8, v8 quad_perm:[1,0,3,2] row_mask:0xf bank_mask:0xf
	v_lshlrev_b32_e32 v0, 7, v20
	v_min_u32_dpp v251, v8, v8 quad_perm:[1,0,3,2] row_mask:0xf bank_mask:0xf
	v_cndmask_b32_e32 v9, v251, v250, vcc
	s_nop 1
	s_waitcnt lgkmcnt(0)
	v_add_f32_e32 v6, v3, v6
	v_max_u32_dpp v8, v9, v9 row_half_mirror row_mask:0xf bank_mask:0x5
	v_min_u32_dpp v8, v9, v9 row_half_mirror row_mask:0xf bank_mask:0xa
	s_nop 1
	ds_bpermute_b32 v13, v241, v6
	v_max_u32_dpp v250, v8, v8 quad_perm:[2,3,0,1] row_mask:0xf bank_mask:0xf
	v_min_u32_dpp v251, v8, v8 quad_perm:[2,3,0,1] row_mask:0xf bank_mask:0xf
	v_cndmask_b32_e64 v9, v251, v250, s[48:49]
	s_waitcnt lgkmcnt(0)
	s_nop 1
	v_add_f32_e32 v6, v6, v13
	v_max_u32_dpp v250, v9, v9 quad_perm:[1,0,3,2] row_mask:0xf bank_mask:0xf
	v_min_u32_dpp v251, v9, v9 quad_perm:[1,0,3,2] row_mask:0xf bank_mask:0xf
	v_cndmask_b32_e32 v8, v251, v250, vcc
	ds_bpermute_b32 v7, v242, v6
	s_nop 1
	v_max_u32_dpp v9, v8, v8 row_mirror row_mask:0xf bank_mask:0x3
	v_min_u32_dpp v9, v8, v8 row_mirror row_mask:0xf bank_mask:0xc
	v_and_b32_e32 v1, 0x7f, v19
	s_nop 1
	v_max_u32_dpp v8, v9, v9 row_ror:12 row_mask:0xf bank_mask:0x5
	v_min_u32_dpp v8, v9, v9 row_ror:4 row_mask:0xf bank_mask:0xa
	s_waitcnt lgkmcnt(0)
	s_nop 1
	v_add_f32_e32 v4, v6, v7
	v_max_u32_dpp v250, v8, v8 quad_perm:[2,3,0,1] row_mask:0xf bank_mask:0xf
	v_min_u32_dpp v251, v8, v8 quad_perm:[2,3,0,1] row_mask:0xf bank_mask:0xf
	v_cndmask_b32_e64 v9, v251, v250, s[48:49]
	v_and_or_b32 v0, v0, s44, v1
	s_nop 1
	v_max_u32_dpp v250, v9, v9 quad_perm:[1,0,3,2] row_mask:0xf bank_mask:0xf
	v_min_u32_dpp v251, v9, v9 quad_perm:[1,0,3,2] row_mask:0xf bank_mask:0xf
	ds_bpermute_b32 v5, v243, v4
	v_cndmask_b32_e32 v8, v251, v250, vcc
	ds_swizzle_b32 v252, v8 offset:0x7c1f
	s_waitcnt lgkmcnt(0)
	ds_permute_b32 v0, v11, v0
	v_max_u32_dpp v9, v252, v8 quad_perm:[0,1,2,3] row_mask:0x5 bank_mask:0xf
	v_min_u32_dpp v9, v252, v8 quad_perm:[0,1,2,3] row_mask:0xa bank_mask:0xf
	v_lshlrev_b32_e32 v6, 7, v18
	s_nop 1
	v_max_u32_dpp v8, v9, v9 row_ror:8 row_mask:0xf bank_mask:0x3
	v_min_u32_dpp v8, v9, v9 row_ror:8 row_mask:0xf bank_mask:0xc
	s_nop 1
	v_max_u32_dpp v9, v8, v8 row_ror:12 row_mask:0xf bank_mask:0x5
	v_min_u32_dpp v9, v8, v8 row_ror:4 row_mask:0xf bank_mask:0xa
	s_nop 1
	v_max_u32_dpp v250, v9, v9 quad_perm:[2,3,0,1] row_mask:0xf bank_mask:0xf
	v_min_u32_dpp v251, v9, v9 quad_perm:[2,3,0,1] row_mask:0xf bank_mask:0xf
	v_cndmask_b32_e64 v8, v251, v250, s[48:49]
	s_nop 1
	v_max_u32_dpp v250, v8, v8 quad_perm:[1,0,3,2] row_mask:0xf bank_mask:0xf
	v_min_u32_dpp v251, v8, v8 quad_perm:[1,0,3,2] row_mask:0xf bank_mask:0xf
	v_cndmask_b32_e32 v9, v251, v250, vcc
	v_xor_b32_e32 v253, 63, v81
	v_lshlrev_b32_e32 v253, 2, v253
	ds_bpermute_b32 v252, v253, v9
	s_waitcnt lgkmcnt(0)
	v_max_u32_dpp v8, v252, v9 quad_perm:[0,1,2,3] row_mask:0x3 bank_mask:0xf
	v_min_u32_dpp v8, v252, v9 quad_perm:[0,1,2,3] row_mask:0xc bank_mask:0xf
	ds_swizzle_b32 v252, v8 offset:0x401f
	s_waitcnt lgkmcnt(0)
	v_max_u32_dpp v9, v252, v8 quad_perm:[0,1,2,3] row_mask:0x5 bank_mask:0xf
	v_min_u32_dpp v9, v252, v8 quad_perm:[0,1,2,3] row_mask:0xa bank_mask:0xf
	s_nop 1
	v_max_u32_dpp v8, v9, v9 row_ror:8 row_mask:0xf bank_mask:0x3
	v_min_u32_dpp v8, v9, v9 row_ror:8 row_mask:0xf bank_mask:0xc
	s_nop 1
	v_max_u32_dpp v9, v8, v8 row_ror:12 row_mask:0xf bank_mask:0x5
	v_min_u32_dpp v9, v8, v8 row_ror:4 row_mask:0xf bank_mask:0xa
	s_nop 1
	v_max_u32_dpp v250, v9, v9 quad_perm:[2,3,0,1] row_mask:0xf bank_mask:0xf
	v_min_u32_dpp v251, v9, v9 quad_perm:[2,3,0,1] row_mask:0xf bank_mask:0xf
	v_cndmask_b32_e64 v8, v251, v250, s[48:49]
	s_nop 1
	v_max_u32_dpp v250, v8, v8 quad_perm:[1,0,3,2] row_mask:0xf bank_mask:0xf
	v_min_u32_dpp v251, v8, v8 quad_perm:[1,0,3,2] row_mask:0xf bank_mask:0xf
	v_cndmask_b32_e32 v9, v251, v250, vcc
	v_not_b32_e32 v253, v9
	v_and_b32_e32 v253, 63, v253
	v_lshlrev_b32_e32 v253, 2, v253
	ds_permute_b32 v8, v253, v81
	s_waitcnt lgkmcnt(0)
	v_lshlrev_b32_e32 v10, 3, v8
	v_lshlrev_b32_e32 v9, 7, v8
	v_and_b32_e32 v10, 0x70, v10
	v_and_or_b32 v9, v9, s43, v10
	v_cmp_gt_u32_e32 vcc, 16, v8
	v_and_b32_e32 v10, 0x7f, v16
	s_nop 0
	v_cndmask_b32_e32 v8, 4, v9, vcc
	ds_permute_b32 v2, v8, v2
	s_waitcnt lgkmcnt(0)
	v_readlane_b32 s2, v2, 0
	s_nop 1
	v_subrev_f32_e32 v2, s2, v2
	v_mul_f32_e32 v2, 0x3fb8aa3b, v2
	v_exp_f32_e32 v2, v2
	s_nop 0
	v_cndmask_b32_e64 v7, 0, v2, s[12:13]
	ds_bpermute_b32 v1, v240, v7
	v_add_f32_e32 v2, v4, v5
	v_div_scale_f32 v4, s[2:3], v2, v2, v3
	v_rcp_f32_e32 v5, v4
	s_waitcnt lgkmcnt(0)
	v_add_f32_e32 v1, v7, v1
	ds_bpermute_b32 v9, v241, v1
	v_fma_f32 v11, -v4, v5, 1.0
	v_fmac_f32_e32 v5, v11, v5
	v_div_scale_f32 v11, vcc, v3, v2, v3
	s_waitcnt lgkmcnt(0)
	v_add_f32_e32 v1, v1, v9
	ds_bpermute_b32 v9, v242, v1
	v_mul_f32_e32 v12, v11, v5
	v_fma_f32 v13, -v4, v12, v11
	v_fmac_f32_e32 v12, v13, v5
	v_fma_f32 v4, -v4, v12, v11
	s_waitcnt lgkmcnt(0)
	v_add_f32_e32 v1, v1, v9
	ds_bpermute_b32 v9, v243, v1
	v_div_fmas_f32 v4, v4, v5, v12
	s_waitcnt lgkmcnt(0)
	v_add_f32_e32 v5, v1, v9
	v_div_scale_f32 v9, s[2:3], v5, v5, v7
	v_rcp_f32_e32 v11, v9
	v_div_fixup_f32 v1, v4, v2, v3
	v_and_or_b32 v2, v6, s44, v10
	ds_permute_b32 v2, v8, v2
	v_fma_f32 v3, -v9, v11, 1.0
	v_fmac_f32_e32 v11, v3, v11
	v_div_scale_f32 v3, vcc, v7, v5, v7
	v_mul_f32_e32 v4, v3, v11
	v_fma_f32 v6, -v9, v4, v3
	v_fmac_f32_e32 v4, v6, v11
	v_fma_f32 v3, -v9, v4, v3
	v_div_fmas_f32 v3, v3, v11, v4
	v_div_fixup_f32 v3, v3, v5, v7
	s_waitcnt lgkmcnt(0)
	ds_write2st64_b64 v239, v[0:1], v[2:3] offset0:6 offset1:7
	s_branch .LBB0_330
.Lg_selskip:
	ds_read_b64 v[250:251], v239 offset:512
	s_waitcnt lgkmcnt(0)
	ds_write_b64 v239, v[250:251] offset:3584
	s_branch .LBB0_330
.LBB0_329:
	s_or_b64 exec, exec, s[2:3]
	v_mad_i64_i32 v[0:1], s[2:3], v0, s28, 0
	v_mad_i64_i32 v[4:5], s[2:3], v2, s28, 0
	v_mad_i64_i32 v[2:3], s[2:3], v3, s28, 0
	v_mad_i64_i32 v[8:9], s[2:3], v6, s28, 0
	v_mad_i64_i32 v[6:7], s[2:3], v7, s28, 0
	v_mad_i64_i32 v[12:13], s[2:3], v10, s28, 0
	v_mad_i64_i32 v[10:11], s[2:3], v11, s28, 0
	v_mad_i64_i32 v[14:15], s[2:3], v14, s28, 0
	s_brev_b32 s2, -2
	s_nop 0
	v_bfi_b32 v16, s2, v19, v16
	v_mul_f32_e32 v18, 0.5, v18
	v_add_f32_e32 v16, 1.0, v16
	v_mul_f32_e32 v16, v18, v16
	v_mul_f32_e32 v16, v17, v16
	v_mul_f32_e32 v117, 0x3daaaaab, v16
	ds_bpermute_b32 v250, v255, v117
	s_nop 0
	s_waitcnt vmcnt(23)
	v_cvt_scalef32_pk_f32_fp4 v[18:19], v110, 1.0
	s_waitcnt lgkmcnt(0)
	ds_bpermute_b32 v252, v255, v117 offset:16
	v_cvt_scalef32_pk_f32_fp4 v[20:21], v110, 1.0 op_sel:[1,0,0]
	v_cvt_scalef32_pk_f32_fp4 v[22:23], v110, 1.0 op_sel:[0,1,0]
	v_cvt_scalef32_pk_f32_fp4 v[24:25], v110, 1.0 op_sel:[1,1,0]
	v_cvt_scalef32_pk_f32_fp4 v[26:27], v111, 1.0
	v_cvt_scalef32_pk_f32_fp4 v[28:29], v111, 1.0 op_sel:[1,0,0]
	v_cvt_scalef32_pk_f32_fp4 v[30:31], v111, 1.0 op_sel:[0,1,0]
	v_cvt_scalef32_pk_f32_fp4 v[110:111], v111, 1.0 op_sel:[1,1,0]
	v_pk_fma_f32 v[110:111], v[250:251], v[110:111], v[202:203] op_sel_hi:[0,1,1]
	v_cvt_scalef32_pk_f32_fp4 v[202:203], v112, 1.0
	v_pk_fma_f32 v[200:201], v[250:251], v[202:203], v[200:201] op_sel_hi:[0,1,1]
	v_cvt_scalef32_pk_f32_fp4 v[202:203], v112, 1.0 op_sel:[1,0,0]
	v_pk_fma_f32 v[198:199], v[250:251], v[202:203], v[198:199] op_sel_hi:[0,1,1]
	v_cvt_scalef32_pk_f32_fp4 v[202:203], v112, 1.0 op_sel:[0,1,0]
	v_pk_fma_f32 v[196:197], v[250:251], v[202:203], v[196:197] op_sel_hi:[0,1,1]
	v_cvt_scalef32_pk_f32_fp4 v[202:203], v112, 1.0 op_sel:[1,1,0]
	v_pk_fma_f32 v[194:195], v[250:251], v[202:203], v[194:195] op_sel_hi:[0,1,1]
	v_cvt_scalef32_pk_f32_fp4 v[202:203], v113, 1.0
	v_pk_fma_f32 v[192:193], v[250:251], v[202:203], v[192:193] op_sel_hi:[0,1,1]
	v_cvt_scalef32_pk_f32_fp4 v[202:203], v113, 1.0 op_sel:[1,0,0]
	v_pk_fma_f32 v[190:191], v[250:251], v[202:203], v[190:191] op_sel_hi:[0,1,1]
	v_cvt_scalef32_pk_f32_fp4 v[202:203], v113, 1.0 op_sel:[0,1,0]
	v_pk_fma_f32 v[188:189], v[250:251], v[202:203], v[188:189] op_sel_hi:[0,1,1]
	v_cvt_scalef32_pk_f32_fp4 v[112:113], v113, 1.0 op_sel:[1,1,0]
	v_pk_fma_f32 v[18:19], v[18:19], v[250:251], v[216:217] op_sel_hi:[1,0,1]
	v_pk_fma_f32 v[20:21], v[20:21], v[250:251], v[214:215] op_sel_hi:[1,0,1]
	v_pk_fma_f32 v[22:23], v[22:23], v[250:251], v[212:213] op_sel_hi:[1,0,1]
	v_pk_fma_f32 v[24:25], v[250:251], v[24:25], v[210:211] op_sel_hi:[0,1,1]
	v_pk_fma_f32 v[26:27], v[250:251], v[26:27], v[208:209] op_sel_hi:[0,1,1]
	v_pk_fma_f32 v[28:29], v[250:251], v[28:29], v[206:207] op_sel_hi:[0,1,1]
	v_pk_fma_f32 v[30:31], v[250:251], v[30:31], v[204:205] op_sel_hi:[0,1,1]
	v_pk_fma_f32 v[16:17], v[250:251], v[112:113], v[176:177] op_sel_hi:[0,1,1]
	s_waitcnt vmcnt(22)
	v_cvt_scalef32_pk_f32_fp4 v[176:177], v106, 1.0
	s_waitcnt lgkmcnt(0)
	ds_bpermute_b32 v250, v255, v117 offset:32
	v_pk_fma_f32 v[18:19], v[176:177], v[252:253], v[18:19] op_sel_hi:[1,0,1]
	v_cvt_scalef32_pk_f32_fp4 v[176:177], v106, 1.0 op_sel:[1,0,0]
	v_pk_fma_f32 v[20:21], v[176:177], v[252:253], v[20:21] op_sel_hi:[1,0,1]
	v_cvt_scalef32_pk_f32_fp4 v[176:177], v106, 1.0 op_sel:[0,1,0]
	v_pk_fma_f32 v[22:23], v[176:177], v[252:253], v[22:23] op_sel_hi:[1,0,1]
	v_cvt_scalef32_pk_f32_fp4 v[176:177], v106, 1.0 op_sel:[1,1,0]
	v_pk_fma_f32 v[24:25], v[252:253], v[176:177], v[24:25] op_sel_hi:[0,1,1]
	v_cvt_scalef32_pk_f32_fp4 v[176:177], v107, 1.0
	v_pk_fma_f32 v[26:27], v[252:253], v[176:177], v[26:27] op_sel_hi:[0,1,1]
	v_cvt_scalef32_pk_f32_fp4 v[176:177], v107, 1.0 op_sel:[1,0,0]
	v_pk_fma_f32 v[28:29], v[252:253], v[176:177], v[28:29] op_sel_hi:[0,1,1]
	v_cvt_scalef32_pk_f32_fp4 v[176:177], v107, 1.0 op_sel:[0,1,0]
	v_pk_fma_f32 v[30:31], v[252:253], v[176:177], v[30:31] op_sel_hi:[0,1,1]
	v_cvt_scalef32_pk_f32_fp4 v[176:177], v108, 1.0 op_sel:[1,0,0]
	v_pk_fma_f32 v[176:177], v[252:253], v[176:177], v[198:199] op_sel_hi:[0,1,1]
	v_cvt_scalef32_pk_f32_fp4 v[198:199], v108, 1.0 op_sel:[0,1,0]
	v_pk_fma_f32 v[196:197], v[252:253], v[198:199], v[196:197] op_sel_hi:[0,1,1]
	v_cvt_scalef32_pk_f32_fp4 v[198:199], v108, 1.0 op_sel:[1,1,0]
	v_pk_fma_f32 v[194:195], v[252:253], v[198:199], v[194:195] op_sel_hi:[0,1,1]
	v_cvt_scalef32_pk_f32_fp4 v[198:199], v109, 1.0
	v_cvt_scalef32_pk_f32_fp4 v[106:107], v107, 1.0 op_sel:[1,1,0]
	v_pk_fma_f32 v[192:193], v[252:253], v[198:199], v[192:193] op_sel_hi:[0,1,1]
	v_cvt_scalef32_pk_f32_fp4 v[198:199], v109, 1.0 op_sel:[1,0,0]
	v_pk_fma_f32 v[106:107], v[252:253], v[106:107], v[110:111] op_sel_hi:[0,1,1]
	v_cvt_scalef32_pk_f32_fp4 v[110:111], v108, 1.0
	v_pk_fma_f32 v[190:191], v[252:253], v[198:199], v[190:191] op_sel_hi:[0,1,1]
	v_cvt_scalef32_pk_f32_fp4 v[198:199], v109, 1.0 op_sel:[0,1,0]
	v_pk_fma_f32 v[110:111], v[252:253], v[110:111], v[200:201] op_sel_hi:[0,1,1]
	v_pk_fma_f32 v[188:189], v[252:253], v[198:199], v[188:189] op_sel_hi:[0,1,1]
	v_cvt_scalef32_pk_f32_fp4 v[108:109], v109, 1.0 op_sel:[1,1,0]
	v_pk_fma_f32 v[16:17], v[252:253], v[108:109], v[16:17] op_sel_hi:[0,1,1]
	s_waitcnt vmcnt(21)
	v_cvt_scalef32_pk_f32_fp4 v[112:113], v102, 1.0
	s_waitcnt lgkmcnt(0)
	ds_bpermute_b32 v252, v255, v117 offset:48
	v_pk_fma_f32 v[18:19], v[112:113], v[250:251], v[18:19] op_sel_hi:[1,0,1]
	v_cvt_scalef32_pk_f32_fp4 v[112:113], v102, 1.0 op_sel:[1,0,0]
	v_pk_fma_f32 v[20:21], v[112:113], v[250:251], v[20:21] op_sel_hi:[1,0,1]
	v_cvt_scalef32_pk_f32_fp4 v[112:113], v102, 1.0 op_sel:[0,1,0]
	v_pk_fma_f32 v[22:23], v[112:113], v[250:251], v[22:23] op_sel_hi:[1,0,1]
	v_cvt_scalef32_pk_f32_fp4 v[112:113], v102, 1.0 op_sel:[1,1,0]
	v_pk_fma_f32 v[24:25], v[250:251], v[112:113], v[24:25] op_sel_hi:[0,1,1]
	v_cvt_scalef32_pk_f32_fp4 v[112:113], v103, 1.0
	v_pk_fma_f32 v[26:27], v[250:251], v[112:113], v[26:27] op_sel_hi:[0,1,1]
	v_cvt_scalef32_pk_f32_fp4 v[112:113], v103, 1.0 op_sel:[1,0,0]
	v_pk_fma_f32 v[28:29], v[250:251], v[112:113], v[28:29] op_sel_hi:[0,1,1]
	v_cvt_scalef32_pk_f32_fp4 v[112:113], v103, 1.0 op_sel:[0,1,0]
	v_cvt_scalef32_pk_f32_fp4 v[102:103], v103, 1.0 op_sel:[1,1,0]
	v_pk_fma_f32 v[102:103], v[250:251], v[102:103], v[106:107] op_sel_hi:[0,1,1]
	v_cvt_scalef32_pk_f32_fp4 v[106:107], v104, 1.0
	v_pk_fma_f32 v[106:107], v[250:251], v[106:107], v[110:111] op_sel_hi:[0,1,1]
	v_cvt_scalef32_pk_f32_fp4 v[110:111], v104, 1.0 op_sel:[1,0,0]
	v_pk_fma_f32 v[110:111], v[250:251], v[110:111], v[176:177] op_sel_hi:[0,1,1]
	v_cvt_scalef32_pk_f32_fp4 v[176:177], v104, 1.0 op_sel:[1,1,0]
	v_pk_fma_f32 v[176:177], v[250:251], v[176:177], v[194:195] op_sel_hi:[0,1,1]
	v_cvt_scalef32_pk_f32_fp4 v[194:195], v105, 1.0
	v_pk_fma_f32 v[192:193], v[250:251], v[194:195], v[192:193] op_sel_hi:[0,1,1]
	v_cvt_scalef32_pk_f32_fp4 v[194:195], v105, 1.0 op_sel:[1,0,0]
	v_pk_fma_f32 v[30:31], v[250:251], v[112:113], v[30:31] op_sel_hi:[0,1,1]
	v_cvt_scalef32_pk_f32_fp4 v[112:113], v104, 1.0 op_sel:[0,1,0]
	v_pk_fma_f32 v[190:191], v[250:251], v[194:195], v[190:191] op_sel_hi:[0,1,1]
	v_cvt_scalef32_pk_f32_fp4 v[194:195], v105, 1.0 op_sel:[0,1,0]
	v_pk_fma_f32 v[112:113], v[250:251], v[112:113], v[196:197] op_sel_hi:[0,1,1]
	v_pk_fma_f32 v[188:189], v[250:251], v[194:195], v[188:189] op_sel_hi:[0,1,1]
	v_cvt_scalef32_pk_f32_fp4 v[104:105], v105, 1.0 op_sel:[1,1,0]
	v_pk_fma_f32 v[16:17], v[250:251], v[104:105], v[16:17] op_sel_hi:[0,1,1]
	s_waitcnt vmcnt(20)
	v_cvt_scalef32_pk_f32_fp4 v[108:109], v98, 1.0
	s_waitcnt lgkmcnt(0)
	ds_bpermute_b32 v250, v255, v117 offset:64
	v_pk_fma_f32 v[18:19], v[108:109], v[252:253], v[18:19] op_sel_hi:[1,0,1]
	v_cvt_scalef32_pk_f32_fp4 v[108:109], v98, 1.0 op_sel:[1,0,0]
	v_pk_fma_f32 v[20:21], v[108:109], v[252:253], v[20:21] op_sel_hi:[1,0,1]
	v_cvt_scalef32_pk_f32_fp4 v[108:109], v98, 1.0 op_sel:[0,1,0]
	v_pk_fma_f32 v[22:23], v[108:109], v[252:253], v[22:23] op_sel_hi:[1,0,1]
	v_cvt_scalef32_pk_f32_fp4 v[108:109], v98, 1.0 op_sel:[1,1,0]
	v_pk_fma_f32 v[24:25], v[252:253], v[108:109], v[24:25] op_sel_hi:[0,1,1]
	v_cvt_scalef32_pk_f32_fp4 v[108:109], v99, 1.0
	v_pk_fma_f32 v[26:27], v[252:253], v[108:109], v[26:27] op_sel_hi:[0,1,1]
	v_cvt_scalef32_pk_f32_fp4 v[108:109], v99, 1.0 op_sel:[1,0,0]
	v_pk_fma_f32 v[28:29], v[252:253], v[108:109], v[28:29] op_sel_hi:[0,1,1]
	v_cvt_scalef32_pk_f32_fp4 v[108:109], v99, 1.0 op_sel:[0,1,0]
	v_cvt_scalef32_pk_f32_fp4 v[98:99], v99, 1.0 op_sel:[1,1,0]
	v_pk_fma_f32 v[98:99], v[252:253], v[98:99], v[102:103] op_sel_hi:[0,1,1]
	v_cvt_scalef32_pk_f32_fp4 v[102:103], v100, 1.0
	v_pk_fma_f32 v[102:103], v[252:253], v[102:103], v[106:107] op_sel_hi:[0,1,1]
	v_cvt_scalef32_pk_f32_fp4 v[106:107], v100, 1.0 op_sel:[1,0,0]
	v_pk_fma_f32 v[106:107], v[252:253], v[106:107], v[110:111] op_sel_hi:[0,1,1]
	v_cvt_scalef32_pk_f32_fp4 v[110:111], v100, 1.0 op_sel:[1,1,0]
	v_pk_fma_f32 v[30:31], v[252:253], v[108:109], v[30:31] op_sel_hi:[0,1,1]
	v_cvt_scalef32_pk_f32_fp4 v[108:109], v100, 1.0 op_sel:[0,1,0]
	v_pk_fma_f32 v[110:111], v[252:253], v[110:111], v[176:177] op_sel_hi:[0,1,1]
	v_cvt_scalef32_pk_f32_fp4 v[176:177], v101, 1.0 op_sel:[1,0,0]
	v_pk_fma_f32 v[108:109], v[252:253], v[108:109], v[112:113] op_sel_hi:[0,1,1]
	v_cvt_scalef32_pk_f32_fp4 v[112:113], v101, 1.0
	v_pk_fma_f32 v[176:177], v[252:253], v[176:177], v[190:191] op_sel_hi:[0,1,1]
	v_cvt_scalef32_pk_f32_fp4 v[190:191], v101, 1.0 op_sel:[0,1,0]
	v_pk_fma_f32 v[112:113], v[252:253], v[112:113], v[192:193] op_sel_hi:[0,1,1]
	v_pk_fma_f32 v[188:189], v[252:253], v[190:191], v[188:189] op_sel_hi:[0,1,1]
	v_cvt_scalef32_pk_f32_fp4 v[100:101], v101, 1.0 op_sel:[1,1,0]
	v_pk_fma_f32 v[16:17], v[252:253], v[100:101], v[16:17] op_sel_hi:[0,1,1]
	s_waitcnt vmcnt(19)
	v_cvt_scalef32_pk_f32_fp4 v[104:105], v94, 1.0
	s_waitcnt lgkmcnt(0)
	ds_bpermute_b32 v252, v255, v117 offset:80
	v_pk_fma_f32 v[18:19], v[104:105], v[250:251], v[18:19] op_sel_hi:[1,0,1]
	v_cvt_scalef32_pk_f32_fp4 v[104:105], v94, 1.0 op_sel:[1,0,0]
	v_pk_fma_f32 v[20:21], v[104:105], v[250:251], v[20:21] op_sel_hi:[1,0,1]
	v_cvt_scalef32_pk_f32_fp4 v[104:105], v94, 1.0 op_sel:[0,1,0]
	v_pk_fma_f32 v[22:23], v[104:105], v[250:251], v[22:23] op_sel_hi:[1,0,1]
	v_cvt_scalef32_pk_f32_fp4 v[104:105], v94, 1.0 op_sel:[1,1,0]
	v_pk_fma_f32 v[24:25], v[250:251], v[104:105], v[24:25] op_sel_hi:[0,1,1]
	v_cvt_scalef32_pk_f32_fp4 v[104:105], v95, 1.0
	v_pk_fma_f32 v[26:27], v[250:251], v[104:105], v[26:27] op_sel_hi:[0,1,1]
	v_cvt_scalef32_pk_f32_fp4 v[104:105], v95, 1.0 op_sel:[1,0,0]
	v_pk_fma_f32 v[28:29], v[250:251], v[104:105], v[28:29] op_sel_hi:[0,1,1]
	v_cvt_scalef32_pk_f32_fp4 v[104:105], v95, 1.0 op_sel:[0,1,0]
	v_cvt_scalef32_pk_f32_fp4 v[94:95], v95, 1.0 op_sel:[1,1,0]
	v_pk_fma_f32 v[94:95], v[250:251], v[94:95], v[98:99] op_sel_hi:[0,1,1]
	v_cvt_scalef32_pk_f32_fp4 v[98:99], v96, 1.0
	v_pk_fma_f32 v[30:31], v[250:251], v[104:105], v[30:31] op_sel_hi:[0,1,1]
	v_pk_fma_f32 v[98:99], v[250:251], v[98:99], v[102:103] op_sel_hi:[0,1,1]
	v_cvt_scalef32_pk_f32_fp4 v[102:103], v96, 1.0 op_sel:[1,0,0]
	v_cvt_scalef32_pk_f32_fp4 v[104:105], v96, 1.0 op_sel:[0,1,0]
	v_pk_fma_f32 v[102:103], v[250:251], v[102:103], v[106:107] op_sel_hi:[0,1,1]
	v_pk_fma_f32 v[104:105], v[250:251], v[104:105], v[108:109] op_sel_hi:[0,1,1]
	v_cvt_scalef32_pk_f32_fp4 v[106:107], v96, 1.0 op_sel:[1,1,0]
	v_cvt_scalef32_pk_f32_fp4 v[108:109], v97, 1.0
	v_pk_fma_f32 v[106:107], v[250:251], v[106:107], v[110:111] op_sel_hi:[0,1,1]
	v_pk_fma_f32 v[108:109], v[250:251], v[108:109], v[112:113] op_sel_hi:[0,1,1]
	v_cvt_scalef32_pk_f32_fp4 v[110:111], v97, 1.0 op_sel:[1,0,0]
	v_cvt_scalef32_pk_f32_fp4 v[112:113], v97, 1.0 op_sel:[0,1,0]
	v_pk_fma_f32 v[110:111], v[250:251], v[110:111], v[176:177] op_sel_hi:[0,1,1]
	v_pk_fma_f32 v[112:113], v[250:251], v[112:113], v[188:189] op_sel_hi:[0,1,1]
	v_cvt_scalef32_pk_f32_fp4 v[96:97], v97, 1.0 op_sel:[1,1,0]
	v_pk_fma_f32 v[16:17], v[250:251], v[96:97], v[16:17] op_sel_hi:[0,1,1]
	s_waitcnt vmcnt(18)
	v_cvt_scalef32_pk_f32_fp4 v[100:101], v90, 1.0
	s_waitcnt lgkmcnt(0)
	ds_bpermute_b32 v250, v255, v117 offset:96
	v_pk_fma_f32 v[18:19], v[100:101], v[252:253], v[18:19] op_sel_hi:[1,0,1]
	v_cvt_scalef32_pk_f32_fp4 v[100:101], v90, 1.0 op_sel:[1,0,0]
	v_pk_fma_f32 v[20:21], v[100:101], v[252:253], v[20:21] op_sel_hi:[1,0,1]
	v_cvt_scalef32_pk_f32_fp4 v[100:101], v90, 1.0 op_sel:[0,1,0]
	v_pk_fma_f32 v[22:23], v[100:101], v[252:253], v[22:23] op_sel_hi:[1,0,1]
	v_cvt_scalef32_pk_f32_fp4 v[100:101], v90, 1.0 op_sel:[1,1,0]
	v_pk_fma_f32 v[24:25], v[252:253], v[100:101], v[24:25] op_sel_hi:[0,1,1]
	v_cvt_scalef32_pk_f32_fp4 v[100:101], v91, 1.0
	v_pk_fma_f32 v[26:27], v[252:253], v[100:101], v[26:27] op_sel_hi:[0,1,1]
	v_cvt_scalef32_pk_f32_fp4 v[100:101], v91, 1.0 op_sel:[1,0,0]
	v_pk_fma_f32 v[28:29], v[252:253], v[100:101], v[28:29] op_sel_hi:[0,1,1]
	v_cvt_scalef32_pk_f32_fp4 v[100:101], v91, 1.0 op_sel:[0,1,0]
	v_cvt_scalef32_pk_f32_fp4 v[90:91], v91, 1.0 op_sel:[1,1,0]
	v_pk_fma_f32 v[90:91], v[252:253], v[90:91], v[94:95] op_sel_hi:[0,1,1]
	v_cvt_scalef32_pk_f32_fp4 v[94:95], v92, 1.0
	v_pk_fma_f32 v[30:31], v[252:253], v[100:101], v[30:31] op_sel_hi:[0,1,1]
	v_pk_fma_f32 v[94:95], v[252:253], v[94:95], v[98:99] op_sel_hi:[0,1,1]
	v_cvt_scalef32_pk_f32_fp4 v[98:99], v92, 1.0 op_sel:[1,0,0]
	v_cvt_scalef32_pk_f32_fp4 v[100:101], v92, 1.0 op_sel:[0,1,0]
	v_pk_fma_f32 v[98:99], v[252:253], v[98:99], v[102:103] op_sel_hi:[0,1,1]
	v_pk_fma_f32 v[100:101], v[252:253], v[100:101], v[104:105] op_sel_hi:[0,1,1]
	v_cvt_scalef32_pk_f32_fp4 v[102:103], v92, 1.0 op_sel:[1,1,0]
	v_cvt_scalef32_pk_f32_fp4 v[104:105], v93, 1.0
	v_pk_fma_f32 v[102:103], v[252:253], v[102:103], v[106:107] op_sel_hi:[0,1,1]
	v_pk_fma_f32 v[104:105], v[252:253], v[104:105], v[108:109] op_sel_hi:[0,1,1]
	v_cvt_scalef32_pk_f32_fp4 v[106:107], v93, 1.0 op_sel:[1,0,0]
	v_cvt_scalef32_pk_f32_fp4 v[108:109], v93, 1.0 op_sel:[0,1,0]
	v_pk_fma_f32 v[106:107], v[252:253], v[106:107], v[110:111] op_sel_hi:[0,1,1]
	v_pk_fma_f32 v[108:109], v[252:253], v[108:109], v[112:113] op_sel_hi:[0,1,1]
	v_cvt_scalef32_pk_f32_fp4 v[92:93], v93, 1.0 op_sel:[1,1,0]
	v_pk_fma_f32 v[16:17], v[252:253], v[92:93], v[16:17] op_sel_hi:[0,1,1]
	s_waitcnt vmcnt(17)
	v_cvt_scalef32_pk_f32_fp4 v[96:97], v86, 1.0
	s_waitcnt lgkmcnt(0)
	ds_bpermute_b32 v252, v255, v117 offset:112
	v_pk_fma_f32 v[18:19], v[96:97], v[250:251], v[18:19] op_sel_hi:[1,0,1]
	v_cvt_scalef32_pk_f32_fp4 v[96:97], v86, 1.0 op_sel:[1,0,0]
	v_pk_fma_f32 v[20:21], v[96:97], v[250:251], v[20:21] op_sel_hi:[1,0,1]
	v_cvt_scalef32_pk_f32_fp4 v[96:97], v86, 1.0 op_sel:[0,1,0]
	v_pk_fma_f32 v[22:23], v[96:97], v[250:251], v[22:23] op_sel_hi:[1,0,1]
	v_cvt_scalef32_pk_f32_fp4 v[96:97], v86, 1.0 op_sel:[1,1,0]
	v_pk_fma_f32 v[24:25], v[250:251], v[96:97], v[24:25] op_sel_hi:[0,1,1]
	v_cvt_scalef32_pk_f32_fp4 v[96:97], v87, 1.0
	v_pk_fma_f32 v[26:27], v[250:251], v[96:97], v[26:27] op_sel_hi:[0,1,1]
	v_cvt_scalef32_pk_f32_fp4 v[96:97], v87, 1.0 op_sel:[1,0,0]
	v_pk_fma_f32 v[28:29], v[250:251], v[96:97], v[28:29] op_sel_hi:[0,1,1]
	v_cvt_scalef32_pk_f32_fp4 v[96:97], v87, 1.0 op_sel:[0,1,0]
	v_cvt_scalef32_pk_f32_fp4 v[86:87], v87, 1.0 op_sel:[1,1,0]
	v_pk_fma_f32 v[86:87], v[250:251], v[86:87], v[90:91] op_sel_hi:[0,1,1]
	v_cvt_scalef32_pk_f32_fp4 v[90:91], v88, 1.0
	v_pk_fma_f32 v[30:31], v[250:251], v[96:97], v[30:31] op_sel_hi:[0,1,1]
	v_pk_fma_f32 v[90:91], v[250:251], v[90:91], v[94:95] op_sel_hi:[0,1,1]
	v_cvt_scalef32_pk_f32_fp4 v[94:95], v88, 1.0 op_sel:[1,0,0]
	v_cvt_scalef32_pk_f32_fp4 v[96:97], v88, 1.0 op_sel:[0,1,0]
	v_pk_fma_f32 v[94:95], v[250:251], v[94:95], v[98:99] op_sel_hi:[0,1,1]
	v_pk_fma_f32 v[96:97], v[250:251], v[96:97], v[100:101] op_sel_hi:[0,1,1]
	v_cvt_scalef32_pk_f32_fp4 v[98:99], v88, 1.0 op_sel:[1,1,0]
	v_cvt_scalef32_pk_f32_fp4 v[100:101], v89, 1.0
	v_pk_fma_f32 v[98:99], v[250:251], v[98:99], v[102:103] op_sel_hi:[0,1,1]
	v_pk_fma_f32 v[100:101], v[250:251], v[100:101], v[104:105] op_sel_hi:[0,1,1]
	v_cvt_scalef32_pk_f32_fp4 v[102:103], v89, 1.0 op_sel:[1,0,0]
	v_cvt_scalef32_pk_f32_fp4 v[104:105], v89, 1.0 op_sel:[0,1,0]
	v_pk_fma_f32 v[102:103], v[250:251], v[102:103], v[106:107] op_sel_hi:[0,1,1]
	v_pk_fma_f32 v[104:105], v[250:251], v[104:105], v[108:109] op_sel_hi:[0,1,1]
	v_cvt_scalef32_pk_f32_fp4 v[88:89], v89, 1.0 op_sel:[1,1,0]
	v_pk_fma_f32 v[16:17], v[250:251], v[88:89], v[16:17] op_sel_hi:[0,1,1]
	s_waitcnt vmcnt(16)
	v_cvt_scalef32_pk_f32_fp4 v[92:93], v82, 1.0
	s_waitcnt lgkmcnt(0)
	v_pk_fma_f32 v[216:217], v[92:93], v[252:253], v[18:19] op_sel_hi:[1,0,1]
	v_cvt_scalef32_pk_f32_fp4 v[18:19], v82, 1.0 op_sel:[1,0,0]
	v_pk_fma_f32 v[214:215], v[18:19], v[252:253], v[20:21] op_sel_hi:[1,0,1]
	v_cvt_scalef32_pk_f32_fp4 v[18:19], v82, 1.0 op_sel:[0,1,0]
	v_pk_fma_f32 v[212:213], v[18:19], v[252:253], v[22:23] op_sel_hi:[1,0,1]
	v_cvt_scalef32_pk_f32_fp4 v[18:19], v82, 1.0 op_sel:[1,1,0]
	v_pk_fma_f32 v[210:211], v[252:253], v[18:19], v[24:25] op_sel_hi:[0,1,1]
	v_cvt_scalef32_pk_f32_fp4 v[18:19], v83, 1.0
	v_pk_fma_f32 v[208:209], v[252:253], v[18:19], v[26:27] op_sel_hi:[0,1,1]
	v_cvt_scalef32_pk_f32_fp4 v[18:19], v83, 1.0 op_sel:[1,0,0]
	v_pk_fma_f32 v[206:207], v[252:253], v[18:19], v[28:29] op_sel_hi:[0,1,1]
	v_cvt_scalef32_pk_f32_fp4 v[18:19], v83, 1.0 op_sel:[0,1,0]
	v_pk_fma_f32 v[204:205], v[252:253], v[18:19], v[30:31] op_sel_hi:[0,1,1]
	v_cvt_scalef32_pk_f32_fp4 v[18:19], v83, 1.0 op_sel:[1,1,0]
	v_pk_fma_f32 v[202:203], v[252:253], v[18:19], v[86:87] op_sel_hi:[0,1,1]
	v_cvt_scalef32_pk_f32_fp4 v[18:19], v84, 1.0
	v_pk_fma_f32 v[200:201], v[252:253], v[18:19], v[90:91] op_sel_hi:[0,1,1]
	v_cvt_scalef32_pk_f32_fp4 v[18:19], v84, 1.0 op_sel:[1,0,0]
	v_pk_fma_f32 v[198:199], v[252:253], v[18:19], v[94:95] op_sel_hi:[0,1,1]
	v_cvt_scalef32_pk_f32_fp4 v[18:19], v84, 1.0 op_sel:[0,1,0]
	v_pk_fma_f32 v[196:197], v[252:253], v[18:19], v[96:97] op_sel_hi:[0,1,1]
	v_cvt_scalef32_pk_f32_fp4 v[18:19], v84, 1.0 op_sel:[1,1,0]
	v_pk_fma_f32 v[194:195], v[252:253], v[18:19], v[98:99] op_sel_hi:[0,1,1]
	v_cvt_scalef32_pk_f32_fp4 v[18:19], v85, 1.0
	v_pk_fma_f32 v[192:193], v[252:253], v[18:19], v[100:101] op_sel_hi:[0,1,1]
	v_cvt_scalef32_pk_f32_fp4 v[18:19], v85, 1.0 op_sel:[1,0,0]
	v_pk_fma_f32 v[190:191], v[252:253], v[18:19], v[102:103] op_sel_hi:[0,1,1]
	v_cvt_scalef32_pk_f32_fp4 v[18:19], v85, 1.0 op_sel:[0,1,0]
	v_pk_fma_f32 v[188:189], v[252:253], v[18:19], v[104:105] op_sel_hi:[0,1,1]
	v_cvt_scalef32_pk_f32_fp4 v[18:19], v85, 1.0 op_sel:[1,1,0]
	v_pk_fma_f32 v[176:177], v[252:253], v[18:19], v[16:17] op_sel_hi:[0,1,1]
	v_lshl_add_u64 v[0:1], v[120:121], 0, v[0:1]
	v_lshl_add_u64 v[4:5], v[120:121], 0, v[4:5]
	global_load_dwordx4 v[110:113], v[0:1], off offset:768
	global_load_dwordx4 v[106:109], v[4:5], off offset:768
	v_lshl_add_u64 v[0:1], v[120:121], 0, v[2:3]
	v_lshl_add_u64 v[2:3], v[120:121], 0, v[8:9]
	global_load_dwordx4 v[102:105], v[0:1], off offset:768
	global_load_dwordx4 v[98:101], v[2:3], off offset:768
	v_lshl_add_u64 v[0:1], v[120:121], 0, v[6:7]
	v_lshl_add_u64 v[2:3], v[120:121], 0, v[12:13]
	global_load_dwordx4 v[94:97], v[0:1], off offset:768
	global_load_dwordx4 v[90:93], v[2:3], off offset:768
	v_lshl_add_u64 v[0:1], v[120:121], 0, v[10:11]
	v_lshl_add_u64 v[2:3], v[120:121], 0, v[14:15]
	global_load_dwordx4 v[86:89], v[0:1], off offset:768
	global_load_dwordx4 v[82:85], v[2:3], off offset:768
	s_addk_i32 s24, 0x200
	s_cmp_lg_u32 s24, s61
	s_cbranch_scc0 .LBB0_334

.LBB0_336:
	s_andn2_saveexec_b64 s[2:3], s[2:3]
	v_mul_f32_e32 v2, v0, v0
	v_fmamk_f32 v3, v2, 0xba1345e1, v222
	v_fmaak_f32 v3, v2, v3, 0xbcdac9b8
	v_fmaak_f32 v3, v2, v3, 0x3de703be
	v_fmaak_f32 v3, v2, v3, 0xbec09330
	v_fmaak_f32 v2, v2, v3, 0x3e0375d0
	v_fma_f32 v2, |v0|, v2, |v0|
	s_or_b64 exec, exec, s[2:3]
	s_brev_b32 s2, -2
	v_bfi_b32 v0, s2, v2, v0
	v_mul_f32_e32 v1, 0.5, v1
	v_add_f32_e32 v0, 1.0, v0
	v_mul_f32_e32 v0, v1, v0
	v_mul_f32_e32 v0, v219, v0
	v_mul_f32_e32 v0, 0x3daaaaab, v0
	v_mov_b32_e32 v153, v170
	v_mov_b32_e32 v149, v172
	v_mov_b32_e32 v145, v174
	v_mov_b32_e32 v141, v178
	v_mov_b32_e32 v169, v180
	v_mov_b32_e32 v165, v182
	v_mov_b32_e32 v161, v184
	v_mov_b32_e32 v157, v186
	v_readlane_b32 s2, v0, 0
	v_readlane_b32 s3, v0, 32
	v_readlane_b32 s24, v0, 4
	v_readlane_b32 s25, v0, 36
	v_readlane_b32 s26, v0, 8
	v_readlane_b32 s27, v0, 40
	v_readlane_b32 s30, v0, 12
	v_readlane_b32 s31, v0, 44
	v_readlane_b32 s34, v0, 16
	v_readlane_b32 s35, v0, 48
	v_readlane_b32 s36, v0, 20
	v_readlane_b32 s37, v0, 52
	v_readlane_b32 s38, v0, 24
	v_readlane_b32 s39, v0, 56
	v_readlane_b32 s40, v0, 28
	v_readlane_b32 s41, v0, 60
	v_mov_b32_e32 v0, s2
	v_mov_b32_e32 v1, s3
	s_waitcnt vmcnt(7)
	v_cvt_scalef32_pk_f32_fp4 v[2:3], v110, 1.0
	v_cndmask_b32_e64 v0, v0, v1, s[6:7]
	v_pk_fma_f32 v[4:5], v[0:1], v[2:3], v[216:217] op_sel_hi:[0,1,1]
	v_mov_b32_e32 v1, s24
	v_mov_b32_e32 v2, s25
	s_waitcnt vmcnt(6)
	v_cvt_scalef32_pk_f32_fp4 v[6:7], v106, 1.0
	v_cndmask_b32_e64 v2, v1, v2, s[6:7]
	v_pk_fma_f32 v[6:7], v[2:3], v[6:7], v[4:5] op_sel_hi:[0,1,1]
	v_mov_b32_e32 v1, s26
	v_mov_b32_e32 v3, s27
	s_waitcnt vmcnt(5)
	v_cvt_scalef32_pk_f32_fp4 v[8:9], v102, 1.0
	v_cndmask_b32_e64 v4, v1, v3, s[6:7]
	v_mov_b32_e32 v1, s30
	v_mov_b32_e32 v3, s31
	v_pk_fma_f32 v[8:9], v[4:5], v[8:9], v[6:7] op_sel_hi:[0,1,1]
	s_waitcnt vmcnt(4)
	v_cvt_scalef32_pk_f32_fp4 v[10:11], v98, 1.0
	v_cndmask_b32_e64 v6, v1, v3, s[6:7]
	v_mov_b32_e32 v1, s34
	v_mov_b32_e32 v3, s35
	v_pk_fma_f32 v[8:9], v[6:7], v[10:11], v[8:9] op_sel_hi:[0,1,1]
	s_waitcnt vmcnt(3)
	v_cvt_scalef32_pk_f32_fp4 v[10:11], v94, 1.0
	v_cndmask_b32_e64 v12, v1, v3, s[6:7]
	v_mov_b32_e32 v1, s36
	v_mov_b32_e32 v3, s37
	v_pk_fma_f32 v[8:9], v[12:13], v[10:11], v[8:9] op_sel_hi:[0,1,1]
	s_waitcnt vmcnt(2)
	v_cvt_scalef32_pk_f32_fp4 v[10:11], v90, 1.0
	v_cndmask_b32_e64 v14, v1, v3, s[6:7]
	v_mov_b32_e32 v1, s38
	v_mov_b32_e32 v3, s39
	v_pk_fma_f32 v[8:9], v[14:15], v[10:11], v[8:9] op_sel_hi:[0,1,1]
	s_waitcnt vmcnt(1)
	v_cvt_scalef32_pk_f32_fp4 v[10:11], v86, 1.0
	v_cndmask_b32_e64 v16, v1, v3, s[6:7]
	v_mov_b32_e32 v1, s40
	v_mov_b32_e32 v3, s41
	v_pk_fma_f32 v[8:9], v[16:17], v[10:11], v[8:9] op_sel_hi:[0,1,1]
	s_waitcnt vmcnt(0)
	v_cvt_scalef32_pk_f32_fp4 v[10:11], v82, 1.0
	v_cndmask_b32_e64 v18, v1, v3, s[6:7]
	v_pk_fma_f32 v[56:57], v[18:19], v[10:11], v[8:9] op_sel_hi:[0,1,1]
	v_cvt_scalef32_pk_f32_fp4 v[8:9], v110, 1.0 op_sel:[1,0,0]
	v_pk_fma_f32 v[8:9], v[0:1], v[8:9], v[214:215] op_sel_hi:[0,1,1]
	v_cvt_scalef32_pk_f32_fp4 v[10:11], v106, 1.0 op_sel:[1,0,0]
	v_pk_fma_f32 v[8:9], v[2:3], v[10:11], v[8:9] op_sel_hi:[0,1,1]
	v_cvt_scalef32_pk_f32_fp4 v[10:11], v102, 1.0 op_sel:[1,0,0]
	v_pk_fma_f32 v[8:9], v[4:5], v[10:11], v[8:9] op_sel_hi:[0,1,1]
	v_cvt_scalef32_pk_f32_fp4 v[10:11], v98, 1.0 op_sel:[1,0,0]
	v_pk_fma_f32 v[8:9], v[6:7], v[10:11], v[8:9] op_sel_hi:[0,1,1]
	v_cvt_scalef32_pk_f32_fp4 v[10:11], v94, 1.0 op_sel:[1,0,0]
	v_pk_fma_f32 v[8:9], v[12:13], v[10:11], v[8:9] op_sel_hi:[0,1,1]
	v_cvt_scalef32_pk_f32_fp4 v[10:11], v90, 1.0 op_sel:[1,0,0]
	v_pk_fma_f32 v[8:9], v[14:15], v[10:11], v[8:9] op_sel_hi:[0,1,1]
	v_cvt_scalef32_pk_f32_fp4 v[10:11], v86, 1.0 op_sel:[1,0,0]
	v_pk_fma_f32 v[8:9], v[16:17], v[10:11], v[8:9] op_sel_hi:[0,1,1]
	v_cvt_scalef32_pk_f32_fp4 v[10:11], v82, 1.0 op_sel:[1,0,0]
	v_pk_fma_f32 v[60:61], v[18:19], v[10:11], v[8:9] op_sel_hi:[0,1,1]
	v_cvt_scalef32_pk_f32_fp4 v[8:9], v110, 1.0 op_sel:[0,1,0]
	v_pk_fma_f32 v[8:9], v[0:1], v[8:9], v[212:213] op_sel_hi:[0,1,1]
	v_cvt_scalef32_pk_f32_fp4 v[10:11], v106, 1.0 op_sel:[0,1,0]
	v_pk_fma_f32 v[8:9], v[2:3], v[10:11], v[8:9] op_sel_hi:[0,1,1]
	v_cvt_scalef32_pk_f32_fp4 v[10:11], v102, 1.0 op_sel:[0,1,0]
	v_pk_fma_f32 v[8:9], v[4:5], v[10:11], v[8:9] op_sel_hi:[0,1,1]
	v_cvt_scalef32_pk_f32_fp4 v[10:11], v98, 1.0 op_sel:[0,1,0]
	v_pk_fma_f32 v[8:9], v[6:7], v[10:11], v[8:9] op_sel_hi:[0,1,1]
	v_cvt_scalef32_pk_f32_fp4 v[10:11], v94, 1.0 op_sel:[0,1,0]
	v_pk_fma_f32 v[8:9], v[12:13], v[10:11], v[8:9] op_sel_hi:[0,1,1]
	v_cvt_scalef32_pk_f32_fp4 v[10:11], v90, 1.0 op_sel:[0,1,0]
	v_pk_fma_f32 v[8:9], v[14:15], v[10:11], v[8:9] op_sel_hi:[0,1,1]
	v_cvt_scalef32_pk_f32_fp4 v[10:11], v86, 1.0 op_sel:[0,1,0]
	v_pk_fma_f32 v[8:9], v[16:17], v[10:11], v[8:9] op_sel_hi:[0,1,1]
	v_cvt_scalef32_pk_f32_fp4 v[10:11], v82, 1.0 op_sel:[0,1,0]
	v_pk_fma_f32 v[58:59], v[18:19], v[10:11], v[8:9] op_sel_hi:[0,1,1]
	v_cvt_scalef32_pk_f32_fp4 v[8:9], v110, 1.0 op_sel:[1,1,0]
	v_pk_fma_f32 v[8:9], v[0:1], v[8:9], v[210:211] op_sel_hi:[0,1,1]
	v_cvt_scalef32_pk_f32_fp4 v[10:11], v106, 1.0 op_sel:[1,1,0]
	v_pk_fma_f32 v[8:9], v[2:3], v[10:11], v[8:9] op_sel_hi:[0,1,1]
	v_cvt_scalef32_pk_f32_fp4 v[10:11], v102, 1.0 op_sel:[1,1,0]
	v_pk_fma_f32 v[8:9], v[4:5], v[10:11], v[8:9] op_sel_hi:[0,1,1]
	v_cvt_scalef32_pk_f32_fp4 v[10:11], v98, 1.0 op_sel:[1,1,0]
	v_pk_fma_f32 v[8:9], v[6:7], v[10:11], v[8:9] op_sel_hi:[0,1,1]
	v_cvt_scalef32_pk_f32_fp4 v[10:11], v94, 1.0 op_sel:[1,1,0]
	v_pk_fma_f32 v[8:9], v[12:13], v[10:11], v[8:9] op_sel_hi:[0,1,1]
	v_cvt_scalef32_pk_f32_fp4 v[10:11], v90, 1.0 op_sel:[1,1,0]
	v_pk_fma_f32 v[8:9], v[14:15], v[10:11], v[8:9] op_sel_hi:[0,1,1]
	v_cvt_scalef32_pk_f32_fp4 v[10:11], v86, 1.0 op_sel:[1,1,0]
	v_pk_fma_f32 v[8:9], v[16:17], v[10:11], v[8:9] op_sel_hi:[0,1,1]
	v_cvt_scalef32_pk_f32_fp4 v[10:11], v82, 1.0 op_sel:[1,1,0]
	v_pk_fma_f32 v[64:65], v[18:19], v[10:11], v[8:9] op_sel_hi:[0,1,1]
	v_cvt_scalef32_pk_f32_fp4 v[8:9], v111, 1.0
	v_pk_fma_f32 v[8:9], v[0:1], v[8:9], v[208:209] op_sel_hi:[0,1,1]
	v_cvt_scalef32_pk_f32_fp4 v[10:11], v107, 1.0
	v_pk_fma_f32 v[8:9], v[2:3], v[10:11], v[8:9] op_sel_hi:[0,1,1]
	v_cvt_scalef32_pk_f32_fp4 v[10:11], v103, 1.0
	v_pk_fma_f32 v[8:9], v[4:5], v[10:11], v[8:9] op_sel_hi:[0,1,1]
	v_cvt_scalef32_pk_f32_fp4 v[10:11], v99, 1.0
	v_pk_fma_f32 v[8:9], v[6:7], v[10:11], v[8:9] op_sel_hi:[0,1,1]
	v_cvt_scalef32_pk_f32_fp4 v[10:11], v95, 1.0
	v_pk_fma_f32 v[8:9], v[12:13], v[10:11], v[8:9] op_sel_hi:[0,1,1]
	v_cvt_scalef32_pk_f32_fp4 v[10:11], v91, 1.0
	v_pk_fma_f32 v[8:9], v[14:15], v[10:11], v[8:9] op_sel_hi:[0,1,1]
	v_cvt_scalef32_pk_f32_fp4 v[10:11], v87, 1.0
	v_pk_fma_f32 v[8:9], v[16:17], v[10:11], v[8:9] op_sel_hi:[0,1,1]
	v_cvt_scalef32_pk_f32_fp4 v[10:11], v83, 1.0
	v_pk_fma_f32 v[62:63], v[18:19], v[10:11], v[8:9] op_sel_hi:[0,1,1]
	v_cvt_scalef32_pk_f32_fp4 v[8:9], v111, 1.0 op_sel:[1,0,0]
	v_pk_fma_f32 v[8:9], v[0:1], v[8:9], v[206:207] op_sel_hi:[0,1,1]
	v_cvt_scalef32_pk_f32_fp4 v[10:11], v107, 1.0 op_sel:[1,0,0]
	v_pk_fma_f32 v[8:9], v[2:3], v[10:11], v[8:9] op_sel_hi:[0,1,1]
	v_cvt_scalef32_pk_f32_fp4 v[10:11], v103, 1.0 op_sel:[1,0,0]
	v_pk_fma_f32 v[8:9], v[4:5], v[10:11], v[8:9] op_sel_hi:[0,1,1]
	v_cvt_scalef32_pk_f32_fp4 v[10:11], v99, 1.0 op_sel:[1,0,0]
	v_pk_fma_f32 v[8:9], v[6:7], v[10:11], v[8:9] op_sel_hi:[0,1,1]
	v_cvt_scalef32_pk_f32_fp4 v[10:11], v95, 1.0 op_sel:[1,0,0]
	v_pk_fma_f32 v[8:9], v[12:13], v[10:11], v[8:9] op_sel_hi:[0,1,1]
	v_cvt_scalef32_pk_f32_fp4 v[10:11], v91, 1.0 op_sel:[1,0,0]
	v_pk_fma_f32 v[8:9], v[14:15], v[10:11], v[8:9] op_sel_hi:[0,1,1]
	v_cvt_scalef32_pk_f32_fp4 v[10:11], v87, 1.0 op_sel:[1,0,0]
	v_pk_fma_f32 v[8:9], v[16:17], v[10:11], v[8:9] op_sel_hi:[0,1,1]
	v_cvt_scalef32_pk_f32_fp4 v[10:11], v83, 1.0 op_sel:[1,0,0]
	v_pk_fma_f32 v[68:69], v[18:19], v[10:11], v[8:9] op_sel_hi:[0,1,1]
	v_cvt_scalef32_pk_f32_fp4 v[8:9], v111, 1.0 op_sel:[0,1,0]
	v_pk_fma_f32 v[8:9], v[0:1], v[8:9], v[204:205] op_sel_hi:[0,1,1]
	v_cvt_scalef32_pk_f32_fp4 v[10:11], v107, 1.0 op_sel:[0,1,0]
	v_pk_fma_f32 v[8:9], v[2:3], v[10:11], v[8:9] op_sel_hi:[0,1,1]
	v_cvt_scalef32_pk_f32_fp4 v[10:11], v103, 1.0 op_sel:[0,1,0]
	v_pk_fma_f32 v[8:9], v[4:5], v[10:11], v[8:9] op_sel_hi:[0,1,1]
	v_cvt_scalef32_pk_f32_fp4 v[10:11], v99, 1.0 op_sel:[0,1,0]
	v_pk_fma_f32 v[8:9], v[6:7], v[10:11], v[8:9] op_sel_hi:[0,1,1]
	v_cvt_scalef32_pk_f32_fp4 v[10:11], v95, 1.0 op_sel:[0,1,0]
	v_pk_fma_f32 v[8:9], v[12:13], v[10:11], v[8:9] op_sel_hi:[0,1,1]
	v_cvt_scalef32_pk_f32_fp4 v[10:11], v91, 1.0 op_sel:[0,1,0]
	v_pk_fma_f32 v[8:9], v[14:15], v[10:11], v[8:9] op_sel_hi:[0,1,1]
	v_cvt_scalef32_pk_f32_fp4 v[10:11], v87, 1.0 op_sel:[0,1,0]
	v_pk_fma_f32 v[8:9], v[16:17], v[10:11], v[8:9] op_sel_hi:[0,1,1]
	v_cvt_scalef32_pk_f32_fp4 v[10:11], v83, 1.0 op_sel:[0,1,0]
	v_pk_fma_f32 v[66:67], v[18:19], v[10:11], v[8:9] op_sel_hi:[0,1,1]
	v_cvt_scalef32_pk_f32_fp4 v[8:9], v111, 1.0 op_sel:[1,1,0]
	v_pk_fma_f32 v[8:9], v[0:1], v[8:9], v[202:203] op_sel_hi:[0,1,1]
	v_cvt_scalef32_pk_f32_fp4 v[10:11], v107, 1.0 op_sel:[1,1,0]
	v_pk_fma_f32 v[8:9], v[2:3], v[10:11], v[8:9] op_sel_hi:[0,1,1]
	v_cvt_scalef32_pk_f32_fp4 v[10:11], v103, 1.0 op_sel:[1,1,0]
	v_pk_fma_f32 v[8:9], v[4:5], v[10:11], v[8:9] op_sel_hi:[0,1,1]
	v_cvt_scalef32_pk_f32_fp4 v[10:11], v99, 1.0 op_sel:[1,1,0]
	v_pk_fma_f32 v[8:9], v[6:7], v[10:11], v[8:9] op_sel_hi:[0,1,1]
	v_cvt_scalef32_pk_f32_fp4 v[10:11], v95, 1.0 op_sel:[1,1,0]
	v_pk_fma_f32 v[8:9], v[12:13], v[10:11], v[8:9] op_sel_hi:[0,1,1]
	v_cvt_scalef32_pk_f32_fp4 v[10:11], v91, 1.0 op_sel:[1,1,0]
	v_pk_fma_f32 v[8:9], v[14:15], v[10:11], v[8:9] op_sel_hi:[0,1,1]
	v_cvt_scalef32_pk_f32_fp4 v[10:11], v87, 1.0 op_sel:[1,1,0]
	v_pk_fma_f32 v[8:9], v[16:17], v[10:11], v[8:9] op_sel_hi:[0,1,1]
	v_cvt_scalef32_pk_f32_fp4 v[10:11], v83, 1.0 op_sel:[1,1,0]
	v_pk_fma_f32 v[72:73], v[18:19], v[10:11], v[8:9] op_sel_hi:[0,1,1]
	v_cvt_scalef32_pk_f32_fp4 v[8:9], v112, 1.0
	v_pk_fma_f32 v[8:9], v[0:1], v[8:9], v[200:201] op_sel_hi:[0,1,1]
	v_cvt_scalef32_pk_f32_fp4 v[10:11], v108, 1.0
	v_pk_fma_f32 v[8:9], v[2:3], v[10:11], v[8:9] op_sel_hi:[0,1,1]
	v_cvt_scalef32_pk_f32_fp4 v[10:11], v104, 1.0
	v_pk_fma_f32 v[8:9], v[4:5], v[10:11], v[8:9] op_sel_hi:[0,1,1]
	v_cvt_scalef32_pk_f32_fp4 v[10:11], v100, 1.0
	v_pk_fma_f32 v[8:9], v[6:7], v[10:11], v[8:9] op_sel_hi:[0,1,1]
	v_cvt_scalef32_pk_f32_fp4 v[10:11], v96, 1.0
	v_pk_fma_f32 v[8:9], v[12:13], v[10:11], v[8:9] op_sel_hi:[0,1,1]
	v_cvt_scalef32_pk_f32_fp4 v[10:11], v92, 1.0
	v_pk_fma_f32 v[8:9], v[14:15], v[10:11], v[8:9] op_sel_hi:[0,1,1]
	v_cvt_scalef32_pk_f32_fp4 v[10:11], v88, 1.0
	v_pk_fma_f32 v[8:9], v[16:17], v[10:11], v[8:9] op_sel_hi:[0,1,1]
	v_cvt_scalef32_pk_f32_fp4 v[10:11], v84, 1.0
	v_pk_fma_f32 v[70:71], v[18:19], v[10:11], v[8:9] op_sel_hi:[0,1,1]
	v_cvt_scalef32_pk_f32_fp4 v[8:9], v112, 1.0 op_sel:[1,0,0]
	v_pk_fma_f32 v[8:9], v[0:1], v[8:9], v[198:199] op_sel_hi:[0,1,1]
	v_cvt_scalef32_pk_f32_fp4 v[10:11], v108, 1.0 op_sel:[1,0,0]
	v_pk_fma_f32 v[8:9], v[2:3], v[10:11], v[8:9] op_sel_hi:[0,1,1]
	v_cvt_scalef32_pk_f32_fp4 v[10:11], v104, 1.0 op_sel:[1,0,0]
	v_pk_fma_f32 v[8:9], v[4:5], v[10:11], v[8:9] op_sel_hi:[0,1,1]
	v_cvt_scalef32_pk_f32_fp4 v[10:11], v100, 1.0 op_sel:[1,0,0]
	v_pk_fma_f32 v[8:9], v[6:7], v[10:11], v[8:9] op_sel_hi:[0,1,1]
	v_cvt_scalef32_pk_f32_fp4 v[10:11], v96, 1.0 op_sel:[1,0,0]
	v_pk_fma_f32 v[8:9], v[12:13], v[10:11], v[8:9] op_sel_hi:[0,1,1]
	v_cvt_scalef32_pk_f32_fp4 v[10:11], v92, 1.0 op_sel:[1,0,0]
	v_pk_fma_f32 v[8:9], v[14:15], v[10:11], v[8:9] op_sel_hi:[0,1,1]
	v_cvt_scalef32_pk_f32_fp4 v[10:11], v88, 1.0 op_sel:[1,0,0]
	v_pk_fma_f32 v[8:9], v[16:17], v[10:11], v[8:9] op_sel_hi:[0,1,1]
	v_cvt_scalef32_pk_f32_fp4 v[10:11], v84, 1.0 op_sel:[1,0,0]
	v_pk_fma_f32 v[76:77], v[18:19], v[10:11], v[8:9] op_sel_hi:[0,1,1]
	v_cvt_scalef32_pk_f32_fp4 v[8:9], v112, 1.0 op_sel:[0,1,0]
	v_pk_fma_f32 v[8:9], v[0:1], v[8:9], v[196:197] op_sel_hi:[0,1,1]
	v_cvt_scalef32_pk_f32_fp4 v[10:11], v108, 1.0 op_sel:[0,1,0]
	v_pk_fma_f32 v[8:9], v[2:3], v[10:11], v[8:9] op_sel_hi:[0,1,1]
	v_cvt_scalef32_pk_f32_fp4 v[10:11], v104, 1.0 op_sel:[0,1,0]
	v_pk_fma_f32 v[8:9], v[4:5], v[10:11], v[8:9] op_sel_hi:[0,1,1]
	v_cvt_scalef32_pk_f32_fp4 v[10:11], v100, 1.0 op_sel:[0,1,0]
	v_pk_fma_f32 v[8:9], v[6:7], v[10:11], v[8:9] op_sel_hi:[0,1,1]
	v_cvt_scalef32_pk_f32_fp4 v[10:11], v96, 1.0 op_sel:[0,1,0]
	v_pk_fma_f32 v[8:9], v[12:13], v[10:11], v[8:9] op_sel_hi:[0,1,1]
	v_cvt_scalef32_pk_f32_fp4 v[10:11], v92, 1.0 op_sel:[0,1,0]
	v_pk_fma_f32 v[8:9], v[14:15], v[10:11], v[8:9] op_sel_hi:[0,1,1]
	v_cvt_scalef32_pk_f32_fp4 v[10:11], v88, 1.0 op_sel:[0,1,0]
	v_pk_fma_f32 v[8:9], v[16:17], v[10:11], v[8:9] op_sel_hi:[0,1,1]
	v_cvt_scalef32_pk_f32_fp4 v[10:11], v84, 1.0 op_sel:[0,1,0]
	v_pk_fma_f32 v[74:75], v[18:19], v[10:11], v[8:9] op_sel_hi:[0,1,1]
	v_cvt_scalef32_pk_f32_fp4 v[8:9], v112, 1.0 op_sel:[1,1,0]
	v_pk_fma_f32 v[8:9], v[0:1], v[8:9], v[194:195] op_sel_hi:[0,1,1]
	v_cvt_scalef32_pk_f32_fp4 v[10:11], v108, 1.0 op_sel:[1,1,0]
	v_pk_fma_f32 v[8:9], v[2:3], v[10:11], v[8:9] op_sel_hi:[0,1,1]
	v_cvt_scalef32_pk_f32_fp4 v[10:11], v104, 1.0 op_sel:[1,1,0]
	v_pk_fma_f32 v[8:9], v[4:5], v[10:11], v[8:9] op_sel_hi:[0,1,1]
	v_cvt_scalef32_pk_f32_fp4 v[10:11], v100, 1.0 op_sel:[1,1,0]
	v_pk_fma_f32 v[8:9], v[6:7], v[10:11], v[8:9] op_sel_hi:[0,1,1]
	v_cvt_scalef32_pk_f32_fp4 v[10:11], v96, 1.0 op_sel:[1,1,0]
	v_pk_fma_f32 v[8:9], v[12:13], v[10:11], v[8:9] op_sel_hi:[0,1,1]
	v_cvt_scalef32_pk_f32_fp4 v[10:11], v92, 1.0 op_sel:[1,1,0]
	v_pk_fma_f32 v[8:9], v[14:15], v[10:11], v[8:9] op_sel_hi:[0,1,1]
	v_cvt_scalef32_pk_f32_fp4 v[10:11], v88, 1.0 op_sel:[1,1,0]
	v_pk_fma_f32 v[8:9], v[16:17], v[10:11], v[8:9] op_sel_hi:[0,1,1]
	v_cvt_scalef32_pk_f32_fp4 v[10:11], v84, 1.0 op_sel:[1,1,0]
	v_pk_fma_f32 v[82:83], v[18:19], v[10:11], v[8:9] op_sel_hi:[0,1,1]
	v_cvt_scalef32_pk_f32_fp4 v[8:9], v113, 1.0
	v_pk_fma_f32 v[8:9], v[0:1], v[8:9], v[192:193] op_sel_hi:[0,1,1]
	v_cvt_scalef32_pk_f32_fp4 v[10:11], v109, 1.0
	v_pk_fma_f32 v[8:9], v[2:3], v[10:11], v[8:9] op_sel_hi:[0,1,1]
	v_cvt_scalef32_pk_f32_fp4 v[10:11], v105, 1.0
	v_pk_fma_f32 v[8:9], v[4:5], v[10:11], v[8:9] op_sel_hi:[0,1,1]
	v_cvt_scalef32_pk_f32_fp4 v[10:11], v101, 1.0
	v_pk_fma_f32 v[8:9], v[6:7], v[10:11], v[8:9] op_sel_hi:[0,1,1]
	v_cvt_scalef32_pk_f32_fp4 v[10:11], v97, 1.0
	v_pk_fma_f32 v[8:9], v[12:13], v[10:11], v[8:9] op_sel_hi:[0,1,1]
	v_cvt_scalef32_pk_f32_fp4 v[10:11], v93, 1.0
	v_pk_fma_f32 v[8:9], v[14:15], v[10:11], v[8:9] op_sel_hi:[0,1,1]
	v_cvt_scalef32_pk_f32_fp4 v[10:11], v89, 1.0
	v_pk_fma_f32 v[8:9], v[16:17], v[10:11], v[8:9] op_sel_hi:[0,1,1]
	v_cvt_scalef32_pk_f32_fp4 v[10:11], v85, 1.0
	v_pk_fma_f32 v[78:79], v[18:19], v[10:11], v[8:9] op_sel_hi:[0,1,1]
	v_cvt_scalef32_pk_f32_fp4 v[8:9], v113, 1.0 op_sel:[1,0,0]
	v_pk_fma_f32 v[8:9], v[0:1], v[8:9], v[190:191] op_sel_hi:[0,1,1]
	v_cvt_scalef32_pk_f32_fp4 v[10:11], v109, 1.0 op_sel:[1,0,0]
	v_pk_fma_f32 v[8:9], v[2:3], v[10:11], v[8:9] op_sel_hi:[0,1,1]
	v_cvt_scalef32_pk_f32_fp4 v[10:11], v105, 1.0 op_sel:[1,0,0]
	v_pk_fma_f32 v[8:9], v[4:5], v[10:11], v[8:9] op_sel_hi:[0,1,1]
	v_cvt_scalef32_pk_f32_fp4 v[10:11], v101, 1.0 op_sel:[1,0,0]
	v_pk_fma_f32 v[8:9], v[6:7], v[10:11], v[8:9] op_sel_hi:[0,1,1]
	v_cvt_scalef32_pk_f32_fp4 v[10:11], v97, 1.0 op_sel:[1,0,0]
	v_pk_fma_f32 v[8:9], v[12:13], v[10:11], v[8:9] op_sel_hi:[0,1,1]
	v_cvt_scalef32_pk_f32_fp4 v[10:11], v93, 1.0 op_sel:[1,0,0]
	v_pk_fma_f32 v[8:9], v[14:15], v[10:11], v[8:9] op_sel_hi:[0,1,1]
	v_cvt_scalef32_pk_f32_fp4 v[10:11], v89, 1.0 op_sel:[1,0,0]
	v_pk_fma_f32 v[8:9], v[16:17], v[10:11], v[8:9] op_sel_hi:[0,1,1]
	v_cvt_scalef32_pk_f32_fp4 v[10:11], v85, 1.0 op_sel:[1,0,0]
	v_pk_fma_f32 v[90:91], v[18:19], v[10:11], v[8:9] op_sel_hi:[0,1,1]
	v_cvt_scalef32_pk_f32_fp4 v[8:9], v113, 1.0 op_sel:[0,1,0]
	v_pk_fma_f32 v[8:9], v[0:1], v[8:9], v[188:189] op_sel_hi:[0,1,1]
	v_cvt_scalef32_pk_f32_fp4 v[10:11], v109, 1.0 op_sel:[0,1,0]
	v_pk_fma_f32 v[8:9], v[2:3], v[10:11], v[8:9] op_sel_hi:[0,1,1]
	v_cvt_scalef32_pk_f32_fp4 v[10:11], v105, 1.0 op_sel:[0,1,0]
	v_pk_fma_f32 v[8:9], v[4:5], v[10:11], v[8:9] op_sel_hi:[0,1,1]
	v_cvt_scalef32_pk_f32_fp4 v[10:11], v101, 1.0 op_sel:[0,1,0]
	v_pk_fma_f32 v[8:9], v[6:7], v[10:11], v[8:9] op_sel_hi:[0,1,1]
	v_cvt_scalef32_pk_f32_fp4 v[10:11], v97, 1.0 op_sel:[0,1,0]
	v_pk_fma_f32 v[8:9], v[12:13], v[10:11], v[8:9] op_sel_hi:[0,1,1]
	v_cvt_scalef32_pk_f32_fp4 v[10:11], v93, 1.0 op_sel:[0,1,0]
	v_pk_fma_f32 v[8:9], v[14:15], v[10:11], v[8:9] op_sel_hi:[0,1,1]
	v_cvt_scalef32_pk_f32_fp4 v[10:11], v89, 1.0 op_sel:[0,1,0]
	v_pk_fma_f32 v[8:9], v[16:17], v[10:11], v[8:9] op_sel_hi:[0,1,1]
	v_cvt_scalef32_pk_f32_fp4 v[10:11], v85, 1.0 op_sel:[0,1,0]
	v_pk_fma_f32 v[86:87], v[18:19], v[10:11], v[8:9] op_sel_hi:[0,1,1]
	v_cvt_scalef32_pk_f32_fp4 v[8:9], v113, 1.0 op_sel:[1,1,0]
	v_pk_fma_f32 v[0:1], v[0:1], v[8:9], v[176:177] op_sel_hi:[0,1,1]
	v_cvt_scalef32_pk_f32_fp4 v[8:9], v109, 1.0 op_sel:[1,1,0]
	v_pk_fma_f32 v[0:1], v[2:3], v[8:9], v[0:1] op_sel_hi:[0,1,1]
	v_cvt_scalef32_pk_f32_fp4 v[2:3], v105, 1.0 op_sel:[1,1,0]
	v_pk_fma_f32 v[0:1], v[4:5], v[2:3], v[0:1] op_sel_hi:[0,1,1]
	v_cvt_scalef32_pk_f32_fp4 v[2:3], v101, 1.0 op_sel:[1,1,0]
	v_pk_fma_f32 v[0:1], v[6:7], v[2:3], v[0:1] op_sel_hi:[0,1,1]
	v_cvt_scalef32_pk_f32_fp4 v[2:3], v97, 1.0 op_sel:[1,1,0]
	v_pk_fma_f32 v[0:1], v[12:13], v[2:3], v[0:1] op_sel_hi:[0,1,1]
	v_cvt_scalef32_pk_f32_fp4 v[2:3], v93, 1.0 op_sel:[1,1,0]
	v_pk_fma_f32 v[0:1], v[14:15], v[2:3], v[0:1] op_sel_hi:[0,1,1]
	v_cvt_scalef32_pk_f32_fp4 v[2:3], v89, 1.0 op_sel:[1,1,0]
	v_pk_fma_f32 v[0:1], v[16:17], v[2:3], v[0:1] op_sel_hi:[0,1,1]
	v_cvt_scalef32_pk_f32_fp4 v[2:3], v85, 1.0 op_sel:[1,1,0]
	v_pk_fma_f32 v[84:85], v[18:19], v[2:3], v[0:1] op_sel_hi:[0,1,1]
	s_cmp_eq_u32 s54, 0
	s_cbranch_scc1 .Lg_noex
	v_lshlrev_b32_e32 v112, 3, v81
	v_add_u32_e32 v113, s62, v112
	v_or_b32_e32 v112, 0x8000, v112
	ds_write_b64 v113, v[56:57]
	ds_write_b64 v113, v[60:61] offset:512
	ds_write_b64 v113, v[58:59] offset:1024
	ds_write_b64 v113, v[64:65] offset:1536
	ds_write_b64 v113, v[62:63] offset:2048
	ds_write_b64 v113, v[68:69] offset:2560
	ds_write_b64 v113, v[66:67] offset:3072
	ds_write_b64 v113, v[72:73] offset:3584
	ds_write_b64 v113, v[70:71] offset:4096
	ds_write_b64 v113, v[76:77] offset:4608
	ds_write_b64 v113, v[74:75] offset:5120
	ds_write_b64 v113, v[82:83] offset:5632
	ds_write_b64 v113, v[78:79] offset:6144
	ds_write_b64 v113, v[90:91] offset:6656
	ds_write_b64 v113, v[86:87] offset:7168
	ds_write_b64 v113, v[84:85] offset:7680
	s_waitcnt lgkmcnt(0)
	s_barrier
	s_cmp_lg_u32 s60, s63
	s_cbranch_scc1 .LBB0_327
	ds_read_b64 v[56:57], v112
	ds_read_b64 v[60:61], v112 offset:512
	ds_read_b64 v[58:59], v112 offset:1024
	ds_read_b64 v[64:65], v112 offset:1536
	ds_read_b64 v[62:63], v112 offset:2048
	ds_read_b64 v[68:69], v112 offset:2560
	ds_read_b64 v[66:67], v112 offset:3072
	ds_read_b64 v[72:73], v112 offset:3584
	s_waitcnt lgkmcnt(0)
	ds_read_b64 v[70:71], v112 offset:4096
	ds_read_b64 v[76:77], v112 offset:4608
	ds_read_b64 v[74:75], v112 offset:5120
	ds_read_b64 v[82:83], v112 offset:5632
	ds_read_b64 v[78:79], v112 offset:6144
	ds_read_b64 v[90:91], v112 offset:6656
	ds_read_b64 v[86:87], v112 offset:7168
	ds_read_b64 v[84:85], v112 offset:7680
	s_waitcnt lgkmcnt(0)
	ds_read_b64 v[0:1], v112 offset:8192
	ds_read_b64 v[2:3], v112 offset:8704
	ds_read_b64 v[4:5], v112 offset:9216
	ds_read_b64 v[6:7], v112 offset:9728
	ds_read_b64 v[8:9], v112 offset:10240
	ds_read_b64 v[10:11], v112 offset:10752
	ds_read_b64 v[12:13], v112 offset:11264
	ds_read_b64 v[14:15], v112 offset:11776
	s_waitcnt lgkmcnt(7)
	v_pk_add_f32 v[56:57], v[56:57], v[0:1]
	s_waitcnt lgkmcnt(6)
	v_pk_add_f32 v[60:61], v[60:61], v[2:3]
	s_waitcnt lgkmcnt(5)
	v_pk_add_f32 v[58:59], v[58:59], v[4:5]
	s_waitcnt lgkmcnt(4)
	v_pk_add_f32 v[64:65], v[64:65], v[6:7]
	s_waitcnt lgkmcnt(3)
	v_pk_add_f32 v[62:63], v[62:63], v[8:9]
	s_waitcnt lgkmcnt(2)
	v_pk_add_f32 v[68:69], v[68:69], v[10:11]
	s_waitcnt lgkmcnt(1)
	v_pk_add_f32 v[66:67], v[66:67], v[12:13]
	s_waitcnt lgkmcnt(0)
	v_pk_add_f32 v[72:73], v[72:73], v[14:15]
	ds_read_b64 v[16:17], v112 offset:12288
	ds_read_b64 v[18:19], v112 offset:12800
	ds_read_b64 v[20:21], v112 offset:13312
	ds_read_b64 v[22:23], v112 offset:13824
	ds_read_b64 v[24:25], v112 offset:14336
	ds_read_b64 v[26:27], v112 offset:14848
	ds_read_b64 v[28:29], v112 offset:15360
	ds_read_b64 v[30:31], v112 offset:15872
	s_waitcnt lgkmcnt(7)
	v_pk_add_f32 v[70:71], v[70:71], v[16:17]
	s_waitcnt lgkmcnt(6)
	v_pk_add_f32 v[76:77], v[76:77], v[18:19]
	s_waitcnt lgkmcnt(5)
	v_pk_add_f32 v[74:75], v[74:75], v[20:21]
	s_waitcnt lgkmcnt(4)
	v_pk_add_f32 v[82:83], v[82:83], v[22:23]
	s_waitcnt lgkmcnt(3)
	v_pk_add_f32 v[78:79], v[78:79], v[24:25]
	s_waitcnt lgkmcnt(2)
	v_pk_add_f32 v[90:91], v[90:91], v[26:27]
	s_waitcnt lgkmcnt(1)
	v_pk_add_f32 v[86:87], v[86:87], v[28:29]
	s_waitcnt lgkmcnt(0)
	v_pk_add_f32 v[84:85], v[84:85], v[30:31]
	ds_read_b64 v[0:1], v112 offset:16384
	ds_read_b64 v[2:3], v112 offset:16896
	ds_read_b64 v[4:5], v112 offset:17408
	ds_read_b64 v[6:7], v112 offset:17920
	ds_read_b64 v[8:9], v112 offset:18432
	ds_read_b64 v[10:11], v112 offset:18944
	ds_read_b64 v[12:13], v112 offset:19456
	ds_read_b64 v[14:15], v112 offset:19968
	s_waitcnt lgkmcnt(7)
	v_pk_add_f32 v[56:57], v[56:57], v[0:1]
	s_waitcnt lgkmcnt(6)
	v_pk_add_f32 v[60:61], v[60:61], v[2:3]
	s_waitcnt lgkmcnt(5)
	v_pk_add_f32 v[58:59], v[58:59], v[4:5]
	s_waitcnt lgkmcnt(4)
	v_pk_add_f32 v[64:65], v[64:65], v[6:7]
	s_waitcnt lgkmcnt(3)
	v_pk_add_f32 v[62:63], v[62:63], v[8:9]
	s_waitcnt lgkmcnt(2)
	v_pk_add_f32 v[68:69], v[68:69], v[10:11]
	s_waitcnt lgkmcnt(1)
	v_pk_add_f32 v[66:67], v[66:67], v[12:13]
	s_waitcnt lgkmcnt(0)
	v_pk_add_f32 v[72:73], v[72:73], v[14:15]
	ds_read_b64 v[16:17], v112 offset:20480
	ds_read_b64 v[18:19], v112 offset:20992
	ds_read_b64 v[20:21], v112 offset:21504
	ds_read_b64 v[22:23], v112 offset:22016
	ds_read_b64 v[24:25], v112 offset:22528
	ds_read_b64 v[26:27], v112 offset:23040
	ds_read_b64 v[28:29], v112 offset:23552
	ds_read_b64 v[30:31], v112 offset:24064
	s_waitcnt lgkmcnt(7)
	v_pk_add_f32 v[70:71], v[70:71], v[16:17]
	s_waitcnt lgkmcnt(6)
	v_pk_add_f32 v[76:77], v[76:77], v[18:19]
	s_waitcnt lgkmcnt(5)
	v_pk_add_f32 v[74:75], v[74:75], v[20:21]
	s_waitcnt lgkmcnt(4)
	v_pk_add_f32 v[82:83], v[82:83], v[22:23]
	s_waitcnt lgkmcnt(3)
	v_pk_add_f32 v[78:79], v[78:79], v[24:25]
	s_waitcnt lgkmcnt(2)
	v_pk_add_f32 v[90:91], v[90:91], v[26:27]
	s_waitcnt lgkmcnt(1)
	v_pk_add_f32 v[86:87], v[86:87], v[28:29]
	s_waitcnt lgkmcnt(0)
	v_pk_add_f32 v[84:85], v[84:85], v[30:31]
	ds_read_b64 v[0:1], v112 offset:24576
	ds_read_b64 v[2:3], v112 offset:25088
	ds_read_b64 v[4:5], v112 offset:25600
	ds_read_b64 v[6:7], v112 offset:26112
	ds_read_b64 v[8:9], v112 offset:26624
	ds_read_b64 v[10:11], v112 offset:27136
	ds_read_b64 v[12:13], v112 offset:27648
	ds_read_b64 v[14:15], v112 offset:28160
	s_waitcnt lgkmcnt(7)
	v_pk_add_f32 v[56:57], v[56:57], v[0:1]
	s_waitcnt lgkmcnt(6)
	v_pk_add_f32 v[60:61], v[60:61], v[2:3]
	s_waitcnt lgkmcnt(5)
	v_pk_add_f32 v[58:59], v[58:59], v[4:5]
	s_waitcnt lgkmcnt(4)
	v_pk_add_f32 v[64:65], v[64:65], v[6:7]
	s_waitcnt lgkmcnt(3)
	v_pk_add_f32 v[62:63], v[62:63], v[8:9]
	s_waitcnt lgkmcnt(2)
	v_pk_add_f32 v[68:69], v[68:69], v[10:11]
	s_waitcnt lgkmcnt(1)
	v_pk_add_f32 v[66:67], v[66:67], v[12:13]
	s_waitcnt lgkmcnt(0)
	v_pk_add_f32 v[72:73], v[72:73], v[14:15]
	ds_read_b64 v[16:17], v112 offset:28672
	ds_read_b64 v[18:19], v112 offset:29184
	ds_read_b64 v[20:21], v112 offset:29696
	ds_read_b64 v[22:23], v112 offset:30208
	ds_read_b64 v[24:25], v112 offset:30720
	ds_read_b64 v[26:27], v112 offset:31232
	ds_read_b64 v[28:29], v112 offset:31744
	ds_read_b64 v[30:31], v112 offset:32256
	s_waitcnt lgkmcnt(7)
	v_pk_add_f32 v[70:71], v[70:71], v[16:17]
	s_waitcnt lgkmcnt(6)
	v_pk_add_f32 v[76:77], v[76:77], v[18:19]
	s_waitcnt lgkmcnt(5)
	v_pk_add_f32 v[74:75], v[74:75], v[20:21]
	s_waitcnt lgkmcnt(4)
	v_pk_add_f32 v[82:83], v[82:83], v[22:23]
	s_waitcnt lgkmcnt(3)
	v_pk_add_f32 v[78:79], v[78:79], v[24:25]
	s_waitcnt lgkmcnt(2)
	v_pk_add_f32 v[90:91], v[90:91], v[26:27]
	s_waitcnt lgkmcnt(1)
	v_pk_add_f32 v[86:87], v[86:87], v[28:29]
	s_waitcnt lgkmcnt(0)
	v_pk_add_f32 v[84:85], v[84:85], v[30:31]
.Lg_noex:
	global_load_dwordx4 v[0:3], v[124:125], off offset:48
	global_load_dwordx4 v[8:11], v[124:125], off offset:32
	global_load_dwordx4 v[20:23], v[124:125], off offset:16
	global_load_dwordx4 v[32:35], v[124:125], off
	global_load_dwordx4 v[12:15], v[126:127], off offset:48
	global_load_dwordx4 v[28:31], v[126:127], off offset:32
	global_load_dwordx4 v[40:43], v[126:127], off offset:16
	global_load_dwordx4 v[52:55], v[126:127], off
	global_load_dwordx4 v[4:7], v[124:125], off offset:112
	global_load_dwordx4 v[24:27], v[124:125], off offset:96
	global_load_dwordx4 v[36:39], v[124:125], off offset:80
	global_load_dwordx4 v[48:51], v[124:125], off offset:64
	global_load_dwordx4 v[16:19], v[126:127], off offset:112
	global_load_dwordx4 v[44:47], v[126:127], off offset:96
	ds_bpermute_b32 v88, v243, v56
	ds_bpermute_b32 v89, v243, v60
	ds_bpermute_b32 v92, v243, v57
	ds_bpermute_b32 v93, v243, v61
	v_mov_b32_e32 v178, v56
	v_mov_b32_e32 v179, v60
	s_waitcnt lgkmcnt(2)
	v_pk_add_f32 v[88:89], v[178:179], v[88:89]
	s_mov_b32 s2, 0x3fd744fd
	v_mov_b32_e32 v60, v57
	ds_bpermute_b32 v94, v243, v58
	ds_bpermute_b32 v95, v243, v64
	v_pk_fma_f32 v[88:89], v[152:153], s[2:3], v[88:89] op_sel_hi:[1,0,1]
	s_waitcnt lgkmcnt(2)
	v_pk_add_f32 v[56:57], v[60:61], v[92:93]
	ds_bpermute_b32 v96, v243, v59
	ds_bpermute_b32 v97, v243, v65
	v_add_f32_e32 v117, 0, v88
	v_pk_fma_f32 v[92:93], v[150:151], s[2:3], v[56:57] op_sel_hi:[1,0,1]
	v_mov_b32_e32 v57, v64
	v_add_f32_e32 v56, v117, v92
	v_add_f32_e32 v56, v56, v89
	v_add_f32_e32 v60, v56, v93
	v_mov_b32_e32 v56, v58
	s_waitcnt lgkmcnt(2)
	v_pk_add_f32 v[56:57], v[56:57], v[94:95]
	v_mov_b32_e32 v64, v59
	ds_bpermute_b32 v98, v243, v62
	ds_bpermute_b32 v99, v243, v68
	v_pk_fma_f32 v[94:95], v[148:149], s[2:3], v[56:57] op_sel_hi:[1,0,1]
	s_waitcnt lgkmcnt(2)
	v_pk_add_f32 v[56:57], v[64:65], v[96:97]
	ds_bpermute_b32 v100, v243, v63
	ds_bpermute_b32 v101, v243, v69
	v_pk_fma_f32 v[64:65], v[146:147], s[2:3], v[56:57] op_sel_hi:[1,0,1]
	v_add_f32_e32 v56, v60, v94
	v_add_f32_e32 v56, v56, v64
	v_add_f32_e32 v56, v56, v95
	v_add_f32_e32 v58, v56, v65
	v_mov_b32_e32 v56, v62
	v_mov_b32_e32 v57, v68
	s_waitcnt lgkmcnt(2)
	v_pk_add_f32 v[56:57], v[56:57], v[98:99]
	v_mov_b32_e32 v68, v63
	ds_bpermute_b32 v102, v243, v66
	ds_bpermute_b32 v103, v243, v72
	v_pk_fma_f32 v[96:97], v[144:145], s[2:3], v[56:57] op_sel_hi:[1,0,1]
	s_waitcnt lgkmcnt(2)
	v_pk_add_f32 v[56:57], v[68:69], v[100:101]
	ds_bpermute_b32 v104, v243, v67
	ds_bpermute_b32 v105, v243, v73
	v_pk_fma_f32 v[68:69], v[142:143], s[2:3], v[56:57] op_sel_hi:[1,0,1]
	v_add_f32_e32 v56, v58, v96
	v_add_f32_e32 v56, v56, v68
	v_add_f32_e32 v56, v56, v97
	v_add_f32_e32 v58, v56, v69
	v_mov_b32_e32 v56, v66
	v_mov_b32_e32 v57, v72
	s_waitcnt lgkmcnt(2)
	v_pk_add_f32 v[56:57], v[56:57], v[102:103]
	v_mov_b32_e32 v72, v67
	ds_bpermute_b32 v106, v243, v70
	ds_bpermute_b32 v107, v243, v76
	v_pk_fma_f32 v[98:99], v[140:141], s[2:3], v[56:57] op_sel_hi:[1,0,1]
	s_waitcnt lgkmcnt(2)
	v_pk_add_f32 v[56:57], v[72:73], v[104:105]
	ds_bpermute_b32 v108, v243, v71
	ds_bpermute_b32 v109, v243, v77
	v_pk_fma_f32 v[66:67], v[138:139], s[2:3], v[56:57] op_sel_hi:[1,0,1]
	v_add_f32_e32 v56, v58, v98
	v_add_f32_e32 v56, v56, v66
	v_add_f32_e32 v56, v56, v99
	v_add_f32_e32 v58, v56, v67
	v_mov_b32_e32 v56, v70
	v_mov_b32_e32 v57, v76
	s_waitcnt lgkmcnt(2)
	v_pk_add_f32 v[56:57], v[56:57], v[106:107]
	v_mov_b32_e32 v76, v71
	ds_bpermute_b32 v110, v243, v74
	ds_bpermute_b32 v111, v243, v82
	v_pk_fma_f32 v[72:73], v[168:169], s[2:3], v[56:57] op_sel_hi:[1,0,1]
	s_waitcnt lgkmcnt(2)
	v_pk_add_f32 v[56:57], v[76:77], v[108:109]
	ds_bpermute_b32 v112, v243, v75
	ds_bpermute_b32 v113, v243, v83
	v_pk_fma_f32 v[70:71], v[166:167], s[2:3], v[56:57] op_sel_hi:[1,0,1]
	v_add_f32_e32 v56, v58, v72
	v_add_f32_e32 v56, v56, v70
	v_add_f32_e32 v56, v56, v73
	v_add_f32_e32 v58, v56, v71
	v_mov_b32_e32 v56, v74
	v_mov_b32_e32 v57, v82
	s_waitcnt lgkmcnt(2)
	v_pk_add_f32 v[56:57], v[56:57], v[110:111]
	v_mov_b32_e32 v82, v75
	ds_bpermute_b32 v170, v243, v78
	ds_bpermute_b32 v171, v243, v90
	v_pk_fma_f32 v[76:77], v[164:165], s[2:3], v[56:57] op_sel_hi:[1,0,1]
	s_waitcnt lgkmcnt(2)
	v_pk_add_f32 v[56:57], v[82:83], v[112:113]
	ds_bpermute_b32 v172, v243, v79
	ds_bpermute_b32 v173, v243, v91
	v_pk_fma_f32 v[74:75], v[162:163], s[2:3], v[56:57] op_sel_hi:[1,0,1]
	v_add_f32_e32 v56, v58, v76
	v_add_f32_e32 v56, v56, v74
	v_add_f32_e32 v56, v56, v77
	v_add_f32_e32 v58, v56, v75
	v_mov_b32_e32 v56, v78
	v_mov_b32_e32 v57, v90
	s_waitcnt lgkmcnt(2)
	v_pk_add_f32 v[56:57], v[56:57], v[170:171]
	v_mov_b32_e32 v90, v79
	ds_bpermute_b32 v174, v243, v86
	ds_bpermute_b32 v175, v243, v84
	v_pk_fma_f32 v[82:83], v[160:161], s[2:3], v[56:57] op_sel_hi:[1,0,1]
	s_waitcnt lgkmcnt(2)
	v_pk_add_f32 v[56:57], v[90:91], v[172:173]
	ds_bpermute_b32 v176, v243, v87
	ds_bpermute_b32 v177, v243, v85
	v_pk_fma_f32 v[78:79], v[158:159], s[2:3], v[56:57] op_sel_hi:[1,0,1]
	v_add_f32_e32 v56, v58, v82
	v_add_f32_e32 v56, v56, v78
	v_add_f32_e32 v56, v56, v83
	v_add_f32_e32 v58, v56, v79
	v_mov_b32_e32 v56, v86
	v_mov_b32_e32 v57, v84
	s_waitcnt lgkmcnt(2)
	v_pk_add_f32 v[56:57], v[56:57], v[174:175]
	v_mov_b32_e32 v84, v87
	v_pk_fma_f32 v[90:91], v[156:157], s[2:3], v[56:57] op_sel_hi:[1,0,1]
	s_waitcnt lgkmcnt(0)
	v_pk_add_f32 v[56:57], v[84:85], v[176:177]
	s_waitcnt vmcnt(10)
	v_mov_b32_e32 v86, v32
	v_pk_fma_f32 v[84:85], v[154:155], s[2:3], v[56:57] op_sel_hi:[1,0,1]
	v_add_f32_e32 v56, v58, v90
	v_add_f32_e32 v56, v56, v84
	v_add_f32_e32 v56, v56, v91
	v_add_f32_e32 v101, v56, v85
	ds_bpermute_b32 v102, v242, v101
	s_waitcnt vmcnt(6)
	v_mov_b32_e32 v100, v52
	v_mov_b32_e32 v52, v20
	global_load_dwordx4 v[56:59], v[126:127], off offset:80
	global_load_dwordx4 v[60:63], v[126:127], off offset:64
	v_mov_b32_e32 v87, v34
	s_waitcnt lgkmcnt(0)
	v_add_f32_e32 v32, v101, v102
	ds_bpermute_b32 v102, v241, v32
	v_mov_b32_e32 v34, v33
	v_mov_b32_e32 v103, v42
	v_mov_b32_e32 v42, v41
	v_mov_b32_e32 v41, v30
	s_waitcnt lgkmcnt(0)
	v_add_f32_e32 v20, v32, v102
	ds_bpermute_b32 v32, v240, v20
	v_mov_b32_e32 v102, v40
	v_mov_b32_e32 v40, v28
	v_mov_b32_e32 v30, v29
	s_mov_b32 s2, 0x800000
	s_waitcnt lgkmcnt(0)
	v_add_f32_e32 v32, v20, v32
	ds_bpermute_b32 v33, v244, v32
	v_mov_b32_e32 v20, v8
	v_mov_b32_e32 v8, v0
	v_mov_b32_e32 v101, v54
	v_mov_b32_e32 v54, v53
	s_waitcnt lgkmcnt(0)
	v_add_f32_e32 v28, v32, v33
	ds_bpermute_b32 v32, v245, v28
	v_mov_b32_e32 v53, v22
	v_mov_b32_e32 v22, v21
	v_mov_b32_e32 v21, v10
	v_mov_b32_e32 v10, v9
	s_waitcnt lgkmcnt(0)
	v_add_f32_e32 v0, v28, v32
	v_mul_f32_e32 v0, 0x3a800000, v0
	v_pk_add_f32 v[28:29], v[88:89], v[0:1] op_sel_hi:[1,0] neg_lo:[0,1] neg_hi:[0,1]
	v_pk_add_f32 v[88:89], v[92:93], v[0:1] op_sel_hi:[1,0] neg_lo:[0,1] neg_hi:[0,1]
	v_pk_mul_f32 v[32:33], v[28:29], v[28:29]
	v_pk_mul_f32 v[92:93], v[88:89], v[88:89]
	v_pk_add_f32 v[94:95], v[94:95], v[0:1] op_sel_hi:[1,0] neg_lo:[0,1] neg_hi:[0,1]
	v_pk_add_f32 v[64:65], v[64:65], v[0:1] op_sel_hi:[1,0] neg_lo:[0,1] neg_hi:[0,1]
	v_pk_add_f32 v[96:97], v[96:97], v[0:1] op_sel_hi:[1,0] neg_lo:[0,1] neg_hi:[0,1]
	v_pk_add_f32 v[68:69], v[68:69], v[0:1] op_sel_hi:[1,0] neg_lo:[0,1] neg_hi:[0,1]
	v_pk_add_f32 v[98:99], v[98:99], v[0:1] op_sel_hi:[1,0] neg_lo:[0,1] neg_hi:[0,1]
	v_pk_add_f32 v[66:67], v[66:67], v[0:1] op_sel_hi:[1,0] neg_lo:[0,1] neg_hi:[0,1]
	v_pk_add_f32 v[72:73], v[72:73], v[0:1] op_sel_hi:[1,0] neg_lo:[0,1] neg_hi:[0,1]
	v_pk_add_f32 v[70:71], v[70:71], v[0:1] op_sel_hi:[1,0] neg_lo:[0,1] neg_hi:[0,1]
	v_pk_add_f32 v[76:77], v[76:77], v[0:1] op_sel_hi:[1,0] neg_lo:[0,1] neg_hi:[0,1]
	v_pk_add_f32 v[74:75], v[74:75], v[0:1] op_sel_hi:[1,0] neg_lo:[0,1] neg_hi:[0,1]
	v_pk_add_f32 v[82:83], v[82:83], v[0:1] op_sel_hi:[1,0] neg_lo:[0,1] neg_hi:[0,1]
	v_pk_add_f32 v[78:79], v[78:79], v[0:1] op_sel_hi:[1,0] neg_lo:[0,1] neg_hi:[0,1]
	v_pk_add_f32 v[90:91], v[90:91], v[0:1] op_sel_hi:[1,0] neg_lo:[0,1] neg_hi:[0,1]
	v_pk_add_f32 v[84:85], v[84:85], v[0:1] op_sel_hi:[1,0] neg_lo:[0,1] neg_hi:[0,1]
	v_add_f32_e32 v0, v32, v92
	v_add_f32_e32 v0, v33, v0
	v_pk_mul_f32 v[104:105], v[94:95], v[94:95]
	v_add_f32_e32 v0, v93, v0
	v_pk_mul_f32 v[106:107], v[64:65], v[64:65]
	v_add_f32_e32 v0, v104, v0
	v_add_f32_e32 v0, v106, v0
	v_add_f32_e32 v0, v105, v0
	v_pk_mul_f32 v[108:109], v[96:97], v[96:97]
	v_add_f32_e32 v0, v107, v0
	v_pk_mul_f32 v[110:111], v[68:69], v[68:69]
	v_add_f32_e32 v0, v108, v0
	v_add_f32_e32 v0, v110, v0
	v_add_f32_e32 v0, v109, v0
	v_pk_mul_f32 v[112:113], v[98:99], v[98:99]
	v_add_f32_e32 v0, v111, v0
	v_pk_mul_f32 v[138:139], v[66:67], v[66:67]
	v_add_f32_e32 v0, v112, v0
	v_add_f32_e32 v0, v138, v0
	v_add_f32_e32 v0, v113, v0
	v_pk_mul_f32 v[140:141], v[72:73], v[72:73]
	v_add_f32_e32 v0, v139, v0
	v_pk_mul_f32 v[142:143], v[70:71], v[70:71]
	v_add_f32_e32 v0, v140, v0
	v_add_f32_e32 v0, v142, v0
	v_add_f32_e32 v0, v141, v0
	v_pk_mul_f32 v[144:145], v[76:77], v[76:77]
	v_add_f32_e32 v0, v143, v0
	v_pk_mul_f32 v[146:147], v[74:75], v[74:75]
	v_add_f32_e32 v0, v144, v0
	v_add_f32_e32 v0, v146, v0
	v_add_f32_e32 v0, v145, v0
	v_add_f32_e32 v0, v147, v0
	v_mov_b32_e32 v148, v79
	v_mov_b32_e32 v149, v83
	v_fmac_f32_e32 v0, v82, v82
	v_pk_mul_f32 v[148:149], v[148:149], v[148:149]
	v_fmac_f32_e32 v0, v78, v78
	v_mov_b32_e32 v150, v84
	v_mov_b32_e32 v151, v90
	v_add_f32_e32 v0, v149, v0
	v_pk_mul_f32 v[150:151], v[150:151], v[150:151]
	v_add_f32_e32 v0, v148, v0
	v_mov_b32_e32 v152, v85
	v_mov_b32_e32 v153, v91
	v_add_f32_e32 v0, v151, v0
	v_pk_mul_f32 v[152:153], v[152:153], v[152:153]
	v_add_f32_e32 v0, v150, v0
	v_add_f32_e32 v0, v153, v0
	v_add_f32_e32 v0, v152, v0
	ds_bpermute_b32 v32, v242, v0
	s_waitcnt vmcnt(1)
	v_mov_b32_e32 v104, v56
	v_mov_b32_e32 v56, v24
	v_mov_b32_e32 v105, v58
	v_mov_b32_e32 v58, v57
	s_waitcnt lgkmcnt(0)
	v_add_f32_e32 v32, v0, v32
	ds_bpermute_b32 v33, v241, v32
	v_mov_b32_e32 v57, v26
	v_mov_b32_e32 v106, v44
	v_mov_b32_e32 v107, v46
	v_mov_b32_e32 v46, v45
	s_waitcnt lgkmcnt(0)
	v_add_f32_e32 v32, v32, v33
	ds_bpermute_b32 v33, v240, v32
	v_mov_b32_e32 v9, v2
	v_mov_b32_e32 v2, v1
	v_mov_b32_e32 v0, v48
	v_mov_b32_e32 v1, v50
	s_waitcnt lgkmcnt(0)
	v_add_f32_e32 v32, v32, v33
	ds_bpermute_b32 v33, v244, v32
	v_mov_b32_e32 v50, v49
	v_mov_b32_e32 v92, v12
	v_mov_b32_e32 v93, v14
	v_mov_b32_e32 v14, v13
	s_waitcnt lgkmcnt(0)
	v_add_f32_e32 v32, v32, v33
	ds_bpermute_b32 v33, v245, v32
	s_waitcnt vmcnt(0)
	v_mov_b32_e32 v12, v60
	v_mov_b32_e32 v13, v62
	v_mov_b32_e32 v62, v61
	v_mov_b32_e32 v60, v36
	s_waitcnt lgkmcnt(0)
	v_add_f32_e32 v24, v32, v33
	v_fmamk_f32 v24, v24, 0x3a800000, v221
	v_mul_f32_e32 v26, 0x4b800000, v24
	v_cmp_gt_f32_e32 vcc, s2, v24
	v_mov_b32_e32 v61, v38
	v_mov_b32_e32 v38, v37
	v_cndmask_b32_e32 v24, v24, v26, vcc
	v_rsq_f32_e32 v24, v24
	v_mov_b32_e32 v26, v25
	v_mul_f32_e32 v25, 0x45800000, v24
	v_cndmask_b32_e32 v108, v24, v25, vcc
	v_pk_mul_f32 v[24:25], v[28:29], v[108:109] op_sel_hi:[1,0]
	s_nop 0
	v_pk_fma_f32 v[44:45], v[86:87], v[24:25], v[100:101]
	v_pk_mul_f32 v[24:25], v[88:89], v[108:109] op_sel_hi:[1,0]
	s_nop 0
	v_pk_fma_f32 v[32:33], v[34:35], v[24:25], v[54:55]
	v_pk_mul_f32 v[24:25], v[94:95], v[108:109] op_sel_hi:[1,0]
	s_nop 0
	v_pk_fma_f32 v[48:49], v[52:53], v[24:25], v[102:103]
	v_pk_mul_f32 v[24:25], v[64:65], v[108:109] op_sel_hi:[1,0]
	s_nop 0
	v_pk_fma_f32 v[28:29], v[22:23], v[24:25], v[42:43]
	v_pk_mul_f32 v[22:23], v[96:97], v[108:109] op_sel_hi:[1,0]
	s_nop 0
	v_pk_fma_f32 v[40:41], v[20:21], v[22:23], v[40:41]
	v_pk_mul_f32 v[20:21], v[68:69], v[108:109] op_sel_hi:[1,0]
	v_pk_mul_f32 v[22:23], v[90:91], v[108:109] op_sel_hi:[1,0]
	v_pk_fma_f32 v[24:25], v[10:11], v[20:21], v[30:31]
	v_pk_mul_f32 v[10:11], v[98:99], v[108:109] op_sel_hi:[1,0]
	v_mov_b32_e32 v30, v16
	v_pk_fma_f32 v[10:11], v[8:9], v[10:11], v[92:93]
	v_pk_mul_f32 v[8:9], v[66:67], v[108:109] op_sel_hi:[1,0]
	v_mov_b32_e32 v31, v18
	v_pk_fma_f32 v[20:21], v[2:3], v[8:9], v[14:15]
	v_pk_mul_f32 v[2:3], v[72:73], v[108:109] op_sel_hi:[1,0]
	v_mov_b32_e32 v18, v17
	v_pk_fma_f32 v[0:1], v[0:1], v[2:3], v[12:13]
	v_pk_mul_f32 v[2:3], v[70:71], v[108:109] op_sel_hi:[1,0]
	s_nop 0
	v_pk_fma_f32 v[12:13], v[50:51], v[2:3], v[62:63]
	v_pk_mul_f32 v[2:3], v[76:77], v[108:109] op_sel_hi:[1,0]
	s_nop 0
	v_pk_fma_f32 v[36:37], v[60:61], v[2:3], v[104:105]
	v_pk_mul_f32 v[2:3], v[74:75], v[108:109] op_sel_hi:[1,0]
	s_nop 0
	v_pk_fma_f32 v[8:9], v[38:39], v[2:3], v[58:59]
	v_pk_mul_f32 v[2:3], v[82:83], v[108:109] op_sel_hi:[1,0]
	s_nop 0
	v_pk_fma_f32 v[14:15], v[56:57], v[2:3], v[106:107]
	v_pk_mul_f32 v[2:3], v[78:79], v[108:109] op_sel_hi:[1,0]
	s_nop 0
	v_pk_fma_f32 v[2:3], v[26:27], v[2:3], v[46:47]
	v_mov_b32_e32 v26, v4
	v_mov_b32_e32 v27, v6
	v_pk_fma_f32 v[34:35], v[26:27], v[22:23], v[30:31]
	v_pk_mul_f32 v[22:23], v[84:85], v[108:109] op_sel_hi:[1,0]
	v_mov_b32_e32 v6, v5
	v_pk_fma_f32 v[4:5], v[6:7], v[22:23], v[18:19]
	s_and_saveexec_b64 s[2:3], s[8:9]
	s_xor_b64 s[2:3], exec, s[2:3]
	s_cbranch_execz .LBB0_341
	s_andn2_b64 vcc, exec, s[4:5]
	s_cbranch_vccnz .LBB0_341
	v_lshl_add_u64 v[16:17], v[136:137], 2, v[128:129]
	v_mov_b32_e32 v18, v10
	v_mov_b32_e32 v19, v20
	v_mov_b32_e32 v20, v11
	v_mov_b32_e32 v10, v0
	v_mov_b32_e32 v11, v12
	v_mov_b32_e32 v12, v1
	v_mov_b32_e32 v0, v14
	v_mov_b32_e32 v1, v2
	v_mov_b32_e32 v2, v15
	v_mov_b32_e32 v30, v44
	v_mov_b32_e32 v31, v32
	v_mov_b32_e32 v32, v45
	v_mov_b32_e32 v26, v48
	v_mov_b32_e32 v27, v28
	v_mov_b32_e32 v28, v49
	v_mov_b32_e32 v22, v40
	v_mov_b32_e32 v23, v24
	v_mov_b32_e32 v24, v41
	v_mov_b32_e32 v6, v36
	v_mov_b32_e32 v7, v8
	v_mov_b32_e32 v8, v37
	global_store_dwordx4 v[16:17], v[0:3], off offset:96
	global_store_dwordx4 v[16:17], v[30:33], off
	global_store_dwordx4 v[16:17], v[26:29], off offset:16
	v_mov_b32_e32 v2, v34
	v_mov_b32_e32 v3, v4
	v_mov_b32_e32 v4, v35
	global_store_dwordx4 v[16:17], v[22:25], off offset:32
	global_store_dwordx4 v[16:17], v[18:21], off offset:48
	global_store_dwordx4 v[16:17], v[10:13], off offset:64
	global_store_dwordx4 v[16:17], v[6:9], off offset:80
	global_store_dwordx4 v[16:17], v[2:5], off offset:112

.Lg_tail_check:
	s_cmp_eq_u32 s55, 0
	s_cbranch_scc1 .LBB0_344
	s_cmp_lg_u32 s54, 0
	s_cbranch_scc1 .LBB0_344
	s_mov_b32 s54, 1
	s_mov_b64 exec, s[0:1]
	s_lshl_b32 s58, s60, 8
	v_readlane_b32 s63, v249, 0
	s_lshr_b32 s63, s63, 7
	s_and_b32 s63, s63, 2
	s_movk_i32 s61, 0x200
	v_readlane_b32 s2, v249, 0
	s_add_u32 s2, s2, 0x4000
	v_mov_b32_e32 v116, s2
	s_mov_b64 s[22:23], 0
	s_branch .LBB0_328
